# v39 + one LDS base VGPR for all B-fragment reads (3 fewer VALU address ops per iteration in the load segments, ds_read offsets instead); bit-identical
# speedup vs baseline: 1.0117x; 1.0022x over previous
; #define PG8_WAIT_V(n) asm volatile("s_waitcnt vmcnt(" #n ")" ::: "memory")
; #define PG8_WAIT_L(n) asm volatile("s_waitcnt lgkmcnt(" #n ")" ::: "memory")
; #define PG8_BAR __builtin_amdgcn_s_barrier()
; #define PG8_SCHED __builtin_amdgcn_sched_barrier(0)
; template <class Epi, class AddrA, class AddrB>
; __device__ __forceinline__ void gemm_phase(const Sched S, const int lda, const int ldb, const int K, const AddrA addrA,
;                                            const AddrB addrB, const Epi E) {
;     ...
;     const bool has_next = S.next(ui + 1, nxt);
;     const char* nA = has_next ? addrA(nxt) : cA;
;     const char* nB = has_next ? addrB(nxt) : cB;
;     for (int t = 0; t < nt; t += 2) {
;       const bool last = (t == nt - 2);
;       const char* a1 = cA + (size_t)(t + 1) * kstep;
;       const char* a2 = last ? nA : cA + (size_t)(t + 2) * kstep;
;       const char* b2 = last ? nB : cB + (size_t)(t + 2) * kstep;
;       const char* a3 = a2 + kstep;
;       const char* b3 = b2 + kstep;
;       PG8_LDB(B0, 0, 0); PG8_SCHED; PG8_LDA(At, 0, 0); PG8_STAGE(PG8_SA(1, 1), a1 + hstepA, voffA);
;       PG8_WAIT_L(8); PG8_BAR; PG8_WAIT_L(0); PG8_MMA(0, 0, At, B0); PG8_BAR; PG8_SCHED;
;       PG8_LDB(B1, 0, 1); PG8_STAGE(PG8_SB(0, 0), b2, voffB);
;       PG8_BAR; PG8_WAIT_L(0); PG8_MMA(0, 1, At, B1); PG8_BAR;
;       PG8_LDA(At, 0, 1); PG8_STAGE(PG8_SA(0, 0), a2, voffA);
;       PG8_BAR; PG8_WAIT_L(0); PG8_MMA(1, 0, At, B0); PG8_BAR; PG8_SCHED;
;       PG8_STAGE(PG8_SB(0, 1), b2 + hstepB, voffB);
;       PG8_WAIT_V(6); PG8_BAR; PG8_MMA(1, 1, At, B1); PG8_BAR;
.LBB0_108:
	s_ashr_i32 s1, s0, 31
	s_lshl_b64 s[6:7], s[0:1], 20
	s_add_u32 s6, s20, s6
	s_addc_u32 s7, s21, s7
	s_and_b64 s[8:9], s[16:17], exec
	s_cselect_b32 s1, s7, s15
	s_cselect_b32 s11, s6, s14
	s_ashr_i32 s3, s2, 31
	s_lshl_b64 s[8:9], s[2:3], 20
	s_add_u32 s8, s22, s8
	s_addc_u32 s9, s23, s9
	s_and_b64 s[16:17], s[16:17], exec
	s_cselect_b32 s3, s9, s13
	s_cselect_b32 s36, s8, s12
	s_add_u32 s37, s12, 0x100
	s_addc_u32 s38, s13, 0
	s_add_u32 s12, s14, 0x80080
	s_addc_u32 s13, s15, 0
	s_mov_b32 s39, -2
	s_add_i32 s40, 0, 0x10000
	v_add_u32_e32 v246, s40, v145
	ds_read_b128 v[148:151], v246
	ds_read_b128 v[152:155], v246 offset:1024
	ds_read_b128 v[156:159], v246 offset:2048
	ds_read_b128 v[160:163], v246 offset:3072
	s_add_i32 m0, s24, 0xc000
	ds_read_b128 v[168:171], v146
	ds_read_b128 v[172:175], v146 offset:1024
	ds_read_b128 v[176:179], v146 offset:2048
	ds_read_b128 v[180:183], v146 offset:3072
	ds_read_b128 v[184:187], v146 offset:4096
	ds_read_b128 v[188:191], v146 offset:5120
	ds_read_b128 v[192:195], v146 offset:6144
	ds_read_b128 v[212:215], v146 offset:7168
	global_load_lds_dwordx4 v140, s[12:13]
	s_add_i32 m0, s24, 0xe000
	s_nop 0
	global_load_lds_dwordx4 v138, s[12:13]
	s_waitcnt lgkmcnt(6)
	s_setprio 1
	s_barrier
	v_mfma_f32_16x16x32_bf16 v[128:131], v[148:151], v[168:171], 0
	v_mfma_f32_16x16x32_bf16 v[128:131], v[152:155], v[172:175], v[128:131]
	s_waitcnt lgkmcnt(0)
	v_mfma_f32_16x16x32_bf16 v[120:123], v[148:151], v[176:179], 0
	v_mfma_f32_16x16x32_bf16 v[120:123], v[152:155], v[180:183], v[120:123]
	v_mfma_f32_16x16x32_bf16 v[104:107], v[148:151], v[184:187], 0
	v_mfma_f32_16x16x32_bf16 v[104:107], v[152:155], v[188:191], v[104:107]
	v_mfma_f32_16x16x32_bf16 v[88:91], v[148:151], v[192:195], 0
	v_mfma_f32_16x16x32_bf16 v[88:91], v[152:155], v[212:215], v[88:91]
	v_mfma_f32_16x16x32_bf16 v[124:127], v[156:159], v[168:171], 0
	v_mfma_f32_16x16x32_bf16 v[124:127], v[160:163], v[172:175], v[124:127]
	v_mfma_f32_16x16x32_bf16 v[112:115], v[156:159], v[176:179], 0
	v_mfma_f32_16x16x32_bf16 v[112:115], v[160:163], v[180:183], v[112:115]
	v_mfma_f32_16x16x32_bf16 v[96:99], v[156:159], v[184:187], 0
	v_mfma_f32_16x16x32_bf16 v[96:99], v[160:163], v[188:191], v[96:99]
	v_mfma_f32_16x16x32_bf16 v[80:83], v[156:159], v[192:195], 0
	v_mfma_f32_16x16x32_bf16 v[80:83], v[160:163], v[212:215], v[80:83]
	s_barrier
	s_setprio 0
	s_add_u32 s14, s12, 0xfff80080
	s_addc_u32 s15, s13, -1
	s_cmp_eq_u32 s39, 28
	s_cselect_b32 s17, s1, s15
	s_cselect_b32 s16, s11, s14
	s_cselect_b32 s15, s3, s38
	s_cselect_b32 s14, s36, s37
	s_add_i32 s42, 0, 0x14000
	s_add_i32 s40, s40, s19
	ds_read_b128 v[216:219], v246 offset:16384
	ds_read_b128 v[220:223], v246 offset:17408
	ds_read_b128 v[224:227], v246 offset:18432
	ds_read_b128 v[228:231], v246 offset:19456
	s_add_u32 s98, s14, 0x80
	s_addc_u32 s99, s15, 0
	s_mov_b32 m0, s40
	s_nop 0
	global_load_lds_dwordx4 v134, s[14:15]
	s_add_i32 m0, s40, 0x2000
	s_nop 0
	global_load_lds_dwordx4 v0, s[14:15]
	s_mov_b32 m0, s24
	s_add_u32 s100, s16, 0x80
	s_addc_u32 s101, s17, 0
	s_waitcnt lgkmcnt(2)
	s_setprio 1
	s_barrier
	v_mfma_f32_16x16x32_bf16 v[116:119], v[216:219], v[168:171], 0
	v_mfma_f32_16x16x32_bf16 v[116:119], v[220:223], v[172:175], v[116:119]
	s_waitcnt lgkmcnt(0)
	v_mfma_f32_16x16x32_bf16 v[100:103], v[216:219], v[176:179], 0
	v_mfma_f32_16x16x32_bf16 v[100:103], v[220:223], v[180:183], v[100:103]
	v_mfma_f32_16x16x32_bf16 v[84:87], v[216:219], v[184:187], 0
	v_mfma_f32_16x16x32_bf16 v[84:87], v[220:223], v[188:191], v[84:87]
	v_mfma_f32_16x16x32_bf16 v[72:75], v[216:219], v[192:195], 0
	v_mfma_f32_16x16x32_bf16 v[72:75], v[220:223], v[212:215], v[72:75]
	v_mfma_f32_16x16x32_bf16 v[108:111], v[224:227], v[168:171], 0
	v_mfma_f32_16x16x32_bf16 v[108:111], v[228:231], v[172:175], v[108:111]
	v_mfma_f32_16x16x32_bf16 v[92:95], v[224:227], v[176:179], 0
	v_mfma_f32_16x16x32_bf16 v[92:95], v[228:231], v[180:183], v[92:95]
	v_mfma_f32_16x16x32_bf16 v[76:79], v[224:227], v[184:187], 0
	v_mfma_f32_16x16x32_bf16 v[76:79], v[228:231], v[188:191], v[76:79]
	v_mfma_f32_16x16x32_bf16 v[68:71], v[224:227], v[192:195], 0
	v_mfma_f32_16x16x32_bf16 v[68:71], v[228:231], v[212:215], v[68:71]
	s_barrier
	s_setprio 0
	ds_read_b128 v[168:171], v146 offset:16384
	ds_read_b128 v[172:175], v146 offset:17408
	ds_read_b128 v[176:179], v146 offset:18432
	ds_read_b128 v[180:183], v146 offset:19456
	ds_read_b128 v[184:187], v146 offset:20480
	ds_read_b128 v[188:191], v146 offset:21504
	ds_read_b128 v[192:195], v146 offset:22528
	ds_read_b128 v[212:215], v146 offset:23552
	global_load_lds_dwordx4 v136, s[16:17]
	s_mov_b32 m0, s25
	s_nop 0
	global_load_lds_dwordx4 v132, s[16:17]
	s_waitcnt lgkmcnt(6)
	s_setprio 1
	s_barrier
	v_mfma_f32_16x16x32_bf16 v[64:67], v[148:151], v[168:171], 0
	v_mfma_f32_16x16x32_bf16 v[64:67], v[152:155], v[172:175], v[64:67]
	s_waitcnt lgkmcnt(0)
	v_mfma_f32_16x16x32_bf16 v[56:59], v[148:151], v[176:179], 0
	v_mfma_f32_16x16x32_bf16 v[56:59], v[152:155], v[180:183], v[56:59]
	v_mfma_f32_16x16x32_bf16 v[40:43], v[148:151], v[184:187], 0
	v_mfma_f32_16x16x32_bf16 v[40:43], v[152:155], v[188:191], v[40:43]
	v_mfma_f32_16x16x32_bf16 v[24:27], v[148:151], v[192:195], 0
	v_mfma_f32_16x16x32_bf16 v[24:27], v[152:155], v[212:215], v[24:27]
	v_mfma_f32_16x16x32_bf16 v[60:63], v[156:159], v[168:171], 0
	v_mfma_f32_16x16x32_bf16 v[60:63], v[160:163], v[172:175], v[60:63]
	v_mfma_f32_16x16x32_bf16 v[48:51], v[156:159], v[176:179], 0
	v_mfma_f32_16x16x32_bf16 v[48:51], v[160:163], v[180:183], v[48:51]
	v_mfma_f32_16x16x32_bf16 v[32:35], v[156:159], v[184:187], 0
	v_mfma_f32_16x16x32_bf16 v[32:35], v[160:163], v[188:191], v[32:35]
	v_mfma_f32_16x16x32_bf16 v[16:19], v[156:159], v[192:195], 0
	v_mfma_f32_16x16x32_bf16 v[16:19], v[160:163], v[212:215], v[16:19]
	s_barrier
; #define PG8_WAIT_V(n) asm volatile("s_waitcnt vmcnt(" #n ")" ::: "memory")
; #define PG8_WAIT_L(n) asm volatile("s_waitcnt lgkmcnt(" #n ")" ::: "memory")
; #define PG8_BAR __builtin_amdgcn_s_barrier()
; #define PG8_SCHED __builtin_amdgcn_sched_barrier(0)
; template <class Epi, class AddrA, class AddrB>
; __device__ __forceinline__ void gemm_phase(const Sched S, const int lda, const int ldb, const int K, const AddrA addrA,
;                                            const AddrB addrB, const Epi E) {
;     ...
;       PG8_BAR; PG8_WAIT_L(0); PG8_MMA(1, 0, At, B0); PG8_BAR; PG8_SCHED;
;       PG8_STAGE(PG8_SB(0, 1), b2 + hstepB, voffB);
;       PG8_WAIT_V(6); PG8_BAR; PG8_MMA(1, 1, At, B1); PG8_BAR;
;       PG8_LDB(B0, 1, 0); PG8_SCHED; PG8_LDA(At, 1, 0); PG8_STAGE(PG8_SA(0, 1), a2 + hstepA, voffA);
;       PG8_WAIT_L(8); PG8_BAR; PG8_WAIT_L(0); PG8_MMA(0, 0, At, B0); PG8_BAR; PG8_SCHED;
;       PG8_LDB(B1, 1, 1); PG8_STAGE(PG8_SB(1, 0), b3, voffB);
;       PG8_BAR; PG8_WAIT_L(0); PG8_MMA(0, 1, At, B1); PG8_BAR;
;       PG8_LDA(At, 1, 1); PG8_STAGE(PG8_SA(1, 0), a3, voffA);
;       PG8_BAR; PG8_WAIT_L(0); PG8_MMA(1, 0, At, B0); PG8_BAR; PG8_SCHED;
	s_setprio 0
	s_add_u32 s40, s14, 0x80000
	s_addc_u32 s41, s15, 0
	s_add_i32 s42, s42, s19
	s_mov_b32 m0, s42
	s_nop 0
	global_load_lds_dwordx4 v134, s[40:41]
	s_add_i32 m0, s42, 0x2000
	s_nop 0
	global_load_lds_dwordx4 v0, s[40:41]
	s_add_i32 s40, 0, 0x18000
	s_waitcnt vmcnt(6)
	s_setprio 1
	s_barrier
	v_mfma_f32_16x16x32_bf16 v[52:55], v[216:219], v[168:171], 0
	v_mfma_f32_16x16x32_bf16 v[52:55], v[220:223], v[172:175], v[52:55]
	v_mfma_f32_16x16x32_bf16 v[36:39], v[216:219], v[176:179], 0
	v_mfma_f32_16x16x32_bf16 v[36:39], v[220:223], v[180:183], v[36:39]
	v_mfma_f32_16x16x32_bf16 v[20:23], v[216:219], v[184:187], 0
	v_mfma_f32_16x16x32_bf16 v[20:23], v[220:223], v[188:191], v[20:23]
	v_mfma_f32_16x16x32_bf16 v[8:11], v[216:219], v[192:195], 0
	v_mfma_f32_16x16x32_bf16 v[8:11], v[220:223], v[212:215], v[8:11]
	v_mfma_f32_16x16x32_bf16 v[44:47], v[224:227], v[168:171], 0
	v_mfma_f32_16x16x32_bf16 v[44:47], v[228:231], v[172:175], v[44:47]
	v_mfma_f32_16x16x32_bf16 v[28:31], v[224:227], v[176:179], 0
	v_mfma_f32_16x16x32_bf16 v[28:31], v[228:231], v[180:183], v[28:31]
	v_mfma_f32_16x16x32_bf16 v[12:15], v[224:227], v[184:187], 0
	v_mfma_f32_16x16x32_bf16 v[12:15], v[228:231], v[188:191], v[12:15]
	v_mfma_f32_16x16x32_bf16 v[4:7], v[224:227], v[192:195], 0
	v_mfma_f32_16x16x32_bf16 v[4:7], v[228:231], v[212:215], v[4:7]
	s_barrier
	s_setprio 0
	ds_read_b128 v[148:151], v246 offset:32768
	ds_read_b128 v[152:155], v246 offset:33792
	ds_read_b128 v[156:159], v246 offset:34816
	ds_read_b128 v[160:163], v246 offset:35840
	s_add_u32 s16, s16, 0x80000
	s_addc_u32 s17, s17, 0
	s_mov_b32 m0, s26
	ds_read_b128 v[168:171], v146 offset:32768
	ds_read_b128 v[172:175], v146 offset:33792
	ds_read_b128 v[176:179], v146 offset:34816
	ds_read_b128 v[180:183], v146 offset:35840
	ds_read_b128 v[184:187], v146 offset:36864
	ds_read_b128 v[188:191], v146 offset:37888
	ds_read_b128 v[192:195], v146 offset:38912
	ds_read_b128 v[212:215], v146 offset:39936
	global_load_lds_dwordx4 v136, s[16:17]
	s_mov_b32 m0, s27
	s_nop 0
	global_load_lds_dwordx4 v132, s[16:17]
	s_waitcnt lgkmcnt(6)
	s_setprio 1
	s_barrier
	v_mfma_f32_16x16x32_bf16 v[128:131], v[148:151], v[168:171], v[128:131]
	v_mfma_f32_16x16x32_bf16 v[128:131], v[152:155], v[172:175], v[128:131]
	s_waitcnt lgkmcnt(0)
	v_mfma_f32_16x16x32_bf16 v[120:123], v[148:151], v[176:179], v[120:123]
	v_mfma_f32_16x16x32_bf16 v[120:123], v[152:155], v[180:183], v[120:123]
	v_mfma_f32_16x16x32_bf16 v[104:107], v[148:151], v[184:187], v[104:107]
	v_mfma_f32_16x16x32_bf16 v[104:107], v[152:155], v[188:191], v[104:107]
	v_mfma_f32_16x16x32_bf16 v[88:91], v[148:151], v[192:195], v[88:91]
	v_mfma_f32_16x16x32_bf16 v[88:91], v[152:155], v[212:215], v[88:91]
	v_mfma_f32_16x16x32_bf16 v[124:127], v[156:159], v[168:171], v[124:127]
	v_mfma_f32_16x16x32_bf16 v[124:127], v[160:163], v[172:175], v[124:127]
	v_mfma_f32_16x16x32_bf16 v[112:115], v[156:159], v[176:179], v[112:115]
	v_mfma_f32_16x16x32_bf16 v[112:115], v[160:163], v[180:183], v[112:115]
	v_mfma_f32_16x16x32_bf16 v[96:99], v[156:159], v[184:187], v[96:99]
	v_mfma_f32_16x16x32_bf16 v[96:99], v[160:163], v[188:191], v[96:99]
	v_mfma_f32_16x16x32_bf16 v[80:83], v[156:159], v[192:195], v[80:83]
	v_mfma_f32_16x16x32_bf16 v[80:83], v[160:163], v[212:215], v[80:83]
	s_barrier
	s_setprio 0
	s_add_i32 s16, 0, 0x1c000
	s_add_i32 s17, s40, s19
	s_mov_b32 m0, s17
	ds_read_b128 v[216:219], v246 offset:49152
	ds_read_b128 v[220:223], v246 offset:50176
	ds_read_b128 v[224:227], v246 offset:51200
	ds_read_b128 v[228:231], v246 offset:52224
	global_load_lds_dwordx4 v134, s[98:99]
	s_add_i32 m0, s17, 0x2000
	s_nop 0
	global_load_lds_dwordx4 v0, s[98:99]
	s_mov_b32 m0, s30
	s_waitcnt lgkmcnt(2)
	s_setprio 1
	s_barrier
	v_mfma_f32_16x16x32_bf16 v[116:119], v[216:219], v[168:171], v[116:119]
	v_mfma_f32_16x16x32_bf16 v[116:119], v[220:223], v[172:175], v[116:119]
	s_waitcnt lgkmcnt(0)
	v_mfma_f32_16x16x32_bf16 v[100:103], v[216:219], v[176:179], v[100:103]
	v_mfma_f32_16x16x32_bf16 v[100:103], v[220:223], v[180:183], v[100:103]
	v_mfma_f32_16x16x32_bf16 v[84:87], v[216:219], v[184:187], v[84:87]
	v_mfma_f32_16x16x32_bf16 v[84:87], v[220:223], v[188:191], v[84:87]
	v_mfma_f32_16x16x32_bf16 v[72:75], v[216:219], v[192:195], v[72:75]
	v_mfma_f32_16x16x32_bf16 v[72:75], v[220:223], v[212:215], v[72:75]
	v_mfma_f32_16x16x32_bf16 v[108:111], v[224:227], v[168:171], v[108:111]
	v_mfma_f32_16x16x32_bf16 v[108:111], v[228:231], v[172:175], v[108:111]
	v_mfma_f32_16x16x32_bf16 v[92:95], v[224:227], v[176:179], v[92:95]
	v_mfma_f32_16x16x32_bf16 v[92:95], v[228:231], v[180:183], v[92:95]
	v_mfma_f32_16x16x32_bf16 v[76:79], v[224:227], v[184:187], v[76:79]
	v_mfma_f32_16x16x32_bf16 v[76:79], v[228:231], v[188:191], v[76:79]
	v_mfma_f32_16x16x32_bf16 v[68:71], v[224:227], v[192:195], v[68:71]
	v_mfma_f32_16x16x32_bf16 v[68:71], v[228:231], v[212:215], v[68:71]
	s_barrier
	s_setprio 0
	ds_read_b128 v[168:171], v146 offset:49152
	ds_read_b128 v[172:175], v146 offset:50176
	ds_read_b128 v[176:179], v146 offset:51200
	ds_read_b128 v[180:183], v146 offset:52224
	ds_read_b128 v[184:187], v146 offset:53248
	ds_read_b128 v[188:191], v146 offset:54272
	ds_read_b128 v[192:195], v146 offset:55296
	ds_read_b128 v[212:215], v146 offset:56320
	global_load_lds_dwordx4 v136, s[100:101]
	s_mov_b32 m0, s31
	s_nop 0
	global_load_lds_dwordx4 v132, s[100:101]
	s_waitcnt lgkmcnt(6)
	s_setprio 1
	s_barrier
; #define PG8_WAIT_V(n) asm volatile("s_waitcnt vmcnt(" #n ")" ::: "memory")
; #define PG8_WAIT_L(n) asm volatile("s_waitcnt lgkmcnt(" #n ")" ::: "memory")
; #define PG8_BAR __builtin_amdgcn_s_barrier()
; #define PG8_SCHED __builtin_amdgcn_sched_barrier(0)
; template <class Epi, class AddrA, class AddrB>
; __device__ __forceinline__ void gemm_phase(const Sched S, const int lda, const int ldb, const int K, const AddrA addrA,
;                                            const AddrB addrB, const Epi E) {
;     ...
;       PG8_LDB(B0, 0, 0); PG8_SCHED; PG8_LDA(At, 0, 0); PG8_STAGE(PG8_SA(1, 1), a1 + hstepA, voffA);
;       PG8_WAIT_L(8); PG8_BAR; PG8_WAIT_L(0); PG8_MMA(0, 0, At, B0); PG8_BAR; PG8_SCHED;
;       PG8_LDB(B1, 0, 1); PG8_STAGE(PG8_SB(0, 0), b2, voffB);
;       PG8_BAR; PG8_WAIT_L(0); PG8_MMA(0, 1, At, B1); PG8_BAR;
;     ...
;       PG8_BAR; PG8_WAIT_L(0); PG8_MMA(0, 1, At, B1); PG8_BAR;
;       PG8_LDA(At, 1, 1); PG8_STAGE(PG8_SA(1, 0), a3, voffA);
;       PG8_BAR; PG8_WAIT_L(0); PG8_MMA(1, 0, At, B0); PG8_BAR; PG8_SCHED;
;       PG8_STAGE(PG8_SB(1, 1), b3 + hstepB, voffB);
;       PG8_WAIT_V(6); PG8_BAR; PG8_MMA(1, 1, At, B1); PG8_BAR;
	v_mfma_f32_16x16x32_bf16 v[64:67], v[148:151], v[168:171], v[64:67]
	v_mfma_f32_16x16x32_bf16 v[64:67], v[152:155], v[172:175], v[64:67]
	s_waitcnt lgkmcnt(0)
	v_mfma_f32_16x16x32_bf16 v[56:59], v[148:151], v[176:179], v[56:59]
	v_mfma_f32_16x16x32_bf16 v[56:59], v[152:155], v[180:183], v[56:59]
	v_mfma_f32_16x16x32_bf16 v[40:43], v[148:151], v[184:187], v[40:43]
	v_mfma_f32_16x16x32_bf16 v[40:43], v[152:155], v[188:191], v[40:43]
	v_mfma_f32_16x16x32_bf16 v[24:27], v[148:151], v[192:195], v[24:27]
	v_mfma_f32_16x16x32_bf16 v[24:27], v[152:155], v[212:215], v[24:27]
	v_mfma_f32_16x16x32_bf16 v[60:63], v[156:159], v[168:171], v[60:63]
	v_mfma_f32_16x16x32_bf16 v[60:63], v[160:163], v[172:175], v[60:63]
	v_mfma_f32_16x16x32_bf16 v[48:51], v[156:159], v[176:179], v[48:51]
	v_mfma_f32_16x16x32_bf16 v[48:51], v[160:163], v[180:183], v[48:51]
	v_mfma_f32_16x16x32_bf16 v[32:35], v[156:159], v[184:187], v[32:35]
	v_mfma_f32_16x16x32_bf16 v[32:35], v[160:163], v[188:191], v[32:35]
	v_mfma_f32_16x16x32_bf16 v[16:19], v[156:159], v[192:195], v[16:19]
	v_mfma_f32_16x16x32_bf16 v[16:19], v[160:163], v[212:215], v[16:19]
	s_barrier
	s_setprio 0
	s_add_u32 s14, s14, 0x80080
	s_addc_u32 s15, s15, 0
	s_add_i32 s16, s16, s19
	s_mov_b32 m0, s16
	s_nop 0
	global_load_lds_dwordx4 v134, s[14:15]
	s_add_i32 m0, s16, 0x2000
	s_nop 0
	global_load_lds_dwordx4 v0, s[14:15]
	s_add_i32 s39, s39, 2
	s_add_u32 s37, s37, 0x100
	s_addc_u32 s38, s38, 0
	s_add_u32 s12, s12, 0x100
	s_addc_u32 s13, s13, 0
	s_waitcnt vmcnt(6)
	s_setprio 1
	s_barrier
	v_mfma_f32_16x16x32_bf16 v[52:55], v[216:219], v[168:171], v[52:55]
	v_mfma_f32_16x16x32_bf16 v[52:55], v[220:223], v[172:175], v[52:55]
	v_mfma_f32_16x16x32_bf16 v[36:39], v[216:219], v[176:179], v[36:39]
	v_mfma_f32_16x16x32_bf16 v[36:39], v[220:223], v[180:183], v[36:39]
	v_mfma_f32_16x16x32_bf16 v[20:23], v[216:219], v[184:187], v[20:23]
	v_mfma_f32_16x16x32_bf16 v[20:23], v[220:223], v[188:191], v[20:23]
	v_mfma_f32_16x16x32_bf16 v[8:11], v[216:219], v[192:195], v[8:11]
	v_mfma_f32_16x16x32_bf16 v[8:11], v[220:223], v[212:215], v[8:11]
	v_mfma_f32_16x16x32_bf16 v[44:47], v[224:227], v[168:171], v[44:47]
	v_mfma_f32_16x16x32_bf16 v[44:47], v[228:231], v[172:175], v[44:47]
	v_mfma_f32_16x16x32_bf16 v[28:31], v[224:227], v[176:179], v[28:31]
	v_mfma_f32_16x16x32_bf16 v[28:31], v[228:231], v[180:183], v[28:31]
	v_mfma_f32_16x16x32_bf16 v[12:15], v[224:227], v[184:187], v[12:15]
	v_mfma_f32_16x16x32_bf16 v[12:15], v[228:231], v[188:191], v[12:15]
	v_mfma_f32_16x16x32_bf16 v[4:7], v[224:227], v[192:195], v[4:7]
	v_mfma_f32_16x16x32_bf16 v[4:7], v[228:231], v[212:215], v[4:7]
	s_barrier
	s_setprio 0
	s_cmp_gt_u32 s39, 29
.LBB0_109:
	s_add_i32 s40, 0, 0x10000
	v_add_u32_e32 v246, s40, v145
	ds_read_b128 v[148:151], v246
	ds_read_b128 v[152:155], v246 offset:1024
	ds_read_b128 v[156:159], v246 offset:2048
	ds_read_b128 v[160:163], v246 offset:3072
	s_add_i32 m0, s24, 0xc000
	ds_read_b128 v[168:171], v146
	ds_read_b128 v[172:175], v146 offset:1024
	ds_read_b128 v[176:179], v146 offset:2048
	ds_read_b128 v[180:183], v146 offset:3072
	ds_read_b128 v[184:187], v146 offset:4096
	ds_read_b128 v[188:191], v146 offset:5120
	ds_read_b128 v[192:195], v146 offset:6144
	ds_read_b128 v[212:215], v146 offset:7168
	global_load_lds_dwordx4 v140, s[12:13]
	s_add_i32 m0, s24, 0xe000
	s_nop 0
	global_load_lds_dwordx4 v138, s[12:13]
	s_waitcnt lgkmcnt(6)
	s_setprio 1
	s_barrier
	v_mfma_f32_16x16x32_bf16 v[128:131], v[148:151], v[168:171], v[128:131]
	v_mfma_f32_16x16x32_bf16 v[128:131], v[152:155], v[172:175], v[128:131]
	s_waitcnt lgkmcnt(0)
	v_mfma_f32_16x16x32_bf16 v[120:123], v[148:151], v[176:179], v[120:123]
	v_mfma_f32_16x16x32_bf16 v[120:123], v[152:155], v[180:183], v[120:123]
	v_mfma_f32_16x16x32_bf16 v[104:107], v[148:151], v[184:187], v[104:107]
	v_mfma_f32_16x16x32_bf16 v[104:107], v[152:155], v[188:191], v[104:107]
	v_mfma_f32_16x16x32_bf16 v[88:91], v[148:151], v[192:195], v[88:91]
	v_mfma_f32_16x16x32_bf16 v[88:91], v[152:155], v[212:215], v[88:91]
	v_mfma_f32_16x16x32_bf16 v[124:127], v[156:159], v[168:171], v[124:127]
	v_mfma_f32_16x16x32_bf16 v[124:127], v[160:163], v[172:175], v[124:127]
	v_mfma_f32_16x16x32_bf16 v[112:115], v[156:159], v[176:179], v[112:115]
	v_mfma_f32_16x16x32_bf16 v[112:115], v[160:163], v[180:183], v[112:115]
	v_mfma_f32_16x16x32_bf16 v[96:99], v[156:159], v[184:187], v[96:99]
	v_mfma_f32_16x16x32_bf16 v[96:99], v[160:163], v[188:191], v[96:99]
	v_mfma_f32_16x16x32_bf16 v[80:83], v[156:159], v[192:195], v[80:83]
	v_mfma_f32_16x16x32_bf16 v[80:83], v[160:163], v[212:215], v[80:83]
	s_barrier
	s_setprio 0
	s_add_u32 s14, s12, 0xfff80080
	s_addc_u32 s15, s13, -1
	s_cmp_eq_u32 s39, 28
	s_cselect_b32 s17, s1, s15
	s_cselect_b32 s16, s11, s14
	s_cselect_b32 s15, s3, s38
	s_cselect_b32 s14, s36, s37
	s_add_i32 s42, 0, 0x14000
	s_add_i32 s40, s40, s19
	ds_read_b128 v[216:219], v246 offset:16384
	ds_read_b128 v[220:223], v246 offset:17408
	ds_read_b128 v[224:227], v246 offset:18432
	ds_read_b128 v[228:231], v246 offset:19456
	s_add_u32 s98, s14, 0x80
	s_addc_u32 s99, s15, 0
	s_mov_b32 m0, s40
	s_nop 0
	global_load_lds_dwordx4 v134, s[14:15]
	s_add_i32 m0, s40, 0x2000
	s_nop 0
	global_load_lds_dwordx4 v0, s[14:15]
	s_mov_b32 m0, s24
	s_add_u32 s100, s16, 0x80
	s_addc_u32 s101, s17, 0
	s_waitcnt lgkmcnt(2)
	s_setprio 1
	s_barrier
; #define PG8_WAIT_V(n) asm volatile("s_waitcnt vmcnt(" #n ")" ::: "memory")
; #define PG8_WAIT_L(n) asm volatile("s_waitcnt lgkmcnt(" #n ")" ::: "memory")
; #define PG8_BAR __builtin_amdgcn_s_barrier()
; #define PG8_SCHED __builtin_amdgcn_sched_barrier(0)
; template <class Epi, class AddrA, class AddrB>
; __device__ __forceinline__ void gemm_phase(const Sched S, const int lda, const int ldb, const int K, const AddrA addrA,
;                                            const AddrB addrB, const Epi E) {
;     ...
;       PG8_LDB(B0, 0, 0); PG8_SCHED; PG8_LDA(At, 0, 0); PG8_STAGE(PG8_SA(1, 1), a1 + hstepA, voffA);
;       PG8_WAIT_L(8); PG8_BAR; PG8_WAIT_L(0); PG8_MMA(0, 0, At, B0); PG8_BAR; PG8_SCHED;
;       PG8_LDB(B1, 0, 1); PG8_STAGE(PG8_SB(0, 0), b2, voffB);
;       PG8_BAR; PG8_WAIT_L(0); PG8_MMA(0, 1, At, B1); PG8_BAR;
;       PG8_LDA(At, 0, 1); PG8_STAGE(PG8_SA(0, 0), a2, voffA);
;       PG8_BAR; PG8_WAIT_L(0); PG8_MMA(1, 0, At, B0); PG8_BAR; PG8_SCHED;
;       PG8_STAGE(PG8_SB(0, 1), b2 + hstepB, voffB);
;       PG8_WAIT_V(6); PG8_BAR; PG8_MMA(1, 1, At, B1); PG8_BAR;
;       PG8_LDB(B0, 1, 0); PG8_SCHED; PG8_LDA(At, 1, 0); PG8_STAGE(PG8_SA(0, 1), a2 + hstepA, voffA);
;       PG8_WAIT_L(8); PG8_BAR; PG8_WAIT_L(0); PG8_MMA(0, 0, At, B0); PG8_BAR; PG8_SCHED;
;       PG8_LDB(B1, 1, 1); PG8_STAGE(PG8_SB(1, 0), b3, voffB);
;       PG8_BAR; PG8_WAIT_L(0); PG8_MMA(0, 1, At, B1); PG8_BAR;
;       PG8_LDA(At, 1, 1); PG8_STAGE(PG8_SA(1, 0), a3, voffA);
;       PG8_BAR; PG8_WAIT_L(0); PG8_MMA(1, 0, At, B0); PG8_BAR; PG8_SCHED;
;       PG8_STAGE(PG8_SB(1, 1), b3 + hstepB, voffB);
;       PG8_WAIT_V(6); PG8_BAR; PG8_MMA(1, 1, At, B1); PG8_BAR;
	v_mfma_f32_16x16x32_bf16 v[116:119], v[216:219], v[168:171], v[116:119]
	v_mfma_f32_16x16x32_bf16 v[116:119], v[220:223], v[172:175], v[116:119]
	s_waitcnt lgkmcnt(0)
	v_mfma_f32_16x16x32_bf16 v[100:103], v[216:219], v[176:179], v[100:103]
	v_mfma_f32_16x16x32_bf16 v[100:103], v[220:223], v[180:183], v[100:103]
	v_mfma_f32_16x16x32_bf16 v[84:87], v[216:219], v[184:187], v[84:87]
	v_mfma_f32_16x16x32_bf16 v[84:87], v[220:223], v[188:191], v[84:87]
	v_mfma_f32_16x16x32_bf16 v[72:75], v[216:219], v[192:195], v[72:75]
	v_mfma_f32_16x16x32_bf16 v[72:75], v[220:223], v[212:215], v[72:75]
	v_mfma_f32_16x16x32_bf16 v[108:111], v[224:227], v[168:171], v[108:111]
	v_mfma_f32_16x16x32_bf16 v[108:111], v[228:231], v[172:175], v[108:111]
	v_mfma_f32_16x16x32_bf16 v[92:95], v[224:227], v[176:179], v[92:95]
	v_mfma_f32_16x16x32_bf16 v[92:95], v[228:231], v[180:183], v[92:95]
	v_mfma_f32_16x16x32_bf16 v[76:79], v[224:227], v[184:187], v[76:79]
	v_mfma_f32_16x16x32_bf16 v[76:79], v[228:231], v[188:191], v[76:79]
	v_mfma_f32_16x16x32_bf16 v[68:71], v[224:227], v[192:195], v[68:71]
	v_mfma_f32_16x16x32_bf16 v[68:71], v[228:231], v[212:215], v[68:71]
	s_barrier
	s_setprio 0
	ds_read_b128 v[168:171], v146 offset:16384
	ds_read_b128 v[172:175], v146 offset:17408
	ds_read_b128 v[176:179], v146 offset:18432
	ds_read_b128 v[180:183], v146 offset:19456
	ds_read_b128 v[184:187], v146 offset:20480
	ds_read_b128 v[188:191], v146 offset:21504
	ds_read_b128 v[192:195], v146 offset:22528
	ds_read_b128 v[212:215], v146 offset:23552
	global_load_lds_dwordx4 v136, s[16:17]
	s_mov_b32 m0, s25
	s_nop 0
	global_load_lds_dwordx4 v132, s[16:17]
	s_waitcnt lgkmcnt(6)
	s_setprio 1
	s_barrier
	v_mfma_f32_16x16x32_bf16 v[64:67], v[148:151], v[168:171], v[64:67]
	v_mfma_f32_16x16x32_bf16 v[64:67], v[152:155], v[172:175], v[64:67]
	s_waitcnt lgkmcnt(0)
	v_mfma_f32_16x16x32_bf16 v[56:59], v[148:151], v[176:179], v[56:59]
	v_mfma_f32_16x16x32_bf16 v[56:59], v[152:155], v[180:183], v[56:59]
	v_mfma_f32_16x16x32_bf16 v[40:43], v[148:151], v[184:187], v[40:43]
	v_mfma_f32_16x16x32_bf16 v[40:43], v[152:155], v[188:191], v[40:43]
	v_mfma_f32_16x16x32_bf16 v[24:27], v[148:151], v[192:195], v[24:27]
	v_mfma_f32_16x16x32_bf16 v[24:27], v[152:155], v[212:215], v[24:27]
	v_mfma_f32_16x16x32_bf16 v[60:63], v[156:159], v[168:171], v[60:63]
	v_mfma_f32_16x16x32_bf16 v[60:63], v[160:163], v[172:175], v[60:63]
	v_mfma_f32_16x16x32_bf16 v[48:51], v[156:159], v[176:179], v[48:51]
	v_mfma_f32_16x16x32_bf16 v[48:51], v[160:163], v[180:183], v[48:51]
	v_mfma_f32_16x16x32_bf16 v[32:35], v[156:159], v[184:187], v[32:35]
	v_mfma_f32_16x16x32_bf16 v[32:35], v[160:163], v[188:191], v[32:35]
	v_mfma_f32_16x16x32_bf16 v[16:19], v[156:159], v[192:195], v[16:19]
	v_mfma_f32_16x16x32_bf16 v[16:19], v[160:163], v[212:215], v[16:19]
	s_barrier
	s_setprio 0
	s_add_u32 s40, s14, 0x80000
	s_addc_u32 s41, s15, 0
	s_add_i32 s42, s42, s19
	s_mov_b32 m0, s42
	s_nop 0
	global_load_lds_dwordx4 v134, s[40:41]
	s_add_i32 m0, s42, 0x2000
	s_nop 0
	global_load_lds_dwordx4 v0, s[40:41]
	s_add_i32 s40, 0, 0x18000
	s_waitcnt vmcnt(6)
	s_setprio 1
	s_barrier
	v_mfma_f32_16x16x32_bf16 v[52:55], v[216:219], v[168:171], v[52:55]
	v_mfma_f32_16x16x32_bf16 v[52:55], v[220:223], v[172:175], v[52:55]
	v_mfma_f32_16x16x32_bf16 v[36:39], v[216:219], v[176:179], v[36:39]
	v_mfma_f32_16x16x32_bf16 v[36:39], v[220:223], v[180:183], v[36:39]
	v_mfma_f32_16x16x32_bf16 v[20:23], v[216:219], v[184:187], v[20:23]
	v_mfma_f32_16x16x32_bf16 v[20:23], v[220:223], v[188:191], v[20:23]
	v_mfma_f32_16x16x32_bf16 v[8:11], v[216:219], v[192:195], v[8:11]
	v_mfma_f32_16x16x32_bf16 v[8:11], v[220:223], v[212:215], v[8:11]
	v_mfma_f32_16x16x32_bf16 v[44:47], v[224:227], v[168:171], v[44:47]
	v_mfma_f32_16x16x32_bf16 v[44:47], v[228:231], v[172:175], v[44:47]
	v_mfma_f32_16x16x32_bf16 v[28:31], v[224:227], v[176:179], v[28:31]
	v_mfma_f32_16x16x32_bf16 v[28:31], v[228:231], v[180:183], v[28:31]
	v_mfma_f32_16x16x32_bf16 v[12:15], v[224:227], v[184:187], v[12:15]
	v_mfma_f32_16x16x32_bf16 v[12:15], v[228:231], v[188:191], v[12:15]
	v_mfma_f32_16x16x32_bf16 v[4:7], v[224:227], v[192:195], v[4:7]
	v_mfma_f32_16x16x32_bf16 v[4:7], v[228:231], v[212:215], v[4:7]
	s_barrier
	s_setprio 0
	ds_read_b128 v[148:151], v246 offset:32768
	ds_read_b128 v[152:155], v246 offset:33792
	ds_read_b128 v[156:159], v246 offset:34816
	ds_read_b128 v[160:163], v246 offset:35840
	s_add_u32 s16, s16, 0x80000
	s_addc_u32 s17, s17, 0
	s_mov_b32 m0, s26
	ds_read_b128 v[168:171], v146 offset:32768
	ds_read_b128 v[172:175], v146 offset:33792
	ds_read_b128 v[176:179], v146 offset:34816
	ds_read_b128 v[180:183], v146 offset:35840
	ds_read_b128 v[184:187], v146 offset:36864
	ds_read_b128 v[188:191], v146 offset:37888
	ds_read_b128 v[192:195], v146 offset:38912
	ds_read_b128 v[212:215], v146 offset:39936
	global_load_lds_dwordx4 v136, s[16:17]
	s_mov_b32 m0, s27
	s_nop 0
	global_load_lds_dwordx4 v132, s[16:17]
	s_waitcnt lgkmcnt(6)
	s_setprio 1
	s_barrier
	v_mfma_f32_16x16x32_bf16 v[128:131], v[148:151], v[168:171], v[128:131]
	v_mfma_f32_16x16x32_bf16 v[128:131], v[152:155], v[172:175], v[128:131]
	s_waitcnt lgkmcnt(0)
	v_mfma_f32_16x16x32_bf16 v[120:123], v[148:151], v[176:179], v[120:123]
	v_mfma_f32_16x16x32_bf16 v[120:123], v[152:155], v[180:183], v[120:123]
	v_mfma_f32_16x16x32_bf16 v[104:107], v[148:151], v[184:187], v[104:107]
	v_mfma_f32_16x16x32_bf16 v[104:107], v[152:155], v[188:191], v[104:107]
	v_mfma_f32_16x16x32_bf16 v[88:91], v[148:151], v[192:195], v[88:91]
	v_mfma_f32_16x16x32_bf16 v[88:91], v[152:155], v[212:215], v[88:91]
	v_mfma_f32_16x16x32_bf16 v[124:127], v[156:159], v[168:171], v[124:127]
	v_mfma_f32_16x16x32_bf16 v[124:127], v[160:163], v[172:175], v[124:127]
	v_mfma_f32_16x16x32_bf16 v[112:115], v[156:159], v[176:179], v[112:115]
	v_mfma_f32_16x16x32_bf16 v[112:115], v[160:163], v[180:183], v[112:115]
	v_mfma_f32_16x16x32_bf16 v[96:99], v[156:159], v[184:187], v[96:99]
	v_mfma_f32_16x16x32_bf16 v[96:99], v[160:163], v[188:191], v[96:99]
	v_mfma_f32_16x16x32_bf16 v[80:83], v[156:159], v[192:195], v[80:83]
	v_mfma_f32_16x16x32_bf16 v[80:83], v[160:163], v[212:215], v[80:83]
	s_barrier
; #define PG8_WAIT_V(n) asm volatile("s_waitcnt vmcnt(" #n ")" ::: "memory")
; #define PG8_WAIT_L(n) asm volatile("s_waitcnt lgkmcnt(" #n ")" ::: "memory")
; #define PG8_BAR __builtin_amdgcn_s_barrier()
; #define PG8_SCHED __builtin_amdgcn_sched_barrier(0)
; template <class Epi, class AddrA, class AddrB>
; __device__ __forceinline__ void gemm_phase(const Sched S, const int lda, const int ldb, const int K, const AddrA addrA,
;                                            const AddrB addrB, const Epi E) {
;     ...
;       PG8_STAGE(PG8_SB(0, 1), b2 + hstepB, voffB);
;       PG8_WAIT_V(6); PG8_BAR; PG8_MMA(1, 1, At, B1); PG8_BAR;
;       PG8_LDB(B0, 1, 0); PG8_SCHED; PG8_LDA(At, 1, 0); PG8_STAGE(PG8_SA(0, 1), a2 + hstepA, voffA);
;       PG8_WAIT_L(8); PG8_BAR; PG8_WAIT_L(0); PG8_MMA(0, 0, At, B0); PG8_BAR; PG8_SCHED;
;       PG8_LDB(B1, 1, 1); PG8_STAGE(PG8_SB(1, 0), b3, voffB);
;       PG8_BAR; PG8_WAIT_L(0); PG8_MMA(0, 1, At, B1); PG8_BAR;
;       PG8_LDA(At, 1, 1); PG8_STAGE(PG8_SA(1, 0), a3, voffA);
;       PG8_BAR; PG8_WAIT_L(0); PG8_MMA(1, 0, At, B0); PG8_BAR; PG8_SCHED;
;       PG8_STAGE(PG8_SB(1, 1), b3 + hstepB, voffB);
;       PG8_WAIT_V(6); PG8_BAR; PG8_MMA(1, 1, At, B1); PG8_BAR;
	s_setprio 0
	s_add_i32 s16, 0, 0x1c000
	s_add_i32 s17, s40, s19
	s_mov_b32 m0, s17
	ds_read_b128 v[216:219], v246 offset:49152
	ds_read_b128 v[220:223], v246 offset:50176
	ds_read_b128 v[224:227], v246 offset:51200
	ds_read_b128 v[228:231], v246 offset:52224
	global_load_lds_dwordx4 v134, s[98:99]
	s_add_i32 m0, s17, 0x2000
	s_nop 0
	global_load_lds_dwordx4 v0, s[98:99]
	s_mov_b32 m0, s30
	s_waitcnt lgkmcnt(2)
	s_setprio 1
	s_barrier
	v_mfma_f32_16x16x32_bf16 v[116:119], v[216:219], v[168:171], v[116:119]
	v_mfma_f32_16x16x32_bf16 v[116:119], v[220:223], v[172:175], v[116:119]
	s_waitcnt lgkmcnt(0)
	v_mfma_f32_16x16x32_bf16 v[100:103], v[216:219], v[176:179], v[100:103]
	v_mfma_f32_16x16x32_bf16 v[100:103], v[220:223], v[180:183], v[100:103]
	v_mfma_f32_16x16x32_bf16 v[84:87], v[216:219], v[184:187], v[84:87]
	v_mfma_f32_16x16x32_bf16 v[84:87], v[220:223], v[188:191], v[84:87]
	v_mfma_f32_16x16x32_bf16 v[72:75], v[216:219], v[192:195], v[72:75]
	v_mfma_f32_16x16x32_bf16 v[72:75], v[220:223], v[212:215], v[72:75]
	v_mfma_f32_16x16x32_bf16 v[108:111], v[224:227], v[168:171], v[108:111]
	v_mfma_f32_16x16x32_bf16 v[108:111], v[228:231], v[172:175], v[108:111]
	v_mfma_f32_16x16x32_bf16 v[92:95], v[224:227], v[176:179], v[92:95]
	v_mfma_f32_16x16x32_bf16 v[92:95], v[228:231], v[180:183], v[92:95]
	v_mfma_f32_16x16x32_bf16 v[76:79], v[224:227], v[184:187], v[76:79]
	v_mfma_f32_16x16x32_bf16 v[76:79], v[228:231], v[188:191], v[76:79]
	v_mfma_f32_16x16x32_bf16 v[68:71], v[224:227], v[192:195], v[68:71]
	v_mfma_f32_16x16x32_bf16 v[68:71], v[228:231], v[212:215], v[68:71]
	s_barrier
	s_setprio 0
	ds_read_b128 v[168:171], v146 offset:49152
	ds_read_b128 v[172:175], v146 offset:50176
	ds_read_b128 v[176:179], v146 offset:51200
	ds_read_b128 v[180:183], v146 offset:52224
	ds_read_b128 v[184:187], v146 offset:53248
	ds_read_b128 v[188:191], v146 offset:54272
	ds_read_b128 v[192:195], v146 offset:55296
	ds_read_b128 v[212:215], v146 offset:56320
	global_load_lds_dwordx4 v136, s[100:101]
	s_mov_b32 m0, s31
	s_nop 0
	global_load_lds_dwordx4 v132, s[100:101]
	s_waitcnt lgkmcnt(6)
	s_setprio 1
	s_barrier
	v_mfma_f32_16x16x32_bf16 v[64:67], v[148:151], v[168:171], v[64:67]
	v_mfma_f32_16x16x32_bf16 v[64:67], v[152:155], v[172:175], v[64:67]
	s_waitcnt lgkmcnt(0)
	v_mfma_f32_16x16x32_bf16 v[56:59], v[148:151], v[176:179], v[56:59]
	v_mfma_f32_16x16x32_bf16 v[56:59], v[152:155], v[180:183], v[56:59]
	v_mfma_f32_16x16x32_bf16 v[40:43], v[148:151], v[184:187], v[40:43]
	v_mfma_f32_16x16x32_bf16 v[40:43], v[152:155], v[188:191], v[40:43]
	v_mfma_f32_16x16x32_bf16 v[24:27], v[148:151], v[192:195], v[24:27]
	v_mfma_f32_16x16x32_bf16 v[24:27], v[152:155], v[212:215], v[24:27]
	v_mfma_f32_16x16x32_bf16 v[60:63], v[156:159], v[168:171], v[60:63]
	v_mfma_f32_16x16x32_bf16 v[60:63], v[160:163], v[172:175], v[60:63]
	v_mfma_f32_16x16x32_bf16 v[48:51], v[156:159], v[176:179], v[48:51]
	v_mfma_f32_16x16x32_bf16 v[48:51], v[160:163], v[180:183], v[48:51]
	v_mfma_f32_16x16x32_bf16 v[32:35], v[156:159], v[184:187], v[32:35]
	v_mfma_f32_16x16x32_bf16 v[32:35], v[160:163], v[188:191], v[32:35]
	v_mfma_f32_16x16x32_bf16 v[16:19], v[156:159], v[192:195], v[16:19]
	v_mfma_f32_16x16x32_bf16 v[16:19], v[160:163], v[212:215], v[16:19]
	s_barrier
	s_setprio 0
	s_add_u32 s14, s14, 0x80080
	s_addc_u32 s15, s15, 0
	s_add_i32 s16, s16, s19
	s_mov_b32 m0, s16
	s_nop 0
	global_load_lds_dwordx4 v134, s[14:15]
	s_add_i32 m0, s16, 0x2000
	s_nop 0
	global_load_lds_dwordx4 v0, s[14:15]
	s_add_i32 s39, s39, 2
	s_add_u32 s37, s37, 0x100
	s_addc_u32 s38, s38, 0
	s_add_u32 s12, s12, 0x100
	s_addc_u32 s13, s13, 0
	s_waitcnt vmcnt(6)
	s_setprio 1
	s_barrier
	v_mfma_f32_16x16x32_bf16 v[52:55], v[216:219], v[168:171], v[52:55]
	v_mfma_f32_16x16x32_bf16 v[52:55], v[220:223], v[172:175], v[52:55]
	v_mfma_f32_16x16x32_bf16 v[36:39], v[216:219], v[176:179], v[36:39]
	v_mfma_f32_16x16x32_bf16 v[36:39], v[220:223], v[180:183], v[36:39]
	v_mfma_f32_16x16x32_bf16 v[20:23], v[216:219], v[184:187], v[20:23]
	v_mfma_f32_16x16x32_bf16 v[20:23], v[220:223], v[188:191], v[20:23]
	v_mfma_f32_16x16x32_bf16 v[8:11], v[216:219], v[192:195], v[8:11]
	v_mfma_f32_16x16x32_bf16 v[8:11], v[220:223], v[212:215], v[8:11]
	v_mfma_f32_16x16x32_bf16 v[44:47], v[224:227], v[168:171], v[44:47]
	v_mfma_f32_16x16x32_bf16 v[44:47], v[228:231], v[172:175], v[44:47]
	v_mfma_f32_16x16x32_bf16 v[28:31], v[224:227], v[176:179], v[28:31]
	v_mfma_f32_16x16x32_bf16 v[28:31], v[228:231], v[180:183], v[28:31]
	v_mfma_f32_16x16x32_bf16 v[12:15], v[224:227], v[184:187], v[12:15]
	v_mfma_f32_16x16x32_bf16 v[12:15], v[228:231], v[188:191], v[12:15]
	v_mfma_f32_16x16x32_bf16 v[4:7], v[224:227], v[192:195], v[4:7]
	v_mfma_f32_16x16x32_bf16 v[4:7], v[228:231], v[212:215], v[4:7]
	s_barrier
; template <class Epi, class AddrA, class AddrB>
; __device__ __forceinline__ void gemm_phase(const Sched S, const int lda, const int ldb, const int K, const AddrA addrA,
;                                            const AddrB addrB, const Epi E) {
;     ...
;     E(acc, cur, wr, wc, fr, fq);
;     if (!has_next) break;
;   __device__ __forceinline__ void operator()(EPI_ARGS) const {
;     bf16_t* base = proj + ((size_t)u.pn * MTOK + (size_t)(u.pm * 256 + wr * 64 + fr)) * PLD + wc * 32 + 8 * fq;
; #pragma unroll
;     for (int ai = 0; ai < 2; ++ai)
; #pragma unroll
;       for (int m = 0; m < 4; ++m) {
;         bf16_t* rowp = base + (size_t)(ai * HALF + m * 16) * PLD;
; #pragma unroll
;         for (int bj = 0; bj < 2; ++bj) {
;           const f32x4 v0 = acc[ai][bj][m][0], v1 = acc[ai][bj][m][1];
;           u32x4 o;
;           o.x = pack2(v0[0], v0[1]); o.y = pack2(v0[2], v0[3]); o.z = pack2(v1[0], v1[1]); o.w = pack2(v1[2], v1[3]);
;           *(u32x4*)(rowp + bj * HALF) = o;
;         }
;       }
	s_setprio 0
	s_cmp_gt_u32 s39, 29
	s_cbranch_scc0 .LBB0_109
	s_ashr_i32 s11, s10, 31
	v_lshl_add_u32 v142, s35, 8, v144
	s_lshl_b64 s[10:11], s[10:11], 23
	v_ashrrev_i32_e32 v143, 31, v142
	s_add_u32 s10, s28, s10
	s_addc_u32 s11, s29, s11
	v_lshlrev_b64 v[142:143], 9, v[142:143]
	v_lshl_add_u64 v[142:143], s[10:11], 0, v[142:143]
	v_lshl_add_u64 v[142:143], v[142:143], 0, s[72:73]
	v_lshl_add_u64 v[142:143], v[142:143], 0, v[2:3]
	v_cvt_pk_bf16_f32 v116, v116, v117
	v_cvt_pk_bf16_f32 v117, v118, v119
	v_cvt_pk_bf16_f32 v119, v110, v111
	v_cvt_pk_bf16_f32 v110, v112, v113
	v_add_co_u32_e32 v112, vcc, s96, v142
	s_movk_i32 s1, 0x4000
	s_nop 0
	v_addc_co_u32_e32 v113, vcc, 0, v143, vcc
	v_cvt_pk_bf16_f32 v100, v100, v101
	v_cvt_pk_bf16_f32 v101, v102, v103
	v_cvt_pk_bf16_f32 v103, v94, v95
	v_cvt_pk_bf16_f32 v94, v96, v97
	v_add_co_u32_e32 v96, vcc, s1, v142
	s_movk_i32 s1, 0x6000
	s_nop 0
	v_addc_co_u32_e32 v97, vcc, 0, v143, vcc
	v_cvt_pk_bf16_f32 v84, v84, v85
	v_cvt_pk_bf16_f32 v85, v86, v87
	v_cvt_pk_bf16_f32 v87, v78, v79
	v_cvt_pk_bf16_f32 v78, v80, v81
	v_add_co_u32_e32 v80, vcc, s1, v142
	v_cvt_pk_bf16_f32 v64, v64, v65
	v_cvt_pk_bf16_f32 v65, v66, v67
	v_cvt_pk_bf16_f32 v66, v60, v61
	s_mov_b32 s1, 0x12000
	s_nop 0
	v_addc_co_u32_e32 v81, vcc, 0, v143, vcc
	v_add_co_u32_e32 v60, vcc, s67, v142
	v_cvt_pk_bf16_f32 v52, v52, v53
	v_cvt_pk_bf16_f32 v53, v54, v55
	v_cvt_pk_bf16_f32 v55, v46, v47
	v_cvt_pk_bf16_f32 v46, v48, v49
	s_nop 1
	v_addc_co_u32_e32 v61, vcc, 0, v143, vcc
	v_add_co_u32_e32 v48, vcc, s1, v142
	s_mov_b32 s1, 0x14000
	s_nop 0
	v_addc_co_u32_e32 v49, vcc, 0, v143, vcc
	v_cvt_pk_bf16_f32 v36, v36, v37
	v_cvt_pk_bf16_f32 v37, v38, v39
	v_cvt_pk_bf16_f32 v39, v30, v31
	v_cvt_pk_bf16_f32 v30, v32, v33
	v_add_co_u32_e32 v32, vcc, s1, v142
	s_mov_b32 s1, 0x16000
	s_nop 0
	v_addc_co_u32_e32 v33, vcc, 0, v143, vcc
	v_cvt_pk_bf16_f32 v20, v20, v21
	v_cvt_pk_bf16_f32 v21, v22, v23
	v_cvt_pk_bf16_f32 v23, v14, v15
	v_cvt_pk_bf16_f32 v14, v16, v17
	v_add_co_u32_e32 v16, vcc, s1, v142
	s_mov_b32 s10, s2
	s_nop 0
	v_addc_co_u32_e32 v17, vcc, 0, v143, vcc
	s_and_b64 vcc, exec, s[4:5]
	s_mov_b32 s35, s0
	s_mov_b64 s[12:13], s[8:9]
	s_mov_b64 s[14:15], s[6:7]
	v_cvt_pk_bf16_f32 v128, v128, v129
	v_cvt_pk_bf16_f32 v129, v130, v131
	v_cvt_pk_bf16_f32 v130, v124, v125
	v_cvt_pk_bf16_f32 v131, v126, v127
	flat_store_dwordx4 v[142:143], v[128:131]
	v_cvt_pk_bf16_f32 v118, v108, v109
	flat_store_dwordx4 v[142:143], v[116:119] offset:256
	v_cvt_pk_bf16_f32 v108, v120, v121
	v_cvt_pk_bf16_f32 v109, v122, v123
	v_cvt_pk_bf16_f32 v111, v114, v115
	flat_store_dwordx4 v[112:113], v[108:111]
	v_cvt_pk_bf16_f32 v102, v92, v93
	flat_store_dwordx4 v[112:113], v[100:103] offset:256
	v_cvt_pk_bf16_f32 v92, v104, v105
	v_cvt_pk_bf16_f32 v93, v106, v107
	v_cvt_pk_bf16_f32 v95, v98, v99
	flat_store_dwordx4 v[96:97], v[92:95]
	v_cvt_pk_bf16_f32 v86, v76, v77
	flat_store_dwordx4 v[96:97], v[84:87] offset:256
	v_cvt_pk_bf16_f32 v76, v88, v89
	v_cvt_pk_bf16_f32 v77, v90, v91
	v_cvt_pk_bf16_f32 v79, v82, v83
	flat_store_dwordx4 v[80:81], v[76:79]
	v_cvt_pk_bf16_f32 v72, v72, v73
	v_cvt_pk_bf16_f32 v73, v74, v75
	v_cvt_pk_bf16_f32 v74, v68, v69
	v_cvt_pk_bf16_f32 v75, v70, v71
	flat_store_dwordx4 v[80:81], v[72:75] offset:256
	v_cvt_pk_bf16_f32 v67, v62, v63
	flat_store_dwordx4 v[60:61], v[64:67]
	v_cvt_pk_bf16_f32 v54, v44, v45
	flat_store_dwordx4 v[60:61], v[52:55] offset:256
	v_cvt_pk_bf16_f32 v44, v56, v57
	v_cvt_pk_bf16_f32 v45, v58, v59
	v_cvt_pk_bf16_f32 v47, v50, v51
	flat_store_dwordx4 v[48:49], v[44:47]
	v_cvt_pk_bf16_f32 v38, v28, v29
	flat_store_dwordx4 v[48:49], v[36:39] offset:256
	v_cvt_pk_bf16_f32 v28, v40, v41
	v_cvt_pk_bf16_f32 v29, v42, v43
	v_cvt_pk_bf16_f32 v31, v34, v35
	flat_store_dwordx4 v[32:33], v[28:31]
	v_cvt_pk_bf16_f32 v22, v12, v13
	flat_store_dwordx4 v[32:33], v[20:23] offset:256
	v_cvt_pk_bf16_f32 v12, v24, v25
	v_cvt_pk_bf16_f32 v13, v26, v27
	v_cvt_pk_bf16_f32 v15, v18, v19
	flat_store_dwordx4 v[16:17], v[12:15]
	v_cvt_pk_bf16_f32 v8, v8, v9
	v_cvt_pk_bf16_f32 v9, v10, v11
	v_cvt_pk_bf16_f32 v10, v4, v5
	v_cvt_pk_bf16_f32 v11, v6, v7
	flat_store_dwordx4 v[16:17], v[8:11] offset:256
	s_cbranch_vccz .LBB0_106
	s_waitcnt vmcnt(0)
	s_cmpk_gt_u32 s18, 0xff
	s_cbranch_scc1 .LBB0_113
	s_barrier

; #define PG8_WAIT_V(n) asm volatile("s_waitcnt vmcnt(" #n ")" ::: "memory")
; #define PG8_WAIT_L(n) asm volatile("s_waitcnt lgkmcnt(" #n ")" ::: "memory")
; #define PG8_BAR __builtin_amdgcn_s_barrier()
; #define PG8_SCHED __builtin_amdgcn_sched_barrier(0)
; template <class Epi, class AddrA, class AddrB>
; __device__ __forceinline__ void gemm_phase(const Sched S, const int lda, const int ldb, const int K, const AddrA addrA,
;                                            const AddrB addrB, const Epi E) {
;     ...
;     const bool has_next = S.next(ui + 1, nxt);
;     const char* nA = has_next ? addrA(nxt) : cA;
;     const char* nB = has_next ? addrB(nxt) : cB;
;     for (int t = 0; t < nt; t += 2) {
;       const bool last = (t == nt - 2);
;       const char* a1 = cA + (size_t)(t + 1) * kstep;
;       const char* a2 = last ? nA : cA + (size_t)(t + 2) * kstep;
;       const char* b2 = last ? nB : cB + (size_t)(t + 2) * kstep;
;       const char* a3 = a2 + kstep;
;       const char* b3 = b2 + kstep;
;       PG8_LDB(B0, 0, 0); PG8_SCHED; PG8_LDA(At, 0, 0); PG8_STAGE(PG8_SA(1, 1), a1 + hstepA, voffA);
;       PG8_WAIT_L(8); PG8_BAR; PG8_WAIT_L(0); PG8_MMA(0, 0, At, B0); PG8_BAR; PG8_SCHED;
;       PG8_LDB(B1, 0, 1); PG8_STAGE(PG8_SB(0, 0), b2, voffB);
;       PG8_BAR; PG8_WAIT_L(0); PG8_MMA(0, 1, At, B1); PG8_BAR;
;       PG8_LDA(At, 0, 1); PG8_STAGE(PG8_SA(0, 0), a2, voffA);
;       PG8_BAR; PG8_WAIT_L(0); PG8_MMA(1, 0, At, B0); PG8_BAR; PG8_SCHED;
;       PG8_STAGE(PG8_SB(0, 1), b2 + hstepB, voffB);
;       PG8_WAIT_V(6); PG8_BAR; PG8_MMA(1, 1, At, B1); PG8_BAR;
.LBB0_484:
	s_ashr_i32 s15, s14, 31
	s_lshl_b64 s[20:21], s[14:15], 20
	s_add_u32 s3, s25, s20
	s_addc_u32 s15, s26, s21
	s_lshl_b32 s17, s16, 8
	s_and_b32 s20, s17, 0xfffffe00
	s_ashr_i32 s21, s20, 31
	s_lshl_b64 s[20:21], s[20:21], 1
	s_add_u32 s20, s3, s20
	s_addc_u32 s21, s15, s21
	s_and_b64 s[22:23], s[10:11], exec
	s_cselect_b32 s3, s21, s7
	s_cselect_b32 s15, s20, s6
	s_ashr_i32 s17, s16, 31
	s_lshl_b64 s[22:23], s[16:17], 18
	s_add_u32 s22, s27, s22
	s_addc_u32 s23, s28, s23
	s_and_b64 s[10:11], s[10:11], exec
	s_cselect_b32 s17, s23, s5
	s_cselect_b32 s40, s22, s4
	s_add_u32 s41, s4, 0x100
	s_addc_u32 s42, s5, 0
	s_add_u32 s4, s6, 0x80080
	s_addc_u32 s5, s7, 0
	s_mov_b32 s43, -2
	s_add_i32 s44, 0, 0x10000
	v_add_u32_e32 v246, s44, v167
	ds_read_b128 v[92:95], v246
	ds_read_b128 v[100:103], v246 offset:1024
	ds_read_b128 v[132:135], v246 offset:2048
	ds_read_b128 v[144:147], v246 offset:3072
	s_add_i32 m0, s30, 0xc000
	ds_read_b128 v[148:151], v169
	ds_read_b128 v[152:155], v169 offset:1024
	ds_read_b128 v[176:179], v169 offset:2048
	ds_read_b128 v[180:183], v169 offset:3072
	ds_read_b128 v[184:187], v169 offset:4096
	ds_read_b128 v[188:191], v169 offset:5120
	ds_read_b128 v[192:195], v169 offset:6144
	ds_read_b128 v[212:215], v169 offset:7168
	global_load_lds_dwordx4 v172, s[4:5]
	s_add_i32 m0, s30, 0xe000
	s_nop 0
	global_load_lds_dwordx4 v170, s[4:5]
	s_waitcnt lgkmcnt(6)
	s_setprio 1
	s_barrier
	v_mfma_f32_16x16x32_bf16 v[140:143], v[92:95], v[148:151], 0
	v_mfma_f32_16x16x32_bf16 v[140:143], v[100:103], v[152:155], v[140:143]
	s_waitcnt lgkmcnt(0)
	v_mfma_f32_16x16x32_bf16 v[128:131], v[92:95], v[176:179], 0
	v_mfma_f32_16x16x32_bf16 v[128:131], v[100:103], v[180:183], v[128:131]
	v_mfma_f32_16x16x32_bf16 v[120:123], v[92:95], v[184:187], 0
	v_mfma_f32_16x16x32_bf16 v[120:123], v[100:103], v[188:191], v[120:123]
	v_mfma_f32_16x16x32_bf16 v[112:115], v[92:95], v[192:195], 0
	v_mfma_f32_16x16x32_bf16 v[112:115], v[100:103], v[212:215], v[112:115]
	v_mfma_f32_16x16x32_bf16 v[136:139], v[132:135], v[148:151], 0
	v_mfma_f32_16x16x32_bf16 v[136:139], v[144:147], v[152:155], v[136:139]
	v_mfma_f32_16x16x32_bf16 v[124:127], v[132:135], v[176:179], 0
	v_mfma_f32_16x16x32_bf16 v[124:127], v[144:147], v[180:183], v[124:127]
	v_mfma_f32_16x16x32_bf16 v[116:119], v[132:135], v[184:187], 0
	v_mfma_f32_16x16x32_bf16 v[116:119], v[144:147], v[188:191], v[116:119]
	v_mfma_f32_16x16x32_bf16 v[108:111], v[132:135], v[192:195], 0
	v_mfma_f32_16x16x32_bf16 v[108:111], v[144:147], v[212:215], v[108:111]
	s_barrier
	s_setprio 0
	s_add_u32 s6, s4, 0xfff80080
	s_addc_u32 s7, s5, -1
	s_cmp_eq_u32 s43, 4
	s_cselect_b32 s11, s3, s7
	s_cselect_b32 s10, s15, s6
	s_cselect_b32 s7, s17, s42
	s_cselect_b32 s6, s40, s41
	s_add_i32 s46, 0, 0x14000
	s_add_i32 s44, s44, s29
	s_add_u32 s98, s6, 0x80
	s_addc_u32 s99, s7, 0
	s_mov_b32 m0, s44
	ds_read_b128 v[216:219], v246 offset:16384
	ds_read_b128 v[220:223], v246 offset:17408
	ds_read_b128 v[224:227], v246 offset:18432
	ds_read_b128 v[228:231], v246 offset:19456
	global_load_lds_dwordx4 v158, s[6:7]
	s_add_i32 m0, s44, 0x2000
	s_nop 0
	global_load_lds_dwordx4 v0, s[6:7]
	s_mov_b32 m0, s30
	s_add_u32 s100, s10, 0x80
	s_addc_u32 s101, s11, 0
	s_waitcnt lgkmcnt(2)
	s_setprio 1
	s_barrier
	v_mfma_f32_16x16x32_bf16 v[64:67], v[216:219], v[148:151], 0
	v_mfma_f32_16x16x32_bf16 v[64:67], v[220:223], v[152:155], v[64:67]
	s_waitcnt lgkmcnt(0)
	v_mfma_f32_16x16x32_bf16 v[56:59], v[216:219], v[176:179], 0
	v_mfma_f32_16x16x32_bf16 v[56:59], v[220:223], v[180:183], v[56:59]
	v_mfma_f32_16x16x32_bf16 v[48:51], v[216:219], v[184:187], 0
	v_mfma_f32_16x16x32_bf16 v[48:51], v[220:223], v[188:191], v[48:51]
	v_mfma_f32_16x16x32_bf16 v[40:43], v[216:219], v[192:195], 0
	v_mfma_f32_16x16x32_bf16 v[40:43], v[220:223], v[212:215], v[40:43]
	v_mfma_f32_16x16x32_bf16 v[60:63], v[224:227], v[148:151], 0
	v_mfma_f32_16x16x32_bf16 v[60:63], v[228:231], v[152:155], v[60:63]
	v_mfma_f32_16x16x32_bf16 v[52:55], v[224:227], v[176:179], 0
	v_mfma_f32_16x16x32_bf16 v[52:55], v[228:231], v[180:183], v[52:55]
	v_mfma_f32_16x16x32_bf16 v[44:47], v[224:227], v[184:187], 0
	v_mfma_f32_16x16x32_bf16 v[44:47], v[228:231], v[188:191], v[44:47]
	v_mfma_f32_16x16x32_bf16 v[36:39], v[224:227], v[192:195], 0
	v_mfma_f32_16x16x32_bf16 v[36:39], v[228:231], v[212:215], v[36:39]
	s_barrier
	s_setprio 0
	ds_read_b128 v[148:151], v169 offset:16384
	ds_read_b128 v[152:155], v169 offset:17408
	ds_read_b128 v[176:179], v169 offset:18432
	ds_read_b128 v[180:183], v169 offset:19456
	ds_read_b128 v[184:187], v169 offset:20480
	ds_read_b128 v[188:191], v169 offset:21504
	ds_read_b128 v[192:195], v169 offset:22528
	ds_read_b128 v[212:215], v169 offset:23552
	global_load_lds_dwordx4 v160, s[10:11]
	s_mov_b32 m0, s31
	s_nop 0
	global_load_lds_dwordx4 v156, s[10:11]
	s_waitcnt lgkmcnt(6)
	s_setprio 1
	s_barrier
	v_mfma_f32_16x16x32_bf16 v[104:107], v[92:95], v[148:151], 0
	v_mfma_f32_16x16x32_bf16 v[104:107], v[100:103], v[152:155], v[104:107]
	s_waitcnt lgkmcnt(0)
	v_mfma_f32_16x16x32_bf16 v[88:91], v[92:95], v[176:179], 0
	v_mfma_f32_16x16x32_bf16 v[88:91], v[100:103], v[180:183], v[88:91]
	v_mfma_f32_16x16x32_bf16 v[80:83], v[92:95], v[184:187], 0
	v_mfma_f32_16x16x32_bf16 v[80:83], v[100:103], v[188:191], v[80:83]
	v_mfma_f32_16x16x32_bf16 v[72:75], v[92:95], v[192:195], 0
	v_mfma_f32_16x16x32_bf16 v[72:75], v[100:103], v[212:215], v[72:75]
	v_mfma_f32_16x16x32_bf16 v[96:99], v[132:135], v[148:151], 0
	v_mfma_f32_16x16x32_bf16 v[96:99], v[144:147], v[152:155], v[96:99]
	v_mfma_f32_16x16x32_bf16 v[84:87], v[132:135], v[176:179], 0
	v_mfma_f32_16x16x32_bf16 v[84:87], v[144:147], v[180:183], v[84:87]
	v_mfma_f32_16x16x32_bf16 v[76:79], v[132:135], v[184:187], 0
	v_mfma_f32_16x16x32_bf16 v[76:79], v[144:147], v[188:191], v[76:79]
	v_mfma_f32_16x16x32_bf16 v[68:71], v[132:135], v[192:195], 0
	v_mfma_f32_16x16x32_bf16 v[68:71], v[144:147], v[212:215], v[68:71]
	s_barrier
; #define PG8_WAIT_V(n) asm volatile("s_waitcnt vmcnt(" #n ")" ::: "memory")
; #define PG8_WAIT_L(n) asm volatile("s_waitcnt lgkmcnt(" #n ")" ::: "memory")
; #define PG8_BAR __builtin_amdgcn_s_barrier()
; #define PG8_SCHED __builtin_amdgcn_sched_barrier(0)
; template <class Epi, class AddrA, class AddrB>
; __device__ __forceinline__ void gemm_phase(const Sched S, const int lda, const int ldb, const int K, const AddrA addrA,
;                                            const AddrB addrB, const Epi E) {
;     ...
;       PG8_BAR; PG8_WAIT_L(0); PG8_MMA(1, 0, At, B0); PG8_BAR; PG8_SCHED;
;       PG8_STAGE(PG8_SB(0, 1), b2 + hstepB, voffB);
;       PG8_WAIT_V(6); PG8_BAR; PG8_MMA(1, 1, At, B1); PG8_BAR;
;       PG8_LDB(B0, 1, 0); PG8_SCHED; PG8_LDA(At, 1, 0); PG8_STAGE(PG8_SA(0, 1), a2 + hstepA, voffA);
;       PG8_WAIT_L(8); PG8_BAR; PG8_WAIT_L(0); PG8_MMA(0, 0, At, B0); PG8_BAR; PG8_SCHED;
;       PG8_LDB(B1, 1, 1); PG8_STAGE(PG8_SB(1, 0), b3, voffB);
;       PG8_BAR; PG8_WAIT_L(0); PG8_MMA(0, 1, At, B1); PG8_BAR;
;       PG8_LDA(At, 1, 1); PG8_STAGE(PG8_SA(1, 0), a3, voffA);
;       PG8_BAR; PG8_WAIT_L(0); PG8_MMA(1, 0, At, B0); PG8_BAR; PG8_SCHED;
	s_setprio 0
	s_add_u32 s44, s6, 0x20000
	s_addc_u32 s45, s7, 0
	s_add_i32 s46, s46, s29
	s_mov_b32 m0, s46
	s_nop 0
	global_load_lds_dwordx4 v158, s[44:45]
	s_add_i32 m0, s46, 0x2000
	s_nop 0
	global_load_lds_dwordx4 v0, s[44:45]
	s_add_i32 s44, 0, 0x18000
	s_waitcnt vmcnt(6)
	s_setprio 1
	s_barrier
	v_mfma_f32_16x16x32_bf16 v[32:35], v[216:219], v[148:151], 0
	v_mfma_f32_16x16x32_bf16 v[32:35], v[220:223], v[152:155], v[32:35]
	v_mfma_f32_16x16x32_bf16 v[24:27], v[216:219], v[176:179], 0
	v_mfma_f32_16x16x32_bf16 v[24:27], v[220:223], v[180:183], v[24:27]
	v_mfma_f32_16x16x32_bf16 v[16:19], v[216:219], v[184:187], 0
	v_mfma_f32_16x16x32_bf16 v[16:19], v[220:223], v[188:191], v[16:19]
	v_mfma_f32_16x16x32_bf16 v[8:11], v[216:219], v[192:195], 0
	v_mfma_f32_16x16x32_bf16 v[8:11], v[220:223], v[212:215], v[8:11]
	v_mfma_f32_16x16x32_bf16 v[28:31], v[224:227], v[148:151], 0
	v_mfma_f32_16x16x32_bf16 v[28:31], v[228:231], v[152:155], v[28:31]
	v_mfma_f32_16x16x32_bf16 v[20:23], v[224:227], v[176:179], 0
	v_mfma_f32_16x16x32_bf16 v[20:23], v[228:231], v[180:183], v[20:23]
	v_mfma_f32_16x16x32_bf16 v[12:15], v[224:227], v[184:187], 0
	v_mfma_f32_16x16x32_bf16 v[12:15], v[228:231], v[188:191], v[12:15]
	v_mfma_f32_16x16x32_bf16 v[4:7], v[224:227], v[192:195], 0
	v_mfma_f32_16x16x32_bf16 v[4:7], v[228:231], v[212:215], v[4:7]
	s_barrier
	s_setprio 0
	ds_read_b128 v[92:95], v246 offset:32768
	ds_read_b128 v[100:103], v246 offset:33792
	ds_read_b128 v[132:135], v246 offset:34816
	ds_read_b128 v[144:147], v246 offset:35840
	s_add_u32 s10, s10, 0x80000
	s_addc_u32 s11, s11, 0
	s_mov_b32 m0, s34
	ds_read_b128 v[148:151], v169 offset:32768
	ds_read_b128 v[152:155], v169 offset:33792
	ds_read_b128 v[176:179], v169 offset:34816
	ds_read_b128 v[180:183], v169 offset:35840
	ds_read_b128 v[184:187], v169 offset:36864
	ds_read_b128 v[188:191], v169 offset:37888
	ds_read_b128 v[192:195], v169 offset:38912
	ds_read_b128 v[212:215], v169 offset:39936
	global_load_lds_dwordx4 v160, s[10:11]
	s_mov_b32 m0, s35
	s_nop 0
	global_load_lds_dwordx4 v156, s[10:11]
	s_waitcnt lgkmcnt(6)
	s_setprio 1
	s_barrier
	v_mfma_f32_16x16x32_bf16 v[140:143], v[92:95], v[148:151], v[140:143]
	v_mfma_f32_16x16x32_bf16 v[140:143], v[100:103], v[152:155], v[140:143]
	s_waitcnt lgkmcnt(0)
	v_mfma_f32_16x16x32_bf16 v[128:131], v[92:95], v[176:179], v[128:131]
	v_mfma_f32_16x16x32_bf16 v[128:131], v[100:103], v[180:183], v[128:131]
	v_mfma_f32_16x16x32_bf16 v[120:123], v[92:95], v[184:187], v[120:123]
	v_mfma_f32_16x16x32_bf16 v[120:123], v[100:103], v[188:191], v[120:123]
	v_mfma_f32_16x16x32_bf16 v[112:115], v[92:95], v[192:195], v[112:115]
	v_mfma_f32_16x16x32_bf16 v[112:115], v[100:103], v[212:215], v[112:115]
	v_mfma_f32_16x16x32_bf16 v[136:139], v[132:135], v[148:151], v[136:139]
	v_mfma_f32_16x16x32_bf16 v[136:139], v[144:147], v[152:155], v[136:139]
	v_mfma_f32_16x16x32_bf16 v[124:127], v[132:135], v[176:179], v[124:127]
	v_mfma_f32_16x16x32_bf16 v[124:127], v[144:147], v[180:183], v[124:127]
	v_mfma_f32_16x16x32_bf16 v[116:119], v[132:135], v[184:187], v[116:119]
	v_mfma_f32_16x16x32_bf16 v[116:119], v[144:147], v[188:191], v[116:119]
	v_mfma_f32_16x16x32_bf16 v[108:111], v[132:135], v[192:195], v[108:111]
	v_mfma_f32_16x16x32_bf16 v[108:111], v[144:147], v[212:215], v[108:111]
	s_barrier
	s_setprio 0
	s_add_i32 s10, 0, 0x1c000
	s_add_i32 s11, s44, s29
	s_mov_b32 m0, s11
	ds_read_b128 v[216:219], v246 offset:49152
	ds_read_b128 v[220:223], v246 offset:50176
	ds_read_b128 v[224:227], v246 offset:51200
	ds_read_b128 v[228:231], v246 offset:52224
	global_load_lds_dwordx4 v158, s[98:99]
	s_add_i32 m0, s11, 0x2000
	s_nop 0
	global_load_lds_dwordx4 v0, s[98:99]
	s_mov_b32 m0, s37
	s_waitcnt lgkmcnt(2)
	s_setprio 1
	s_barrier
	v_mfma_f32_16x16x32_bf16 v[64:67], v[216:219], v[148:151], v[64:67]
	v_mfma_f32_16x16x32_bf16 v[64:67], v[220:223], v[152:155], v[64:67]
	s_waitcnt lgkmcnt(0)
	v_mfma_f32_16x16x32_bf16 v[56:59], v[216:219], v[176:179], v[56:59]
	v_mfma_f32_16x16x32_bf16 v[56:59], v[220:223], v[180:183], v[56:59]
	v_mfma_f32_16x16x32_bf16 v[48:51], v[216:219], v[184:187], v[48:51]
	v_mfma_f32_16x16x32_bf16 v[48:51], v[220:223], v[188:191], v[48:51]
	v_mfma_f32_16x16x32_bf16 v[40:43], v[216:219], v[192:195], v[40:43]
	v_mfma_f32_16x16x32_bf16 v[40:43], v[220:223], v[212:215], v[40:43]
	v_mfma_f32_16x16x32_bf16 v[60:63], v[224:227], v[148:151], v[60:63]
	v_mfma_f32_16x16x32_bf16 v[60:63], v[228:231], v[152:155], v[60:63]
	v_mfma_f32_16x16x32_bf16 v[52:55], v[224:227], v[176:179], v[52:55]
	v_mfma_f32_16x16x32_bf16 v[52:55], v[228:231], v[180:183], v[52:55]
	v_mfma_f32_16x16x32_bf16 v[44:47], v[224:227], v[184:187], v[44:47]
	v_mfma_f32_16x16x32_bf16 v[44:47], v[228:231], v[188:191], v[44:47]
	v_mfma_f32_16x16x32_bf16 v[36:39], v[224:227], v[192:195], v[36:39]
	v_mfma_f32_16x16x32_bf16 v[36:39], v[228:231], v[212:215], v[36:39]
	s_barrier
	s_setprio 0
	ds_read_b128 v[148:151], v169 offset:49152
	ds_read_b128 v[152:155], v169 offset:50176
	ds_read_b128 v[176:179], v169 offset:51200
	ds_read_b128 v[180:183], v169 offset:52224
	ds_read_b128 v[184:187], v169 offset:53248
	ds_read_b128 v[188:191], v169 offset:54272
	ds_read_b128 v[192:195], v169 offset:55296
	ds_read_b128 v[212:215], v169 offset:56320
	global_load_lds_dwordx4 v160, s[100:101]
	s_mov_b32 m0, s38
	s_nop 0
	global_load_lds_dwordx4 v156, s[100:101]
	s_waitcnt lgkmcnt(6)
	s_setprio 1
	s_barrier
; #define PG8_WAIT_V(n) asm volatile("s_waitcnt vmcnt(" #n ")" ::: "memory")
; #define PG8_WAIT_L(n) asm volatile("s_waitcnt lgkmcnt(" #n ")" ::: "memory")
; #define PG8_BAR __builtin_amdgcn_s_barrier()
; #define PG8_SCHED __builtin_amdgcn_sched_barrier(0)
; template <class Epi, class AddrA, class AddrB>
; __device__ __forceinline__ void gemm_phase(const Sched S, const int lda, const int ldb, const int K, const AddrA addrA,
;                                            const AddrB addrB, const Epi E) {
;     ...
;       PG8_LDB(B0, 0, 0); PG8_SCHED; PG8_LDA(At, 0, 0); PG8_STAGE(PG8_SA(1, 1), a1 + hstepA, voffA);
;       PG8_WAIT_L(8); PG8_BAR; PG8_WAIT_L(0); PG8_MMA(0, 0, At, B0); PG8_BAR; PG8_SCHED;
;       PG8_LDB(B1, 0, 1); PG8_STAGE(PG8_SB(0, 0), b2, voffB);
;       PG8_BAR; PG8_WAIT_L(0); PG8_MMA(0, 1, At, B1); PG8_BAR;
;       PG8_LDA(At, 0, 1); PG8_STAGE(PG8_SA(0, 0), a2, voffA);
;       PG8_BAR; PG8_WAIT_L(0); PG8_MMA(1, 0, At, B0); PG8_BAR; PG8_SCHED;
;       PG8_STAGE(PG8_SB(0, 1), b2 + hstepB, voffB);
;       PG8_WAIT_V(6); PG8_BAR; PG8_MMA(1, 1, At, B1); PG8_BAR;
;       PG8_LDB(B0, 1, 0); PG8_SCHED; PG8_LDA(At, 1, 0); PG8_STAGE(PG8_SA(0, 1), a2 + hstepA, voffA);
;       PG8_WAIT_L(8); PG8_BAR; PG8_WAIT_L(0); PG8_MMA(0, 0, At, B0); PG8_BAR; PG8_SCHED;
;       PG8_LDB(B1, 1, 1); PG8_STAGE(PG8_SB(1, 0), b3, voffB);
;       PG8_BAR; PG8_WAIT_L(0); PG8_MMA(0, 1, At, B1); PG8_BAR;
;       PG8_LDA(At, 1, 1); PG8_STAGE(PG8_SA(1, 0), a3, voffA);
;       PG8_BAR; PG8_WAIT_L(0); PG8_MMA(1, 0, At, B0); PG8_BAR; PG8_SCHED;
;       PG8_STAGE(PG8_SB(1, 1), b3 + hstepB, voffB);
;       PG8_WAIT_V(6); PG8_BAR; PG8_MMA(1, 1, At, B1); PG8_BAR;
	v_mfma_f32_16x16x32_bf16 v[104:107], v[92:95], v[148:151], v[104:107]
	v_mfma_f32_16x16x32_bf16 v[104:107], v[100:103], v[152:155], v[104:107]
	s_waitcnt lgkmcnt(0)
	v_mfma_f32_16x16x32_bf16 v[88:91], v[92:95], v[176:179], v[88:91]
	v_mfma_f32_16x16x32_bf16 v[88:91], v[100:103], v[180:183], v[88:91]
	v_mfma_f32_16x16x32_bf16 v[80:83], v[92:95], v[184:187], v[80:83]
	v_mfma_f32_16x16x32_bf16 v[80:83], v[100:103], v[188:191], v[80:83]
	v_mfma_f32_16x16x32_bf16 v[72:75], v[92:95], v[192:195], v[72:75]
	v_mfma_f32_16x16x32_bf16 v[72:75], v[100:103], v[212:215], v[72:75]
	v_mfma_f32_16x16x32_bf16 v[96:99], v[132:135], v[148:151], v[96:99]
	v_mfma_f32_16x16x32_bf16 v[96:99], v[144:147], v[152:155], v[96:99]
	v_mfma_f32_16x16x32_bf16 v[84:87], v[132:135], v[176:179], v[84:87]
	v_mfma_f32_16x16x32_bf16 v[84:87], v[144:147], v[180:183], v[84:87]
	v_mfma_f32_16x16x32_bf16 v[76:79], v[132:135], v[184:187], v[76:79]
	v_mfma_f32_16x16x32_bf16 v[76:79], v[144:147], v[188:191], v[76:79]
	v_mfma_f32_16x16x32_bf16 v[68:71], v[132:135], v[192:195], v[68:71]
	v_mfma_f32_16x16x32_bf16 v[68:71], v[144:147], v[212:215], v[68:71]
	s_barrier
	s_setprio 0
	s_add_u32 s6, s6, 0x20080
	s_addc_u32 s7, s7, 0
	s_add_i32 s10, s10, s29
	s_mov_b32 m0, s10
	s_nop 0
	global_load_lds_dwordx4 v158, s[6:7]
	s_add_i32 m0, s10, 0x2000
	s_nop 0
	global_load_lds_dwordx4 v0, s[6:7]
	s_add_i32 s43, s43, 2
	s_add_u32 s41, s41, 0x100
	s_addc_u32 s42, s42, 0
	s_add_u32 s4, s4, 0x100
	s_addc_u32 s5, s5, 0
	s_waitcnt vmcnt(6)
	s_setprio 1
	s_barrier
	v_mfma_f32_16x16x32_bf16 v[32:35], v[216:219], v[148:151], v[32:35]
	v_mfma_f32_16x16x32_bf16 v[32:35], v[220:223], v[152:155], v[32:35]
	v_mfma_f32_16x16x32_bf16 v[24:27], v[216:219], v[176:179], v[24:27]
	v_mfma_f32_16x16x32_bf16 v[24:27], v[220:223], v[180:183], v[24:27]
	v_mfma_f32_16x16x32_bf16 v[16:19], v[216:219], v[184:187], v[16:19]
	v_mfma_f32_16x16x32_bf16 v[16:19], v[220:223], v[188:191], v[16:19]
	v_mfma_f32_16x16x32_bf16 v[8:11], v[216:219], v[192:195], v[8:11]
	v_mfma_f32_16x16x32_bf16 v[8:11], v[220:223], v[212:215], v[8:11]
	v_mfma_f32_16x16x32_bf16 v[28:31], v[224:227], v[148:151], v[28:31]
	v_mfma_f32_16x16x32_bf16 v[28:31], v[228:231], v[152:155], v[28:31]
	v_mfma_f32_16x16x32_bf16 v[20:23], v[224:227], v[176:179], v[20:23]
	v_mfma_f32_16x16x32_bf16 v[20:23], v[228:231], v[180:183], v[20:23]
	v_mfma_f32_16x16x32_bf16 v[12:15], v[224:227], v[184:187], v[12:15]
	v_mfma_f32_16x16x32_bf16 v[12:15], v[228:231], v[188:191], v[12:15]
	v_mfma_f32_16x16x32_bf16 v[4:7], v[224:227], v[192:195], v[4:7]
	v_mfma_f32_16x16x32_bf16 v[4:7], v[228:231], v[212:215], v[4:7]
	s_barrier
	s_setprio 0
	s_cmp_gt_u32 s43, 5
.LBB0_485:
	s_add_i32 s44, 0, 0x10000
	v_add_u32_e32 v246, s44, v167
	ds_read_b128 v[92:95], v246
	ds_read_b128 v[100:103], v246 offset:1024
	ds_read_b128 v[132:135], v246 offset:2048
	ds_read_b128 v[144:147], v246 offset:3072
	s_add_i32 m0, s30, 0xc000
	ds_read_b128 v[148:151], v169
	ds_read_b128 v[152:155], v169 offset:1024
	ds_read_b128 v[176:179], v169 offset:2048
	ds_read_b128 v[180:183], v169 offset:3072
	ds_read_b128 v[184:187], v169 offset:4096
	ds_read_b128 v[188:191], v169 offset:5120
	ds_read_b128 v[192:195], v169 offset:6144
	ds_read_b128 v[212:215], v169 offset:7168
	global_load_lds_dwordx4 v172, s[4:5]
	s_add_i32 m0, s30, 0xe000
	s_nop 0
	global_load_lds_dwordx4 v170, s[4:5]
	s_waitcnt lgkmcnt(6)
	s_setprio 1
	s_barrier
	v_mfma_f32_16x16x32_bf16 v[140:143], v[92:95], v[148:151], v[140:143]
	v_mfma_f32_16x16x32_bf16 v[140:143], v[100:103], v[152:155], v[140:143]
	s_waitcnt lgkmcnt(0)
	v_mfma_f32_16x16x32_bf16 v[128:131], v[92:95], v[176:179], v[128:131]
	v_mfma_f32_16x16x32_bf16 v[128:131], v[100:103], v[180:183], v[128:131]
	v_mfma_f32_16x16x32_bf16 v[120:123], v[92:95], v[184:187], v[120:123]
	v_mfma_f32_16x16x32_bf16 v[120:123], v[100:103], v[188:191], v[120:123]
	v_mfma_f32_16x16x32_bf16 v[112:115], v[92:95], v[192:195], v[112:115]
	v_mfma_f32_16x16x32_bf16 v[112:115], v[100:103], v[212:215], v[112:115]
	v_mfma_f32_16x16x32_bf16 v[136:139], v[132:135], v[148:151], v[136:139]
	v_mfma_f32_16x16x32_bf16 v[136:139], v[144:147], v[152:155], v[136:139]
	v_mfma_f32_16x16x32_bf16 v[124:127], v[132:135], v[176:179], v[124:127]
	v_mfma_f32_16x16x32_bf16 v[124:127], v[144:147], v[180:183], v[124:127]
	v_mfma_f32_16x16x32_bf16 v[116:119], v[132:135], v[184:187], v[116:119]
	v_mfma_f32_16x16x32_bf16 v[116:119], v[144:147], v[188:191], v[116:119]
	v_mfma_f32_16x16x32_bf16 v[108:111], v[132:135], v[192:195], v[108:111]
	v_mfma_f32_16x16x32_bf16 v[108:111], v[144:147], v[212:215], v[108:111]
	s_barrier
	s_setprio 0
	s_add_u32 s6, s4, 0xfff80080
	s_addc_u32 s7, s5, -1
	s_cmp_eq_u32 s43, 4
	s_cselect_b32 s11, s3, s7
	s_cselect_b32 s10, s15, s6
	s_cselect_b32 s7, s17, s42
	s_cselect_b32 s6, s40, s41
	s_add_i32 s46, 0, 0x14000
	s_add_i32 s44, s44, s29
	s_add_u32 s98, s6, 0x80
	s_addc_u32 s99, s7, 0
	s_mov_b32 m0, s44
	ds_read_b128 v[216:219], v246 offset:16384
	ds_read_b128 v[220:223], v246 offset:17408
	ds_read_b128 v[224:227], v246 offset:18432
	ds_read_b128 v[228:231], v246 offset:19456
	global_load_lds_dwordx4 v158, s[6:7]
	s_add_i32 m0, s44, 0x2000
	s_nop 0
	global_load_lds_dwordx4 v0, s[6:7]
	s_mov_b32 m0, s30
	s_add_u32 s100, s10, 0x80
	s_addc_u32 s101, s11, 0
	s_waitcnt lgkmcnt(2)
	s_setprio 1
	s_barrier
; #define PG8_WAIT_V(n) asm volatile("s_waitcnt vmcnt(" #n ")" ::: "memory")
; #define PG8_WAIT_L(n) asm volatile("s_waitcnt lgkmcnt(" #n ")" ::: "memory")
; #define PG8_BAR __builtin_amdgcn_s_barrier()
; #define PG8_SCHED __builtin_amdgcn_sched_barrier(0)
; template <class Epi, class AddrA, class AddrB>
; __device__ __forceinline__ void gemm_phase(const Sched S, const int lda, const int ldb, const int K, const AddrA addrA,
;                                            const AddrB addrB, const Epi E) {
;     ...
;       PG8_LDB(B0, 0, 0); PG8_SCHED; PG8_LDA(At, 0, 0); PG8_STAGE(PG8_SA(1, 1), a1 + hstepA, voffA);
;       PG8_WAIT_L(8); PG8_BAR; PG8_WAIT_L(0); PG8_MMA(0, 0, At, B0); PG8_BAR; PG8_SCHED;
;       PG8_LDB(B1, 0, 1); PG8_STAGE(PG8_SB(0, 0), b2, voffB);
;       PG8_BAR; PG8_WAIT_L(0); PG8_MMA(0, 1, At, B1); PG8_BAR;
;       PG8_LDA(At, 0, 1); PG8_STAGE(PG8_SA(0, 0), a2, voffA);
;       PG8_BAR; PG8_WAIT_L(0); PG8_MMA(1, 0, At, B0); PG8_BAR; PG8_SCHED;
;       PG8_STAGE(PG8_SB(0, 1), b2 + hstepB, voffB);
;       PG8_WAIT_V(6); PG8_BAR; PG8_MMA(1, 1, At, B1); PG8_BAR;
;       PG8_LDB(B0, 1, 0); PG8_SCHED; PG8_LDA(At, 1, 0); PG8_STAGE(PG8_SA(0, 1), a2 + hstepA, voffA);
;       PG8_WAIT_L(8); PG8_BAR; PG8_WAIT_L(0); PG8_MMA(0, 0, At, B0); PG8_BAR; PG8_SCHED;
;       PG8_LDB(B1, 1, 1); PG8_STAGE(PG8_SB(1, 0), b3, voffB);
;       PG8_BAR; PG8_WAIT_L(0); PG8_MMA(0, 1, At, B1); PG8_BAR;
;       PG8_LDA(At, 1, 1); PG8_STAGE(PG8_SA(1, 0), a3, voffA);
;       PG8_BAR; PG8_WAIT_L(0); PG8_MMA(1, 0, At, B0); PG8_BAR; PG8_SCHED;
;       PG8_STAGE(PG8_SB(1, 1), b3 + hstepB, voffB);
;       PG8_WAIT_V(6); PG8_BAR; PG8_MMA(1, 1, At, B1); PG8_BAR;
	v_mfma_f32_16x16x32_bf16 v[64:67], v[216:219], v[148:151], v[64:67]
	v_mfma_f32_16x16x32_bf16 v[64:67], v[220:223], v[152:155], v[64:67]
	s_waitcnt lgkmcnt(0)
	v_mfma_f32_16x16x32_bf16 v[56:59], v[216:219], v[176:179], v[56:59]
	v_mfma_f32_16x16x32_bf16 v[56:59], v[220:223], v[180:183], v[56:59]
	v_mfma_f32_16x16x32_bf16 v[48:51], v[216:219], v[184:187], v[48:51]
	v_mfma_f32_16x16x32_bf16 v[48:51], v[220:223], v[188:191], v[48:51]
	v_mfma_f32_16x16x32_bf16 v[40:43], v[216:219], v[192:195], v[40:43]
	v_mfma_f32_16x16x32_bf16 v[40:43], v[220:223], v[212:215], v[40:43]
	v_mfma_f32_16x16x32_bf16 v[60:63], v[224:227], v[148:151], v[60:63]
	v_mfma_f32_16x16x32_bf16 v[60:63], v[228:231], v[152:155], v[60:63]
	v_mfma_f32_16x16x32_bf16 v[52:55], v[224:227], v[176:179], v[52:55]
	v_mfma_f32_16x16x32_bf16 v[52:55], v[228:231], v[180:183], v[52:55]
	v_mfma_f32_16x16x32_bf16 v[44:47], v[224:227], v[184:187], v[44:47]
	v_mfma_f32_16x16x32_bf16 v[44:47], v[228:231], v[188:191], v[44:47]
	v_mfma_f32_16x16x32_bf16 v[36:39], v[224:227], v[192:195], v[36:39]
	v_mfma_f32_16x16x32_bf16 v[36:39], v[228:231], v[212:215], v[36:39]
	s_barrier
	s_setprio 0
	ds_read_b128 v[148:151], v169 offset:16384
	ds_read_b128 v[152:155], v169 offset:17408
	ds_read_b128 v[176:179], v169 offset:18432
	ds_read_b128 v[180:183], v169 offset:19456
	ds_read_b128 v[184:187], v169 offset:20480
	ds_read_b128 v[188:191], v169 offset:21504
	ds_read_b128 v[192:195], v169 offset:22528
	ds_read_b128 v[212:215], v169 offset:23552
	global_load_lds_dwordx4 v160, s[10:11]
	s_mov_b32 m0, s31
	s_nop 0
	global_load_lds_dwordx4 v156, s[10:11]
	s_waitcnt lgkmcnt(6)
	s_setprio 1
	s_barrier
	v_mfma_f32_16x16x32_bf16 v[104:107], v[92:95], v[148:151], v[104:107]
	v_mfma_f32_16x16x32_bf16 v[104:107], v[100:103], v[152:155], v[104:107]
	s_waitcnt lgkmcnt(0)
	v_mfma_f32_16x16x32_bf16 v[88:91], v[92:95], v[176:179], v[88:91]
	v_mfma_f32_16x16x32_bf16 v[88:91], v[100:103], v[180:183], v[88:91]
	v_mfma_f32_16x16x32_bf16 v[80:83], v[92:95], v[184:187], v[80:83]
	v_mfma_f32_16x16x32_bf16 v[80:83], v[100:103], v[188:191], v[80:83]
	v_mfma_f32_16x16x32_bf16 v[72:75], v[92:95], v[192:195], v[72:75]
	v_mfma_f32_16x16x32_bf16 v[72:75], v[100:103], v[212:215], v[72:75]
	v_mfma_f32_16x16x32_bf16 v[96:99], v[132:135], v[148:151], v[96:99]
	v_mfma_f32_16x16x32_bf16 v[96:99], v[144:147], v[152:155], v[96:99]
	v_mfma_f32_16x16x32_bf16 v[84:87], v[132:135], v[176:179], v[84:87]
	v_mfma_f32_16x16x32_bf16 v[84:87], v[144:147], v[180:183], v[84:87]
	v_mfma_f32_16x16x32_bf16 v[76:79], v[132:135], v[184:187], v[76:79]
	v_mfma_f32_16x16x32_bf16 v[76:79], v[144:147], v[188:191], v[76:79]
	v_mfma_f32_16x16x32_bf16 v[68:71], v[132:135], v[192:195], v[68:71]
	v_mfma_f32_16x16x32_bf16 v[68:71], v[144:147], v[212:215], v[68:71]
	s_barrier
	s_setprio 0
	s_add_u32 s44, s6, 0x20000
	s_addc_u32 s45, s7, 0
	s_add_i32 s46, s46, s29
	s_mov_b32 m0, s46
	s_nop 0
	global_load_lds_dwordx4 v158, s[44:45]
	s_add_i32 m0, s46, 0x2000
	s_nop 0
	global_load_lds_dwordx4 v0, s[44:45]
	s_add_i32 s44, 0, 0x18000
	s_waitcnt vmcnt(6)
	s_setprio 1
	s_barrier
	v_mfma_f32_16x16x32_bf16 v[32:35], v[216:219], v[148:151], v[32:35]
	v_mfma_f32_16x16x32_bf16 v[32:35], v[220:223], v[152:155], v[32:35]
	v_mfma_f32_16x16x32_bf16 v[24:27], v[216:219], v[176:179], v[24:27]
	v_mfma_f32_16x16x32_bf16 v[24:27], v[220:223], v[180:183], v[24:27]
	v_mfma_f32_16x16x32_bf16 v[16:19], v[216:219], v[184:187], v[16:19]
	v_mfma_f32_16x16x32_bf16 v[16:19], v[220:223], v[188:191], v[16:19]
	v_mfma_f32_16x16x32_bf16 v[8:11], v[216:219], v[192:195], v[8:11]
	v_mfma_f32_16x16x32_bf16 v[8:11], v[220:223], v[212:215], v[8:11]
	v_mfma_f32_16x16x32_bf16 v[28:31], v[224:227], v[148:151], v[28:31]
	v_mfma_f32_16x16x32_bf16 v[28:31], v[228:231], v[152:155], v[28:31]
	v_mfma_f32_16x16x32_bf16 v[20:23], v[224:227], v[176:179], v[20:23]
	v_mfma_f32_16x16x32_bf16 v[20:23], v[228:231], v[180:183], v[20:23]
	v_mfma_f32_16x16x32_bf16 v[12:15], v[224:227], v[184:187], v[12:15]
	v_mfma_f32_16x16x32_bf16 v[12:15], v[228:231], v[188:191], v[12:15]
	v_mfma_f32_16x16x32_bf16 v[4:7], v[224:227], v[192:195], v[4:7]
	v_mfma_f32_16x16x32_bf16 v[4:7], v[228:231], v[212:215], v[4:7]
	s_barrier
	s_setprio 0
	ds_read_b128 v[92:95], v246 offset:32768
	ds_read_b128 v[100:103], v246 offset:33792
	ds_read_b128 v[132:135], v246 offset:34816
	ds_read_b128 v[144:147], v246 offset:35840
	s_add_u32 s10, s10, 0x80000
	s_addc_u32 s11, s11, 0
	s_mov_b32 m0, s34
	ds_read_b128 v[148:151], v169 offset:32768
	ds_read_b128 v[152:155], v169 offset:33792
	ds_read_b128 v[176:179], v169 offset:34816
	ds_read_b128 v[180:183], v169 offset:35840
	ds_read_b128 v[184:187], v169 offset:36864
	ds_read_b128 v[188:191], v169 offset:37888
	ds_read_b128 v[192:195], v169 offset:38912
	ds_read_b128 v[212:215], v169 offset:39936
	global_load_lds_dwordx4 v160, s[10:11]
	s_mov_b32 m0, s35
	s_nop 0
	global_load_lds_dwordx4 v156, s[10:11]
	s_waitcnt lgkmcnt(6)
	s_setprio 1
	s_barrier
	v_mfma_f32_16x16x32_bf16 v[140:143], v[92:95], v[148:151], v[140:143]
	v_mfma_f32_16x16x32_bf16 v[140:143], v[100:103], v[152:155], v[140:143]
	s_waitcnt lgkmcnt(0)
	v_mfma_f32_16x16x32_bf16 v[128:131], v[92:95], v[176:179], v[128:131]
	v_mfma_f32_16x16x32_bf16 v[128:131], v[100:103], v[180:183], v[128:131]
	v_mfma_f32_16x16x32_bf16 v[120:123], v[92:95], v[184:187], v[120:123]
	v_mfma_f32_16x16x32_bf16 v[120:123], v[100:103], v[188:191], v[120:123]
	v_mfma_f32_16x16x32_bf16 v[112:115], v[92:95], v[192:195], v[112:115]
	v_mfma_f32_16x16x32_bf16 v[112:115], v[100:103], v[212:215], v[112:115]
	v_mfma_f32_16x16x32_bf16 v[136:139], v[132:135], v[148:151], v[136:139]
	v_mfma_f32_16x16x32_bf16 v[136:139], v[144:147], v[152:155], v[136:139]
	v_mfma_f32_16x16x32_bf16 v[124:127], v[132:135], v[176:179], v[124:127]
	v_mfma_f32_16x16x32_bf16 v[124:127], v[144:147], v[180:183], v[124:127]
	v_mfma_f32_16x16x32_bf16 v[116:119], v[132:135], v[184:187], v[116:119]
	v_mfma_f32_16x16x32_bf16 v[116:119], v[144:147], v[188:191], v[116:119]
	v_mfma_f32_16x16x32_bf16 v[108:111], v[132:135], v[192:195], v[108:111]
	v_mfma_f32_16x16x32_bf16 v[108:111], v[144:147], v[212:215], v[108:111]
	s_barrier
; #define PG8_WAIT_V(n) asm volatile("s_waitcnt vmcnt(" #n ")" ::: "memory")
; #define PG8_WAIT_L(n) asm volatile("s_waitcnt lgkmcnt(" #n ")" ::: "memory")
; #define PG8_BAR __builtin_amdgcn_s_barrier()
; #define PG8_SCHED __builtin_amdgcn_sched_barrier(0)
; template <class Epi, class AddrA, class AddrB>
; __device__ __forceinline__ void gemm_phase(const Sched S, const int lda, const int ldb, const int K, const AddrA addrA,
;                                            const AddrB addrB, const Epi E) {
;     ...
;       PG8_STAGE(PG8_SB(0, 1), b2 + hstepB, voffB);
;       PG8_WAIT_V(6); PG8_BAR; PG8_MMA(1, 1, At, B1); PG8_BAR;
;       PG8_LDB(B0, 1, 0); PG8_SCHED; PG8_LDA(At, 1, 0); PG8_STAGE(PG8_SA(0, 1), a2 + hstepA, voffA);
;       PG8_WAIT_L(8); PG8_BAR; PG8_WAIT_L(0); PG8_MMA(0, 0, At, B0); PG8_BAR; PG8_SCHED;
;       PG8_LDB(B1, 1, 1); PG8_STAGE(PG8_SB(1, 0), b3, voffB);
;       PG8_BAR; PG8_WAIT_L(0); PG8_MMA(0, 1, At, B1); PG8_BAR;
;       PG8_LDA(At, 1, 1); PG8_STAGE(PG8_SA(1, 0), a3, voffA);
;       PG8_BAR; PG8_WAIT_L(0); PG8_MMA(1, 0, At, B0); PG8_BAR; PG8_SCHED;
;       PG8_STAGE(PG8_SB(1, 1), b3 + hstepB, voffB);
;       PG8_WAIT_V(6); PG8_BAR; PG8_MMA(1, 1, At, B1); PG8_BAR;
	s_setprio 0
	s_add_i32 s10, 0, 0x1c000
	s_add_i32 s11, s44, s29
	s_mov_b32 m0, s11
	ds_read_b128 v[216:219], v246 offset:49152
	ds_read_b128 v[220:223], v246 offset:50176
	ds_read_b128 v[224:227], v246 offset:51200
	ds_read_b128 v[228:231], v246 offset:52224
	global_load_lds_dwordx4 v158, s[98:99]
	s_add_i32 m0, s11, 0x2000
	s_nop 0
	global_load_lds_dwordx4 v0, s[98:99]
	s_mov_b32 m0, s37
	s_waitcnt lgkmcnt(2)
	s_setprio 1
	s_barrier
	v_mfma_f32_16x16x32_bf16 v[64:67], v[216:219], v[148:151], v[64:67]
	v_mfma_f32_16x16x32_bf16 v[64:67], v[220:223], v[152:155], v[64:67]
	s_waitcnt lgkmcnt(0)
	v_mfma_f32_16x16x32_bf16 v[56:59], v[216:219], v[176:179], v[56:59]
	v_mfma_f32_16x16x32_bf16 v[56:59], v[220:223], v[180:183], v[56:59]
	v_mfma_f32_16x16x32_bf16 v[48:51], v[216:219], v[184:187], v[48:51]
	v_mfma_f32_16x16x32_bf16 v[48:51], v[220:223], v[188:191], v[48:51]
	v_mfma_f32_16x16x32_bf16 v[40:43], v[216:219], v[192:195], v[40:43]
	v_mfma_f32_16x16x32_bf16 v[40:43], v[220:223], v[212:215], v[40:43]
	v_mfma_f32_16x16x32_bf16 v[60:63], v[224:227], v[148:151], v[60:63]
	v_mfma_f32_16x16x32_bf16 v[60:63], v[228:231], v[152:155], v[60:63]
	v_mfma_f32_16x16x32_bf16 v[52:55], v[224:227], v[176:179], v[52:55]
	v_mfma_f32_16x16x32_bf16 v[52:55], v[228:231], v[180:183], v[52:55]
	v_mfma_f32_16x16x32_bf16 v[44:47], v[224:227], v[184:187], v[44:47]
	v_mfma_f32_16x16x32_bf16 v[44:47], v[228:231], v[188:191], v[44:47]
	v_mfma_f32_16x16x32_bf16 v[36:39], v[224:227], v[192:195], v[36:39]
	v_mfma_f32_16x16x32_bf16 v[36:39], v[228:231], v[212:215], v[36:39]
	s_barrier
	s_setprio 0
	ds_read_b128 v[148:151], v169 offset:49152
	ds_read_b128 v[152:155], v169 offset:50176
	ds_read_b128 v[176:179], v169 offset:51200
	ds_read_b128 v[180:183], v169 offset:52224
	ds_read_b128 v[184:187], v169 offset:53248
	ds_read_b128 v[188:191], v169 offset:54272
	ds_read_b128 v[192:195], v169 offset:55296
	ds_read_b128 v[212:215], v169 offset:56320
	global_load_lds_dwordx4 v160, s[100:101]
	s_mov_b32 m0, s38
	s_nop 0
	global_load_lds_dwordx4 v156, s[100:101]
	s_waitcnt lgkmcnt(6)
	s_setprio 1
	s_barrier
	v_mfma_f32_16x16x32_bf16 v[104:107], v[92:95], v[148:151], v[104:107]
	v_mfma_f32_16x16x32_bf16 v[104:107], v[100:103], v[152:155], v[104:107]
	s_waitcnt lgkmcnt(0)
	v_mfma_f32_16x16x32_bf16 v[88:91], v[92:95], v[176:179], v[88:91]
	v_mfma_f32_16x16x32_bf16 v[88:91], v[100:103], v[180:183], v[88:91]
	v_mfma_f32_16x16x32_bf16 v[80:83], v[92:95], v[184:187], v[80:83]
	v_mfma_f32_16x16x32_bf16 v[80:83], v[100:103], v[188:191], v[80:83]
	v_mfma_f32_16x16x32_bf16 v[72:75], v[92:95], v[192:195], v[72:75]
	v_mfma_f32_16x16x32_bf16 v[72:75], v[100:103], v[212:215], v[72:75]
	v_mfma_f32_16x16x32_bf16 v[96:99], v[132:135], v[148:151], v[96:99]
	v_mfma_f32_16x16x32_bf16 v[96:99], v[144:147], v[152:155], v[96:99]
	v_mfma_f32_16x16x32_bf16 v[84:87], v[132:135], v[176:179], v[84:87]
	v_mfma_f32_16x16x32_bf16 v[84:87], v[144:147], v[180:183], v[84:87]
	v_mfma_f32_16x16x32_bf16 v[76:79], v[132:135], v[184:187], v[76:79]
	v_mfma_f32_16x16x32_bf16 v[76:79], v[144:147], v[188:191], v[76:79]
	v_mfma_f32_16x16x32_bf16 v[68:71], v[132:135], v[192:195], v[68:71]
	v_mfma_f32_16x16x32_bf16 v[68:71], v[144:147], v[212:215], v[68:71]
	s_barrier
	s_setprio 0
	s_add_u32 s6, s6, 0x20080
	s_addc_u32 s7, s7, 0
	s_add_i32 s10, s10, s29
	s_mov_b32 m0, s10
	s_nop 0
	global_load_lds_dwordx4 v158, s[6:7]
	s_add_i32 m0, s10, 0x2000
	s_nop 0
	global_load_lds_dwordx4 v0, s[6:7]
	s_add_i32 s43, s43, 2
	s_add_u32 s41, s41, 0x100
	s_addc_u32 s42, s42, 0
	s_add_u32 s4, s4, 0x100
	s_addc_u32 s5, s5, 0
	s_waitcnt vmcnt(6)
	s_setprio 1
	s_barrier
	v_mfma_f32_16x16x32_bf16 v[32:35], v[216:219], v[148:151], v[32:35]
	v_mfma_f32_16x16x32_bf16 v[32:35], v[220:223], v[152:155], v[32:35]
	v_mfma_f32_16x16x32_bf16 v[24:27], v[216:219], v[176:179], v[24:27]
	v_mfma_f32_16x16x32_bf16 v[24:27], v[220:223], v[180:183], v[24:27]
	v_mfma_f32_16x16x32_bf16 v[16:19], v[216:219], v[184:187], v[16:19]
	v_mfma_f32_16x16x32_bf16 v[16:19], v[220:223], v[188:191], v[16:19]
	v_mfma_f32_16x16x32_bf16 v[8:11], v[216:219], v[192:195], v[8:11]
	v_mfma_f32_16x16x32_bf16 v[8:11], v[220:223], v[212:215], v[8:11]
	v_mfma_f32_16x16x32_bf16 v[28:31], v[224:227], v[148:151], v[28:31]
	v_mfma_f32_16x16x32_bf16 v[28:31], v[228:231], v[152:155], v[28:31]
	v_mfma_f32_16x16x32_bf16 v[20:23], v[224:227], v[176:179], v[20:23]
	v_mfma_f32_16x16x32_bf16 v[20:23], v[228:231], v[180:183], v[20:23]
	v_mfma_f32_16x16x32_bf16 v[12:15], v[224:227], v[184:187], v[12:15]
	v_mfma_f32_16x16x32_bf16 v[12:15], v[228:231], v[188:191], v[12:15]
	v_mfma_f32_16x16x32_bf16 v[4:7], v[224:227], v[192:195], v[4:7]
	v_mfma_f32_16x16x32_bf16 v[4:7], v[228:231], v[212:215], v[4:7]
	s_barrier
	s_setprio 0
	s_cmp_gt_u32 s43, 5
	s_cbranch_scc0 .LBB0_485
; __device__ __forceinline__ size_t pidx(size_t row, int col) { return ((size_t)(col >> 8) * MTOK + row) * PLD + (col & 255); }
; __device__ __forceinline__ float bflo(unsigned v) { return __uint_as_float(v << 16); }
; __device__ __forceinline__ float bfhi(unsigned v) { return __uint_as_float(v & 0xffff0000u); }
; __device__ __forceinline__ float siluf_(float x) { return x * __builtin_amdgcn_rcpf(1.0f + __expf(-x)); }
;   __device__ __forceinline__ void operator()(EPI_ARGS) const {
;     const size_t row0 = (size_t)u.pm * 256 + wr * 64 + fr;
;     const int col0 = u.pn * 256 + wc * 32 + 8 * fq;
; #pragma unroll
;     for (int bj = 0; bj < 2; ++bj) {
;       const int c = col0 + bj * HALF;
;       const f32x4 s0 = *(const f32x4*)(psc + c), s1 = *(const f32x4*)(psc + c + 4);
; #pragma unroll
;       for (int ai = 0; ai < 2; ++ai) {
;         u32x4 z[4];
; #pragma unroll
;         for (int m = 0; m < 4; ++m) z[m] = *(const u32x4*)(proj + pidx(row0 + ai * HALF + m * 16, PZ + c));
;         __builtin_amdgcn_sched_barrier(0);
; #pragma unroll
;         for (int m = 0; m < 4; ++m) {
;           const size_t row = row0 + ai * HALF + m * 16;
;           const f32x4 v0 = acc[ai][bj][m][0], v1 = acc[ai][bj][m][1];
;           u32x4 o;
;           o.x = pack2(v0[0] * s0[0] * siluf_(bflo(z[m].x)), v0[1] * s0[1] * siluf_(bfhi(z[m].x)));
;           o.y = pack2(v0[2] * s0[2] * siluf_(bflo(z[m].y)), v0[3] * s0[3] * siluf_(bfhi(z[m].y)));
;           o.z = pack2(v1[0] * s1[0] * siluf_(bflo(z[m].z)), v1[1] * s1[1] * siluf_(bfhi(z[m].z)));
;           o.w = pack2(v1[2] * s1[2] * siluf_(bflo(z[m].w)), v1[3] * s1[3] * siluf_(bfhi(z[m].w)));
;           *(u32x4*)(y0 + row * DM + c) = o;
;         }
;       }
;     }
;   }
	s_ashr_i32 s3, s2, 31
	s_lshl_b64 s[2:3], s[2:3], 8
	v_lshl_add_u64 v[186:187], s[2:3], 0, v[162:163]
	s_lshl_b32 s2, s33, 8
	v_or_b32_e32 v196, s2, v168
	s_addk_i32 s2, 0x800
	s_ashr_i32 s2, s2, 8
	s_ashr_i32 s3, s2, 31
	s_lshl_b64 s[2:3], s[2:3], 23
	s_add_u32 s2, s0, s2
	s_addc_u32 s3, s1, s3
	v_lshlrev_b32_e32 v2, 1, v168
	v_or_b32_e32 v194, 16, v186
	v_mov_b32_e32 v195, v187
	v_ashrrev_i32_e32 v197, 31, v196
	v_lshl_add_u64 v[188:189], s[2:3], 0, v[2:3]
	v_lshlrev_b64 v[178:179], 9, v[186:187]
	v_lshlrev_b64 v[180:181], 9, v[194:195]
	v_or_b32_e32 v192, 32, v186
	v_mov_b32_e32 v193, v187
	v_or_b32_e32 v190, 48, v186
	v_mov_b32_e32 v191, v187
	v_lshl_add_u64 v[176:177], v[196:197], 2, s[12:13]
	v_lshl_add_u64 v[132:133], v[188:189], 0, v[178:179]
	v_lshl_add_u64 v[134:135], v[188:189], 0, v[180:181]
	v_lshlrev_b64 v[182:183], 9, v[192:193]
	v_lshlrev_b64 v[184:185], 9, v[190:191]
	global_load_dwordx4 v[92:95], v[176:177], off offset:16
	global_load_dwordx4 v[100:103], v[176:177], off
	flat_load_dwordx4 v[152:155], v[132:133]
	flat_load_dwordx4 v[148:151], v[134:135]
	v_lshl_add_u64 v[132:133], v[188:189], 0, v[182:183]
	v_lshl_add_u64 v[134:135], v[188:189], 0, v[184:185]
	flat_load_dwordx4 v[144:147], v[132:133]
	s_nop 0
	flat_load_dwordx4 v[132:135], v[134:135]
	s_waitcnt vmcnt(0) lgkmcnt(0)
	v_lshlrev_b32_e32 v213, 16, v152
	v_mul_f32_e32 v2, 0xbfb8aa3b, v213
	v_exp_f32_e32 v2, v2
	v_mov_b32_e32 v214, v140
	v_mov_b32_e32 v212, v100
	s_mov_b64 s[4:5], 0x90
	v_add_f32_e32 v2, 1.0, v2
	v_rcp_f32_e32 v215, v2
	s_nop 0
	v_pk_mul_f32 v[212:213], v[214:215], v[212:213]
	s_nop 0
	v_mul_f32_e32 v2, v212, v213
	v_and_b32_e32 v213, 0xffff0000, v152
	v_mul_f32_e32 v140, 0xbfb8aa3b, v213
	v_exp_f32_e32 v140, v140
	v_mov_b32_e32 v214, v141
	v_mov_b32_e32 v212, v101
	v_add_f32_e32 v140, 1.0, v140
	v_rcp_f32_e32 v215, v140
	s_nop 0
	v_pk_mul_f32 v[140:141], v[214:215], v[212:213]
	s_nop 0
	v_mul_f32_e32 v140, v140, v141
	v_lshlrev_b32_e32 v141, 16, v153
	v_cvt_pk_bf16_f32 v152, v2, v140
	v_mul_f32_e32 v2, 0xbfb8aa3b, v141
	v_exp_f32_e32 v2, v2
	v_mov_b32_e32 v212, v142
	v_mov_b32_e32 v140, v102
	v_mov_b32_e32 v142, v136
	v_add_f32_e32 v2, 1.0, v2
	v_rcp_f32_e32 v213, v2
	s_nop 0
	v_pk_mul_f32 v[140:141], v[212:213], v[140:141]
	s_nop 0
	v_mul_f32_e32 v2, v140, v141
	v_and_b32_e32 v141, 0xffff0000, v153
	v_mul_f32_e32 v140, 0xbfb8aa3b, v141
	v_exp_f32_e32 v140, v140
	v_mov_b32_e32 v212, v143
	v_add_f32_e32 v140, 1.0, v140
	v_rcp_f32_e32 v213, v140
	v_mov_b32_e32 v140, v103
	v_pk_mul_f32 v[140:141], v[212:213], v[140:141]
	s_nop 0
	v_mul_f32_e32 v140, v140, v141
	v_lshlrev_b32_e32 v141, 16, v154
	v_cvt_pk_bf16_f32 v153, v2, v140
	v_mul_f32_e32 v2, 0xbfb8aa3b, v141
	v_exp_f32_e32 v2, v2
	v_mov_b32_e32 v140, v92
	v_add_f32_e32 v2, 1.0, v2
	v_rcp_f32_e32 v143, v2
	s_nop 0
	v_pk_mul_f32 v[140:141], v[142:143], v[140:141]
	s_nop 0
	v_mul_f32_e32 v2, v140, v141
	v_and_b32_e32 v141, 0xffff0000, v154
	v_mul_f32_e32 v136, 0xbfb8aa3b, v141
	v_exp_f32_e32 v136, v136
	v_mov_b32_e32 v142, v137
	v_mov_b32_e32 v140, v93
	v_add_f32_e32 v136, 1.0, v136
	v_rcp_f32_e32 v143, v136
	s_nop 0
	v_pk_mul_f32 v[136:137], v[142:143], v[140:141]
	s_nop 0
	v_mul_f32_e32 v136, v136, v137
	v_lshlrev_b32_e32 v137, 16, v155
	v_cvt_pk_bf16_f32 v154, v2, v136
	v_mul_f32_e32 v2, 0xbfb8aa3b, v137
	v_exp_f32_e32 v2, v2
	v_mov_b32_e32 v140, v138
	v_mov_b32_e32 v136, v94
	v_mov_b32_e32 v142, v128
	v_add_f32_e32 v2, 1.0, v2
	v_rcp_f32_e32 v141, v2
	v_mov_b32_e32 v138, v100
	v_pk_mul_f32 v[136:137], v[140:141], v[136:137]
	s_nop 0
	v_mul_f32_e32 v2, v136, v137
	v_and_b32_e32 v137, 0xffff0000, v155
	v_mul_f32_e32 v136, 0xbfb8aa3b, v137
	v_exp_f32_e32 v136, v136
	v_mov_b32_e32 v140, v139
	v_lshlrev_b32_e32 v139, 16, v148
	v_add_f32_e32 v136, 1.0, v136
	v_rcp_f32_e32 v141, v136
	v_mov_b32_e32 v136, v95
	v_pk_mul_f32 v[136:137], v[140:141], v[136:137]
	s_nop 0
	v_mul_f32_e32 v136, v136, v137
	v_cvt_pk_bf16_f32 v155, v2, v136
	v_mul_f32_e32 v2, 0xbfb8aa3b, v139
	v_exp_f32_e32 v2, v2
	v_lshlrev_b64 v[140:141], 1, v[196:197]
	v_lshlrev_b64 v[136:137], 12, v[186:187]
	v_lshl_add_u64 v[136:137], s[8:9], 0, v[136:137]
	v_add_f32_e32 v2, 1.0, v2
	v_rcp_f32_e32 v143, v2
	v_lshl_add_u64 v[136:137], v[136:137], 0, v[140:141]
	flat_store_dwordx4 v[136:137], v[152:155]
	v_pk_mul_f32 v[138:139], v[142:143], v[138:139]
	s_nop 0
	v_mul_f32_e32 v2, v138, v139
	v_and_b32_e32 v139, 0xffff0000, v148
	v_mul_f32_e32 v128, 0xbfb8aa3b, v139
	v_exp_f32_e32 v128, v128
	v_mov_b32_e32 v142, v129
	v_mov_b32_e32 v138, v101
	v_add_f32_e32 v128, 1.0, v128
	v_rcp_f32_e32 v143, v128
	s_nop 0
	v_pk_mul_f32 v[128:129], v[142:143], v[138:139]
	s_nop 0
	v_mul_f32_e32 v128, v128, v129
	v_lshlrev_b32_e32 v139, 16, v149
	v_cvt_pk_bf16_f32 v128, v2, v128
	v_mul_f32_e32 v2, 0xbfb8aa3b, v139
	v_exp_f32_e32 v2, v2
	v_mov_b32_e32 v142, v130
	v_mov_b32_e32 v138, v102
	v_add_f32_e32 v2, 1.0, v2
	v_rcp_f32_e32 v143, v2
	s_nop 0
	v_pk_mul_f32 v[138:139], v[142:143], v[138:139]
	s_nop 0
	v_mul_f32_e32 v2, v138, v139
	v_and_b32_e32 v139, 0xffff0000, v149
	v_mul_f32_e32 v129, 0xbfb8aa3b, v139
	v_exp_f32_e32 v129, v129
	v_mov_b32_e32 v142, v131
	v_mov_b32_e32 v138, v103
	v_lshl_add_u64 v[148:149], v[186:187], 0, s[52:53]
	v_add_f32_e32 v129, 1.0, v129
	v_rcp_f32_e32 v143, v129
	s_nop 0
	v_pk_mul_f32 v[130:131], v[142:143], v[138:139]
	s_nop 0
	v_mul_f32_e32 v129, v130, v131
	v_lshlrev_b32_e32 v131, 16, v150
	v_cvt_pk_bf16_f32 v129, v2, v129
	v_mul_f32_e32 v2, 0xbfb8aa3b, v131
	v_exp_f32_e32 v2, v2
	v_mov_b32_e32 v138, v124
	v_mov_b32_e32 v130, v92
	v_add_f32_e32 v2, 1.0, v2
	v_rcp_f32_e32 v139, v2
	s_nop 0
	v_pk_mul_f32 v[130:131], v[138:139], v[130:131]
; __device__ __forceinline__ float bflo(unsigned v) { return __uint_as_float(v << 16); }
; __device__ __forceinline__ float bfhi(unsigned v) { return __uint_as_float(v & 0xffff0000u); }
; __device__ __forceinline__ float siluf_(float x) { return x * __builtin_amdgcn_rcpf(1.0f + __expf(-x)); }
;   __device__ __forceinline__ void operator()(EPI_ARGS) const {
;     ...
;         for (int m = 0; m < 4; ++m) {
;           const size_t row = row0 + ai * HALF + m * 16;
;           const f32x4 v0 = acc[ai][bj][m][0], v1 = acc[ai][bj][m][1];
;           u32x4 o;
;           o.x = pack2(v0[0] * s0[0] * siluf_(bflo(z[m].x)), v0[1] * s0[1] * siluf_(bfhi(z[m].x)));
;           o.y = pack2(v0[2] * s0[2] * siluf_(bflo(z[m].y)), v0[3] * s0[3] * siluf_(bfhi(z[m].y)));
;           o.z = pack2(v1[0] * s1[0] * siluf_(bflo(z[m].z)), v1[1] * s1[1] * siluf_(bfhi(z[m].z)));
;           o.w = pack2(v1[2] * s1[2] * siluf_(bflo(z[m].w)), v1[3] * s1[3] * siluf_(bfhi(z[m].w)));
;           *(u32x4*)(y0 + row * DM + c) = o;
;         }
	s_nop 0
	v_mul_f32_e32 v2, v130, v131
	v_and_b32_e32 v131, 0xffff0000, v150
	v_mul_f32_e32 v124, 0xbfb8aa3b, v131
	v_exp_f32_e32 v124, v124
	v_mov_b32_e32 v138, v125
	v_mov_b32_e32 v130, v93
	v_add_f32_e32 v124, 1.0, v124
	v_rcp_f32_e32 v139, v124
	s_nop 0
	v_pk_mul_f32 v[124:125], v[138:139], v[130:131]
	s_nop 0
	v_mul_f32_e32 v124, v124, v125
	v_lshlrev_b32_e32 v125, 16, v151
	v_cvt_pk_bf16_f32 v130, v2, v124
	v_mul_f32_e32 v2, 0xbfb8aa3b, v125
	v_exp_f32_e32 v2, v2
	v_mov_b32_e32 v138, v126
	v_mov_b32_e32 v124, v94
	v_mov_b32_e32 v126, v100
	v_add_f32_e32 v2, 1.0, v2
	v_rcp_f32_e32 v139, v2
	s_nop 0
	v_pk_mul_f32 v[124:125], v[138:139], v[124:125]
	s_nop 0
	v_mul_f32_e32 v2, v124, v125
	v_and_b32_e32 v125, 0xffff0000, v151
	v_mul_f32_e32 v124, 0xbfb8aa3b, v125
	v_exp_f32_e32 v124, v124
	v_mov_b32_e32 v138, v127
	v_lshlrev_b32_e32 v127, 16, v144
	v_add_f32_e32 v124, 1.0, v124
	v_rcp_f32_e32 v139, v124
	v_mov_b32_e32 v124, v95
	v_pk_mul_f32 v[124:125], v[138:139], v[124:125]
	s_nop 0
	v_mul_f32_e32 v124, v124, v125
	v_cvt_pk_bf16_f32 v131, v2, v124
	v_mul_f32_e32 v2, 0xbfb8aa3b, v127
	v_exp_f32_e32 v2, v2
	v_lshlrev_b64 v[124:125], 12, v[194:195]
	v_lshl_add_u64 v[124:125], s[8:9], 0, v[124:125]
	v_lshl_add_u64 v[124:125], v[124:125], 0, v[140:141]
	v_add_f32_e32 v2, 1.0, v2
	flat_store_dwordx4 v[124:125], v[128:131]
	s_nop 1
	v_rcp_f32_e32 v129, v2
	v_mov_b32_e32 v128, v120
	v_lshlrev_b64 v[130:131], 9, v[148:149]
	v_pk_mul_f32 v[126:127], v[128:129], v[126:127]
	s_nop 0
	v_mul_f32_e32 v2, v126, v127
	v_and_b32_e32 v127, 0xffff0000, v144
	v_mul_f32_e32 v120, 0xbfb8aa3b, v127
	v_exp_f32_e32 v120, v120
	v_mov_b32_e32 v128, v121
	v_mov_b32_e32 v126, v101
	v_add_f32_e32 v120, 1.0, v120
	v_rcp_f32_e32 v129, v120
	s_nop 0
	v_pk_mul_f32 v[120:121], v[128:129], v[126:127]
	s_nop 0
	v_mul_f32_e32 v120, v120, v121
	v_lshlrev_b32_e32 v127, 16, v145
	v_cvt_pk_bf16_f32 v120, v2, v120
	v_mul_f32_e32 v2, 0xbfb8aa3b, v127
	v_exp_f32_e32 v2, v2
	v_mov_b32_e32 v128, v122
	v_mov_b32_e32 v126, v102
	v_add_f32_e32 v2, 1.0, v2
	v_rcp_f32_e32 v129, v2
	s_nop 0
	v_pk_mul_f32 v[126:127], v[128:129], v[126:127]
	s_nop 0
	v_mul_f32_e32 v2, v126, v127
	v_and_b32_e32 v127, 0xffff0000, v145
	v_mul_f32_e32 v121, 0xbfb8aa3b, v127
	v_exp_f32_e32 v121, v121
	v_mov_b32_e32 v128, v123
	v_mov_b32_e32 v126, v103
	v_add_f32_e32 v121, 1.0, v121
	v_rcp_f32_e32 v129, v121
	s_nop 0
	v_pk_mul_f32 v[122:123], v[128:129], v[126:127]
	s_nop 0
	v_mul_f32_e32 v121, v122, v123
	v_lshlrev_b32_e32 v123, 16, v146
	v_cvt_pk_bf16_f32 v121, v2, v121
	v_mul_f32_e32 v2, 0xbfb8aa3b, v123
	v_exp_f32_e32 v2, v2
	v_mov_b32_e32 v126, v116
	v_mov_b32_e32 v122, v92
	v_add_f32_e32 v2, 1.0, v2
	v_rcp_f32_e32 v127, v2
	s_nop 0
	v_pk_mul_f32 v[122:123], v[126:127], v[122:123]
	s_nop 0
	v_mul_f32_e32 v2, v122, v123
	v_and_b32_e32 v123, 0xffff0000, v146
	v_mul_f32_e32 v116, 0xbfb8aa3b, v123
	v_exp_f32_e32 v116, v116
	v_mov_b32_e32 v126, v117
	v_mov_b32_e32 v122, v93
	v_add_f32_e32 v116, 1.0, v116
	v_rcp_f32_e32 v127, v116
	s_nop 0
	v_pk_mul_f32 v[116:117], v[126:127], v[122:123]
	s_nop 0
	v_mul_f32_e32 v116, v116, v117
	v_lshlrev_b32_e32 v117, 16, v147
	v_cvt_pk_bf16_f32 v122, v2, v116
	v_mul_f32_e32 v2, 0xbfb8aa3b, v117
	v_exp_f32_e32 v2, v2
	v_mov_b32_e32 v126, v118
	v_mov_b32_e32 v116, v94
	v_mov_b32_e32 v118, v112
	v_add_f32_e32 v2, 1.0, v2
	v_rcp_f32_e32 v127, v2
	s_nop 0
	v_pk_mul_f32 v[116:117], v[126:127], v[116:117]
	s_nop 0
	v_mul_f32_e32 v2, v116, v117
	v_and_b32_e32 v117, 0xffff0000, v147
	v_mul_f32_e32 v116, 0xbfb8aa3b, v117
	v_exp_f32_e32 v116, v116
	v_mov_b32_e32 v126, v119
	v_lshl_add_u64 v[146:147], v[186:187], 0, s[4:5]
	s_mov_b64 s[4:5], 0xa0
	v_add_f32_e32 v116, 1.0, v116
	v_rcp_f32_e32 v127, v116
	v_mov_b32_e32 v116, v95
	v_lshl_add_u64 v[144:145], v[186:187], 0, s[4:5]
	s_mov_b64 s[4:5], 0xb0
	v_pk_mul_f32 v[116:117], v[126:127], v[116:117]
	v_lshl_add_u64 v[142:143], v[186:187], 0, s[4:5]
	v_mul_f32_e32 v116, v116, v117
	v_cvt_pk_bf16_f32 v123, v2, v116
	v_lshlrev_b64 v[116:117], 12, v[192:193]
	v_lshl_add_u64 v[116:117], s[8:9], 0, v[116:117]
	v_lshl_add_u64 v[128:129], v[116:117], 0, v[140:141]
	v_lshlrev_b32_e32 v117, 16, v132
	v_mul_f32_e32 v2, 0xbfb8aa3b, v117
	v_exp_f32_e32 v2, v2
	v_mov_b32_e32 v116, v100
	flat_store_dwordx4 v[128:129], v[120:123]
	v_lshlrev_b64 v[138:139], 9, v[142:143]
	v_add_f32_e32 v2, 1.0, v2
	v_rcp_f32_e32 v119, v2
	s_nop 0
	v_pk_mul_f32 v[116:117], v[118:119], v[116:117]
	s_nop 0
	v_mul_f32_e32 v2, v116, v117
	v_and_b32_e32 v117, 0xffff0000, v132
	v_mul_f32_e32 v112, 0xbfb8aa3b, v117
	v_exp_f32_e32 v112, v112
	v_mov_b32_e32 v118, v113
	v_mov_b32_e32 v116, v101
	v_add_f32_e32 v112, 1.0, v112
	v_rcp_f32_e32 v119, v112
	s_nop 0
	v_pk_mul_f32 v[112:113], v[118:119], v[116:117]
	s_nop 0
	v_mul_f32_e32 v112, v112, v113
	v_lshlrev_b32_e32 v117, 16, v133
	v_cvt_pk_bf16_f32 v112, v2, v112
	v_mul_f32_e32 v2, 0xbfb8aa3b, v117
	v_exp_f32_e32 v2, v2
	v_mov_b32_e32 v118, v114
	v_mov_b32_e32 v116, v102
	v_add_f32_e32 v2, 1.0, v2
	v_rcp_f32_e32 v119, v2
	s_nop 0
	v_pk_mul_f32 v[116:117], v[118:119], v[116:117]
	s_nop 0
	v_mul_f32_e32 v2, v116, v117
	v_and_b32_e32 v117, 0xffff0000, v133
	v_mul_f32_e32 v113, 0xbfb8aa3b, v117
	v_exp_f32_e32 v113, v113
	v_mov_b32_e32 v118, v115
	v_mov_b32_e32 v116, v103
	v_lshlrev_b64 v[132:133], 9, v[146:147]
	v_add_f32_e32 v113, 1.0, v113
	v_rcp_f32_e32 v119, v113
	s_nop 0
	v_pk_mul_f32 v[114:115], v[118:119], v[116:117]
	s_nop 0
	v_mul_f32_e32 v113, v114, v115
	v_lshlrev_b32_e32 v115, 16, v134
	v_cvt_pk_bf16_f32 v113, v2, v113
	v_mul_f32_e32 v2, 0xbfb8aa3b, v115
	v_exp_f32_e32 v2, v2
	v_mov_b32_e32 v116, v108
	v_mov_b32_e32 v114, v92
; __device__ __forceinline__ size_t pidx(size_t row, int col) { return ((size_t)(col >> 8) * MTOK + row) * PLD + (col & 255); }
; __device__ __forceinline__ float bflo(unsigned v) { return __uint_as_float(v << 16); }
; __device__ __forceinline__ float bfhi(unsigned v) { return __uint_as_float(v & 0xffff0000u); }
; __device__ __forceinline__ float siluf_(float x) { return x * __builtin_amdgcn_rcpf(1.0f + __expf(-x)); }
;   __device__ __forceinline__ void operator()(EPI_ARGS) const {
;     ...
;         for (int m = 0; m < 4; ++m) z[m] = *(const u32x4*)(proj + pidx(row0 + ai * HALF + m * 16, PZ + c));
;         __builtin_amdgcn_sched_barrier(0);
; #pragma unroll
;         for (int m = 0; m < 4; ++m) {
;           const size_t row = row0 + ai * HALF + m * 16;
;           const f32x4 v0 = acc[ai][bj][m][0], v1 = acc[ai][bj][m][1];
;           u32x4 o;
;           o.x = pack2(v0[0] * s0[0] * siluf_(bflo(z[m].x)), v0[1] * s0[1] * siluf_(bfhi(z[m].x)));
;           o.y = pack2(v0[2] * s0[2] * siluf_(bflo(z[m].y)), v0[3] * s0[3] * siluf_(bfhi(z[m].y)));
;           o.z = pack2(v1[0] * s1[0] * siluf_(bflo(z[m].z)), v1[1] * s1[1] * siluf_(bfhi(z[m].z)));
;           o.w = pack2(v1[2] * s1[2] * siluf_(bflo(z[m].w)), v1[3] * s1[3] * siluf_(bfhi(z[m].w)));
;           *(u32x4*)(y0 + row * DM + c) = o;
;         }
	v_add_f32_e32 v2, 1.0, v2
	v_rcp_f32_e32 v117, v2
	s_nop 0
	v_pk_mul_f32 v[114:115], v[116:117], v[114:115]
	s_nop 0
	v_mul_f32_e32 v2, v114, v115
	v_and_b32_e32 v115, 0xffff0000, v134
	v_mul_f32_e32 v108, 0xbfb8aa3b, v115
	v_exp_f32_e32 v108, v108
	v_mov_b32_e32 v116, v109
	v_mov_b32_e32 v114, v93
	v_add_f32_e32 v108, 1.0, v108
	v_rcp_f32_e32 v117, v108
	s_nop 0
	v_pk_mul_f32 v[108:109], v[116:117], v[114:115]
	s_nop 0
	v_mul_f32_e32 v108, v108, v109
	v_lshlrev_b32_e32 v109, 16, v135
	v_cvt_pk_bf16_f32 v114, v2, v108
	v_mul_f32_e32 v2, 0xbfb8aa3b, v109
	v_exp_f32_e32 v2, v2
	v_mov_b32_e32 v116, v110
	v_mov_b32_e32 v108, v94
	v_add_f32_e32 v2, 1.0, v2
	v_rcp_f32_e32 v117, v2
	s_nop 0
	v_pk_mul_f32 v[108:109], v[116:117], v[108:109]
	s_nop 0
	v_mul_f32_e32 v2, v108, v109
	v_and_b32_e32 v109, 0xffff0000, v135
	v_mul_f32_e32 v108, 0xbfb8aa3b, v109
	v_exp_f32_e32 v108, v108
	v_mov_b32_e32 v116, v111
	v_lshlrev_b64 v[134:135], 9, v[144:145]
	v_add_f32_e32 v108, 1.0, v108
	v_rcp_f32_e32 v117, v108
	v_mov_b32_e32 v108, v95
	v_pk_mul_f32 v[108:109], v[116:117], v[108:109]
	s_nop 0
	v_mul_f32_e32 v108, v108, v109
	v_cvt_pk_bf16_f32 v115, v2, v108
	v_lshlrev_b64 v[108:109], 12, v[190:191]
	v_lshl_add_u64 v[108:109], s[8:9], 0, v[108:109]
	v_lshl_add_u64 v[126:127], v[108:109], 0, v[140:141]
	flat_store_dwordx4 v[126:127], v[112:115]
	v_lshl_add_u64 v[108:109], v[188:189], 0, v[130:131]
	flat_load_dwordx4 v[120:123], v[108:109]
	v_lshl_add_u64 v[108:109], v[188:189], 0, v[132:133]
	flat_load_dwordx4 v[116:119], v[108:109]
	v_lshl_add_u64 v[108:109], v[188:189], 0, v[134:135]
	flat_load_dwordx4 v[112:115], v[108:109]
	v_lshl_add_u64 v[108:109], v[188:189], 0, v[138:139]
	flat_load_dwordx4 v[108:111], v[108:109]
	s_waitcnt vmcnt(0) lgkmcnt(0)
	v_lshlrev_b32_e32 v151, 16, v120
	v_mul_f32_e32 v2, 0xbfb8aa3b, v151
	v_exp_f32_e32 v2, v2
	v_mov_b32_e32 v152, v104
	v_mov_b32_e32 v150, v100
	v_mov_b32_e32 v175, v3
	v_add_f32_e32 v2, 1.0, v2
	v_rcp_f32_e32 v153, v2
	s_nop 0
	v_pk_mul_f32 v[150:151], v[152:153], v[150:151]
	s_nop 0
	v_mul_f32_e32 v2, v150, v151
	v_and_b32_e32 v151, 0xffff0000, v120
	v_mul_f32_e32 v104, 0xbfb8aa3b, v151
	v_exp_f32_e32 v104, v104
	v_mov_b32_e32 v152, v105
	v_mov_b32_e32 v150, v101
	v_mov_b32_e32 v120, v103
	v_add_f32_e32 v104, 1.0, v104
	v_rcp_f32_e32 v153, v104
	s_nop 0
	v_pk_mul_f32 v[104:105], v[152:153], v[150:151]
	s_nop 0
	v_mul_f32_e32 v104, v104, v105
	v_lshlrev_b32_e32 v151, 16, v121
	v_cvt_pk_bf16_f32 v104, v2, v104
	v_mul_f32_e32 v2, 0xbfb8aa3b, v151
	v_exp_f32_e32 v2, v2
	v_and_b32_e32 v121, 0xffff0000, v121
	v_mul_f32_e32 v105, 0xbfb8aa3b, v121
	v_exp_f32_e32 v105, v105
	v_add_f32_e32 v2, 1.0, v2
	v_rcp_f32_e32 v153, v2
	v_mov_b32_e32 v152, v106
	v_mov_b32_e32 v150, v102
	v_add_f32_e32 v105, 1.0, v105
	v_pk_mul_f32 v[150:151], v[152:153], v[150:151]
	s_nop 0
	v_mul_f32_e32 v2, v150, v151
	v_rcp_f32_e32 v151, v105
	v_mov_b32_e32 v150, v107
	v_pk_mul_f32 v[106:107], v[150:151], v[120:121]
	s_nop 0
	v_mul_f32_e32 v105, v106, v107
	v_lshlrev_b32_e32 v107, 16, v122
	v_cvt_pk_bf16_f32 v105, v2, v105
	v_mul_f32_e32 v2, 0xbfb8aa3b, v107
	v_exp_f32_e32 v2, v2
	v_mov_b32_e32 v120, v96
	v_mov_b32_e32 v106, v92
	v_add_f32_e32 v2, 1.0, v2
	v_rcp_f32_e32 v121, v2
	s_nop 0
	v_pk_mul_f32 v[106:107], v[120:121], v[106:107]
	s_nop 0
	v_mul_f32_e32 v2, v106, v107
	v_and_b32_e32 v107, 0xffff0000, v122
	v_mul_f32_e32 v96, 0xbfb8aa3b, v107
	v_exp_f32_e32 v96, v96
	v_mov_b32_e32 v120, v97
	v_mov_b32_e32 v106, v93
	v_add_f32_e32 v96, 1.0, v96
	v_rcp_f32_e32 v121, v96
	s_nop 0
	v_pk_mul_f32 v[96:97], v[120:121], v[106:107]
	s_nop 0
	v_mul_f32_e32 v96, v96, v97
	v_lshlrev_b32_e32 v97, 16, v123
	v_cvt_pk_bf16_f32 v106, v2, v96
	v_mul_f32_e32 v2, 0xbfb8aa3b, v97
	v_exp_f32_e32 v2, v2
	v_mov_b32_e32 v120, v98
	v_mov_b32_e32 v96, v94
	v_mov_b32_e32 v98, v100
	v_add_f32_e32 v2, 1.0, v2
	v_rcp_f32_e32 v121, v2
	s_nop 0
	v_pk_mul_f32 v[96:97], v[120:121], v[96:97]
	s_nop 0
	v_mul_f32_e32 v2, v96, v97
	v_and_b32_e32 v97, 0xffff0000, v123
	v_mul_f32_e32 v96, 0xbfb8aa3b, v97
	v_exp_f32_e32 v96, v96
	v_mov_b32_e32 v120, v99
	v_lshlrev_b32_e32 v99, 16, v116
	v_add_f32_e32 v96, 1.0, v96
	v_rcp_f32_e32 v121, v96
	v_mov_b32_e32 v96, v95
	v_pk_mul_f32 v[96:97], v[120:121], v[96:97]
	s_nop 0
	v_mul_f32_e32 v96, v96, v97
	v_cvt_pk_bf16_f32 v107, v2, v96
	v_mul_f32_e32 v2, 0xbfb8aa3b, v99
	v_exp_f32_e32 v2, v2
	v_lshlrev_b64 v[96:97], 12, v[148:149]
	v_lshl_add_u64 v[96:97], s[8:9], 0, v[96:97]
	v_lshl_add_u64 v[96:97], v[96:97], 0, v[140:141]
	v_add_f32_e32 v2, 1.0, v2
	flat_store_dwordx4 v[96:97], v[104:107]
	s_nop 1
	v_rcp_f32_e32 v105, v2
	v_mov_b32_e32 v104, v88
	v_pk_mul_f32 v[98:99], v[104:105], v[98:99]
	s_nop 0
	v_mul_f32_e32 v2, v98, v99
	v_and_b32_e32 v99, 0xffff0000, v116
	v_mul_f32_e32 v88, 0xbfb8aa3b, v99
	v_exp_f32_e32 v88, v88
	v_mov_b32_e32 v104, v89
	v_mov_b32_e32 v98, v101
	v_add_f32_e32 v88, 1.0, v88
	v_rcp_f32_e32 v105, v88
	s_nop 0
	v_pk_mul_f32 v[88:89], v[104:105], v[98:99]
	s_nop 0
	v_mul_f32_e32 v88, v88, v89
	v_lshlrev_b32_e32 v99, 16, v117
	v_cvt_pk_bf16_f32 v88, v2, v88
	v_mul_f32_e32 v2, 0xbfb8aa3b, v99
	v_exp_f32_e32 v2, v2
	v_mov_b32_e32 v104, v90
	v_mov_b32_e32 v98, v102
	v_add_f32_e32 v2, 1.0, v2
	v_rcp_f32_e32 v105, v2
	s_nop 0
	v_pk_mul_f32 v[98:99], v[104:105], v[98:99]
	s_nop 0
	v_mul_f32_e32 v2, v98, v99
	v_and_b32_e32 v99, 0xffff0000, v117
	v_mul_f32_e32 v89, 0xbfb8aa3b, v99
	v_exp_f32_e32 v89, v89
	v_mov_b32_e32 v104, v91
	v_mov_b32_e32 v98, v103
	v_add_f32_e32 v89, 1.0, v89
	v_rcp_f32_e32 v105, v89
	s_nop 0
	v_pk_mul_f32 v[90:91], v[104:105], v[98:99]
	s_nop 0
	v_mul_f32_e32 v89, v90, v91
	v_lshlrev_b32_e32 v91, 16, v118
; __device__ __forceinline__ size_t pidx(size_t row, int col) { return ((size_t)(col >> 8) * MTOK + row) * PLD + (col & 255); }
; __device__ __forceinline__ float bflo(unsigned v) { return __uint_as_float(v << 16); }
; __device__ __forceinline__ float bfhi(unsigned v) { return __uint_as_float(v & 0xffff0000u); }
; __device__ __forceinline__ float siluf_(float x) { return x * __builtin_amdgcn_rcpf(1.0f + __expf(-x)); }
;   __device__ __forceinline__ void operator()(EPI_ARGS) const {
;     ...
;         for (int m = 0; m < 4; ++m) z[m] = *(const u32x4*)(proj + pidx(row0 + ai * HALF + m * 16, PZ + c));
;         __builtin_amdgcn_sched_barrier(0);
; #pragma unroll
;         for (int m = 0; m < 4; ++m) {
;           const size_t row = row0 + ai * HALF + m * 16;
;           const f32x4 v0 = acc[ai][bj][m][0], v1 = acc[ai][bj][m][1];
;           u32x4 o;
;           o.x = pack2(v0[0] * s0[0] * siluf_(bflo(z[m].x)), v0[1] * s0[1] * siluf_(bfhi(z[m].x)));
;           o.y = pack2(v0[2] * s0[2] * siluf_(bflo(z[m].y)), v0[3] * s0[3] * siluf_(bfhi(z[m].y)));
;           o.z = pack2(v1[0] * s1[0] * siluf_(bflo(z[m].z)), v1[1] * s1[1] * siluf_(bfhi(z[m].z)));
;           o.w = pack2(v1[2] * s1[2] * siluf_(bflo(z[m].w)), v1[3] * s1[3] * siluf_(bfhi(z[m].w)));
;           *(u32x4*)(y0 + row * DM + c) = o;
;         }
	v_cvt_pk_bf16_f32 v89, v2, v89
	v_mul_f32_e32 v2, 0xbfb8aa3b, v91
	v_exp_f32_e32 v2, v2
	v_mov_b32_e32 v98, v84
	v_mov_b32_e32 v90, v92
	v_add_f32_e32 v2, 1.0, v2
	v_rcp_f32_e32 v99, v2
	s_nop 0
	v_pk_mul_f32 v[90:91], v[98:99], v[90:91]
	s_nop 0
	v_mul_f32_e32 v2, v90, v91
	v_and_b32_e32 v91, 0xffff0000, v118
	v_mul_f32_e32 v84, 0xbfb8aa3b, v91
	v_exp_f32_e32 v84, v84
	v_mov_b32_e32 v98, v85
	v_mov_b32_e32 v90, v93
	v_add_f32_e32 v84, 1.0, v84
	v_rcp_f32_e32 v99, v84
	s_nop 0
	v_pk_mul_f32 v[84:85], v[98:99], v[90:91]
	s_nop 0
	v_mul_f32_e32 v84, v84, v85
	v_lshlrev_b32_e32 v85, 16, v119
	v_cvt_pk_bf16_f32 v90, v2, v84
	v_mul_f32_e32 v2, 0xbfb8aa3b, v85
	v_exp_f32_e32 v2, v2
	v_mov_b32_e32 v98, v86
	v_mov_b32_e32 v84, v94
	v_mov_b32_e32 v86, v80
	v_add_f32_e32 v2, 1.0, v2
	v_rcp_f32_e32 v99, v2
	s_nop 0
	v_pk_mul_f32 v[84:85], v[98:99], v[84:85]
	s_nop 0
	v_mul_f32_e32 v2, v84, v85
	v_and_b32_e32 v85, 0xffff0000, v119
	v_mul_f32_e32 v84, 0xbfb8aa3b, v85
	v_exp_f32_e32 v84, v84
	v_mov_b32_e32 v98, v87
	v_add_f32_e32 v84, 1.0, v84
	v_rcp_f32_e32 v99, v84
	v_mov_b32_e32 v84, v95
	v_pk_mul_f32 v[84:85], v[98:99], v[84:85]
	s_nop 0
	v_mul_f32_e32 v84, v84, v85
	v_cvt_pk_bf16_f32 v91, v2, v84
	v_lshlrev_b64 v[84:85], 12, v[146:147]
	v_lshl_add_u64 v[84:85], s[8:9], 0, v[84:85]
	v_lshl_add_u64 v[98:99], v[84:85], 0, v[140:141]
	v_lshlrev_b32_e32 v85, 16, v112
	v_mul_f32_e32 v2, 0xbfb8aa3b, v85
	v_exp_f32_e32 v2, v2
	v_mov_b32_e32 v84, v100
	flat_store_dwordx4 v[98:99], v[88:91]
	v_add_f32_e32 v2, 1.0, v2
	v_rcp_f32_e32 v87, v2
	s_nop 0
	v_pk_mul_f32 v[84:85], v[86:87], v[84:85]
	s_nop 0
	v_mul_f32_e32 v2, v84, v85
	v_and_b32_e32 v85, 0xffff0000, v112
	v_mul_f32_e32 v80, 0xbfb8aa3b, v85
	v_exp_f32_e32 v80, v80
	v_mov_b32_e32 v86, v81
	v_mov_b32_e32 v84, v101
	v_add_f32_e32 v80, 1.0, v80
	v_rcp_f32_e32 v87, v80
	s_nop 0
	v_pk_mul_f32 v[80:81], v[86:87], v[84:85]
	s_nop 0
	v_mul_f32_e32 v80, v80, v81
	v_lshlrev_b32_e32 v85, 16, v113
	v_cvt_pk_bf16_f32 v80, v2, v80
	v_mul_f32_e32 v2, 0xbfb8aa3b, v85
	v_exp_f32_e32 v2, v2
	v_mov_b32_e32 v86, v82
	v_mov_b32_e32 v84, v102
	v_add_f32_e32 v2, 1.0, v2
	v_rcp_f32_e32 v87, v2
	s_nop 0
	v_pk_mul_f32 v[84:85], v[86:87], v[84:85]
	s_nop 0
	v_mul_f32_e32 v2, v84, v85
	v_and_b32_e32 v85, 0xffff0000, v113
	v_mul_f32_e32 v81, 0xbfb8aa3b, v85
	v_exp_f32_e32 v81, v81
	v_mov_b32_e32 v86, v83
	v_mov_b32_e32 v84, v103
	v_add_f32_e32 v81, 1.0, v81
	v_rcp_f32_e32 v87, v81
	s_nop 0
	v_pk_mul_f32 v[82:83], v[86:87], v[84:85]
	s_nop 0
	v_mul_f32_e32 v81, v82, v83
	v_lshlrev_b32_e32 v83, 16, v114
	v_cvt_pk_bf16_f32 v81, v2, v81
	v_mul_f32_e32 v2, 0xbfb8aa3b, v83
	v_exp_f32_e32 v2, v2
	v_mov_b32_e32 v84, v76
	v_mov_b32_e32 v82, v92
	v_add_f32_e32 v2, 1.0, v2
	v_rcp_f32_e32 v85, v2
	s_nop 0
	v_pk_mul_f32 v[82:83], v[84:85], v[82:83]
	s_nop 0
	v_mul_f32_e32 v2, v82, v83
	v_and_b32_e32 v83, 0xffff0000, v114
	v_mul_f32_e32 v76, 0xbfb8aa3b, v83
	v_exp_f32_e32 v76, v76
	v_mov_b32_e32 v84, v77
	v_mov_b32_e32 v82, v93
	v_add_f32_e32 v76, 1.0, v76
	v_rcp_f32_e32 v85, v76
	s_nop 0
	v_pk_mul_f32 v[76:77], v[84:85], v[82:83]
	s_nop 0
	v_mul_f32_e32 v76, v76, v77
	v_lshlrev_b32_e32 v77, 16, v115
	v_cvt_pk_bf16_f32 v82, v2, v76
	v_mul_f32_e32 v2, 0xbfb8aa3b, v77
	v_exp_f32_e32 v2, v2
	v_mov_b32_e32 v84, v78
	v_mov_b32_e32 v76, v94
	v_mov_b32_e32 v78, v72
	v_add_f32_e32 v2, 1.0, v2
	v_rcp_f32_e32 v85, v2
	s_nop 0
	v_pk_mul_f32 v[76:77], v[84:85], v[76:77]
	s_nop 0
	v_mul_f32_e32 v2, v76, v77
	v_and_b32_e32 v77, 0xffff0000, v115
	v_mul_f32_e32 v76, 0xbfb8aa3b, v77
	v_exp_f32_e32 v76, v76
	v_mov_b32_e32 v84, v79
	v_add_f32_e32 v76, 1.0, v76
	v_rcp_f32_e32 v85, v76
	v_mov_b32_e32 v76, v95
	v_pk_mul_f32 v[76:77], v[84:85], v[76:77]
	s_nop 0
	v_mul_f32_e32 v76, v76, v77
	v_cvt_pk_bf16_f32 v83, v2, v76
	v_lshlrev_b64 v[76:77], 12, v[144:145]
	v_lshl_add_u64 v[76:77], s[8:9], 0, v[76:77]
	v_lshl_add_u64 v[104:105], v[76:77], 0, v[140:141]
	v_lshlrev_b32_e32 v77, 16, v108
	v_mul_f32_e32 v2, 0xbfb8aa3b, v77
	v_exp_f32_e32 v2, v2
	v_mov_b32_e32 v76, v100
	flat_store_dwordx4 v[104:105], v[80:83]
	v_add_f32_e32 v2, 1.0, v2
	v_rcp_f32_e32 v79, v2
	s_nop 0
	v_pk_mul_f32 v[76:77], v[78:79], v[76:77]
	s_nop 0
	v_mul_f32_e32 v2, v76, v77
	v_and_b32_e32 v77, 0xffff0000, v108
	v_mul_f32_e32 v72, 0xbfb8aa3b, v77
	v_exp_f32_e32 v72, v72
	v_mov_b32_e32 v78, v73
	v_mov_b32_e32 v76, v101
	v_add_f32_e32 v72, 1.0, v72
	v_rcp_f32_e32 v79, v72
	s_nop 0
	v_pk_mul_f32 v[72:73], v[78:79], v[76:77]
	s_nop 0
	v_mul_f32_e32 v72, v72, v73
	v_lshlrev_b32_e32 v77, 16, v109
	v_cvt_pk_bf16_f32 v72, v2, v72
	v_mul_f32_e32 v2, 0xbfb8aa3b, v77
	v_exp_f32_e32 v2, v2
	v_mov_b32_e32 v78, v74
	v_mov_b32_e32 v76, v102
	v_add_f32_e32 v2, 1.0, v2
	v_rcp_f32_e32 v79, v2
	s_nop 0
	v_pk_mul_f32 v[76:77], v[78:79], v[76:77]
	s_nop 0
	v_mul_f32_e32 v2, v76, v77
	v_and_b32_e32 v77, 0xffff0000, v109
	v_mul_f32_e32 v73, 0xbfb8aa3b, v77
	v_exp_f32_e32 v73, v73
	v_mov_b32_e32 v78, v75
	v_mov_b32_e32 v76, v103
	v_add_f32_e32 v73, 1.0, v73
	v_rcp_f32_e32 v79, v73
	s_nop 0
	v_pk_mul_f32 v[74:75], v[78:79], v[76:77]
	s_nop 0
	v_mul_f32_e32 v73, v74, v75
	v_lshlrev_b32_e32 v75, 16, v110
	v_cvt_pk_bf16_f32 v73, v2, v73
	v_mul_f32_e32 v2, 0xbfb8aa3b, v75
	v_exp_f32_e32 v2, v2
	v_mov_b32_e32 v76, v68
	v_mov_b32_e32 v74, v92
	v_add_f32_e32 v2, 1.0, v2
	v_rcp_f32_e32 v77, v2
	s_nop 0
	v_pk_mul_f32 v[74:75], v[76:77], v[74:75]
	s_nop 0
	v_mul_f32_e32 v2, v74, v75
	v_and_b32_e32 v75, 0xffff0000, v110
	v_mul_f32_e32 v68, 0xbfb8aa3b, v75
	v_exp_f32_e32 v68, v68
	v_mov_b32_e32 v76, v69
	v_mov_b32_e32 v74, v93
	v_add_f32_e32 v68, 1.0, v68
	v_rcp_f32_e32 v77, v68
	s_nop 0
	v_pk_mul_f32 v[68:69], v[76:77], v[74:75]
	s_nop 0
	v_mul_f32_e32 v68, v68, v69
	v_lshlrev_b32_e32 v69, 16, v111
	v_cvt_pk_bf16_f32 v74, v2, v68
	v_mul_f32_e32 v2, 0xbfb8aa3b, v69
	v_exp_f32_e32 v2, v2
	v_mov_b32_e32 v76, v70
	v_mov_b32_e32 v68, v94
	v_add_f32_e32 v2, 1.0, v2
	v_rcp_f32_e32 v77, v2
	s_nop 0
	v_pk_mul_f32 v[68:69], v[76:77], v[68:69]
	s_nop 0
	v_mul_f32_e32 v2, v68, v69
	v_and_b32_e32 v69, 0xffff0000, v111
	v_mul_f32_e32 v68, 0xbfb8aa3b, v69
	v_exp_f32_e32 v68, v68
	v_mov_b32_e32 v76, v71
	v_add_f32_e32 v68, 1.0, v68
	v_rcp_f32_e32 v77, v68
	v_mov_b32_e32 v68, v95
	v_lshl_add_u64 v[94:95], s[2:3], 0, v[174:175]
	v_pk_mul_f32 v[68:69], v[76:77], v[68:69]
	s_nop 0
	v_mul_f32_e32 v68, v68, v69
	v_cvt_pk_bf16_f32 v75, v2, v68
	v_lshlrev_b64 v[68:69], 12, v[142:143]
	v_lshl_add_u64 v[68:69], s[8:9], 0, v[68:69]
	v_lshl_add_u64 v[92:93], v[68:69], 0, v[140:141]
	flat_store_dwordx4 v[92:93], v[72:75]
	v_lshl_add_u64 v[76:77], v[94:95], 0, v[178:179]
	global_load_dwordx4 v[68:71], v[176:177], off offset:528
	global_load_dwordx4 v[72:75], v[176:177], off offset:512
	flat_load_dwordx4 v[88:91], v[76:77]
	v_lshl_add_u64 v[76:77], v[94:95], 0, v[180:181]
	flat_load_dwordx4 v[84:87], v[76:77]
	v_lshl_add_u64 v[76:77], v[94:95], 0, v[182:183]
	flat_load_dwordx4 v[80:83], v[76:77]
	v_lshl_add_u64 v[76:77], v[94:95], 0, v[184:185]
	flat_load_dwordx4 v[76:79], v[76:77]
	s_waitcnt vmcnt(0) lgkmcnt(0)
; __device__ __forceinline__ float bflo(unsigned v) { return __uint_as_float(v << 16); }
; __device__ __forceinline__ float bfhi(unsigned v) { return __uint_as_float(v & 0xffff0000u); }
; __device__ __forceinline__ float siluf_(float x) { return x * __builtin_amdgcn_rcpf(1.0f + __expf(-x)); }
;   __device__ __forceinline__ void operator()(EPI_ARGS) const {
;     ...
;         for (int m = 0; m < 4; ++m) {
;           const size_t row = row0 + ai * HALF + m * 16;
;           const f32x4 v0 = acc[ai][bj][m][0], v1 = acc[ai][bj][m][1];
;           u32x4 o;
;           o.x = pack2(v0[0] * s0[0] * siluf_(bflo(z[m].x)), v0[1] * s0[1] * siluf_(bfhi(z[m].x)));
;           o.y = pack2(v0[2] * s0[2] * siluf_(bflo(z[m].y)), v0[3] * s0[3] * siluf_(bfhi(z[m].y)));
;           o.z = pack2(v1[0] * s1[0] * siluf_(bflo(z[m].z)), v1[1] * s1[1] * siluf_(bfhi(z[m].z)));
;           o.w = pack2(v1[2] * s1[2] * siluf_(bflo(z[m].w)), v1[3] * s1[3] * siluf_(bfhi(z[m].w)));
;           *(u32x4*)(y0 + row * DM + c) = o;
;         }
	v_lshlrev_b32_e32 v101, 16, v88
	v_mul_f32_e32 v2, 0xbfb8aa3b, v101
	v_exp_f32_e32 v2, v2
	v_mov_b32_e32 v102, v64
	v_mov_b32_e32 v100, v72
	v_add_f32_e32 v2, 1.0, v2
	v_rcp_f32_e32 v103, v2
	s_nop 0
	v_pk_mul_f32 v[100:101], v[102:103], v[100:101]
	s_nop 0
	v_mul_f32_e32 v2, v100, v101
	v_and_b32_e32 v101, 0xffff0000, v88
	v_mul_f32_e32 v64, 0xbfb8aa3b, v101
	v_exp_f32_e32 v64, v64
	v_mov_b32_e32 v102, v65
	v_mov_b32_e32 v100, v73
	v_mov_b32_e32 v88, v75
	v_add_f32_e32 v64, 1.0, v64
	v_rcp_f32_e32 v103, v64
	s_nop 0
	v_pk_mul_f32 v[64:65], v[102:103], v[100:101]
	s_nop 0
	v_mul_f32_e32 v64, v64, v65
	v_lshlrev_b32_e32 v101, 16, v89
	v_cvt_pk_bf16_f32 v64, v2, v64
	v_mul_f32_e32 v2, 0xbfb8aa3b, v101
	v_exp_f32_e32 v2, v2
	v_and_b32_e32 v89, 0xffff0000, v89
	v_mul_f32_e32 v65, 0xbfb8aa3b, v89
	v_exp_f32_e32 v65, v65
	v_add_f32_e32 v2, 1.0, v2
	v_rcp_f32_e32 v103, v2
	v_mov_b32_e32 v102, v66
	v_mov_b32_e32 v100, v74
	v_add_f32_e32 v65, 1.0, v65
	v_pk_mul_f32 v[100:101], v[102:103], v[100:101]
	s_nop 0
	v_mul_f32_e32 v2, v100, v101
	v_rcp_f32_e32 v101, v65
	v_mov_b32_e32 v100, v67
	v_pk_mul_f32 v[66:67], v[100:101], v[88:89]
	s_nop 0
	v_mul_f32_e32 v65, v66, v67
	v_lshlrev_b32_e32 v67, 16, v90
	v_cvt_pk_bf16_f32 v65, v2, v65
	v_mul_f32_e32 v2, 0xbfb8aa3b, v67
	v_exp_f32_e32 v2, v2
	v_mov_b32_e32 v88, v60
	v_mov_b32_e32 v66, v68
	v_add_f32_e32 v2, 1.0, v2
	v_rcp_f32_e32 v89, v2
	s_nop 0
	v_pk_mul_f32 v[66:67], v[88:89], v[66:67]
	s_nop 0
	v_mul_f32_e32 v2, v66, v67
	v_and_b32_e32 v67, 0xffff0000, v90
	v_mul_f32_e32 v60, 0xbfb8aa3b, v67
	v_exp_f32_e32 v60, v60
	v_mov_b32_e32 v88, v61
	v_mov_b32_e32 v66, v69
	v_add_f32_e32 v60, 1.0, v60
	v_rcp_f32_e32 v89, v60
	s_nop 0
	v_pk_mul_f32 v[60:61], v[88:89], v[66:67]
	s_nop 0
	v_mul_f32_e32 v60, v60, v61
	v_lshlrev_b32_e32 v61, 16, v91
	v_cvt_pk_bf16_f32 v66, v2, v60
	v_mul_f32_e32 v2, 0xbfb8aa3b, v61
	v_exp_f32_e32 v2, v2
	v_mov_b32_e32 v88, v62
	v_mov_b32_e32 v60, v70
	v_mov_b32_e32 v62, v56
	v_add_f32_e32 v2, 1.0, v2
	v_rcp_f32_e32 v89, v2
	s_nop 0
	v_pk_mul_f32 v[60:61], v[88:89], v[60:61]
	s_nop 0
	v_mul_f32_e32 v2, v60, v61
	v_and_b32_e32 v61, 0xffff0000, v91
	v_mul_f32_e32 v60, 0xbfb8aa3b, v61
	v_exp_f32_e32 v60, v60
	v_mov_b32_e32 v88, v63
	v_add_f32_e32 v60, 1.0, v60
	v_rcp_f32_e32 v89, v60
	v_mov_b32_e32 v60, v71
	v_pk_mul_f32 v[60:61], v[88:89], v[60:61]
	s_nop 0
	v_mul_f32_e32 v60, v60, v61
	v_lshlrev_b32_e32 v61, 16, v84
	v_cvt_pk_bf16_f32 v67, v2, v60
	v_mul_f32_e32 v2, 0xbfb8aa3b, v61
	v_exp_f32_e32 v2, v2
	v_mov_b32_e32 v60, v72
	flat_store_dwordx4 v[136:137], v[64:67] offset:256
	v_add_f32_e32 v2, 1.0, v2
	v_rcp_f32_e32 v63, v2
	s_nop 0
	v_pk_mul_f32 v[60:61], v[62:63], v[60:61]
	s_nop 0
	v_mul_f32_e32 v2, v60, v61
	v_and_b32_e32 v61, 0xffff0000, v84
	v_mul_f32_e32 v56, 0xbfb8aa3b, v61
	v_exp_f32_e32 v56, v56
	v_mov_b32_e32 v62, v57
	v_mov_b32_e32 v60, v73
	v_add_f32_e32 v56, 1.0, v56
	v_rcp_f32_e32 v63, v56
	s_nop 0
	v_pk_mul_f32 v[56:57], v[62:63], v[60:61]
	s_nop 0
	v_mul_f32_e32 v56, v56, v57
	v_lshlrev_b32_e32 v61, 16, v85
	v_cvt_pk_bf16_f32 v56, v2, v56
	v_mul_f32_e32 v2, 0xbfb8aa3b, v61
	v_exp_f32_e32 v2, v2
	v_mov_b32_e32 v62, v58
	v_mov_b32_e32 v60, v74
	v_add_f32_e32 v2, 1.0, v2
	v_rcp_f32_e32 v63, v2
	s_nop 0
	v_pk_mul_f32 v[60:61], v[62:63], v[60:61]
	s_nop 0
	v_mul_f32_e32 v2, v60, v61
	v_and_b32_e32 v61, 0xffff0000, v85
	v_mul_f32_e32 v57, 0xbfb8aa3b, v61
	v_exp_f32_e32 v57, v57
	v_mov_b32_e32 v62, v59
	v_mov_b32_e32 v60, v75
	v_add_f32_e32 v57, 1.0, v57
	v_rcp_f32_e32 v63, v57
	s_nop 0
	v_pk_mul_f32 v[58:59], v[62:63], v[60:61]
	s_nop 0
	v_mul_f32_e32 v57, v58, v59
	v_lshlrev_b32_e32 v59, 16, v86
	v_cvt_pk_bf16_f32 v57, v2, v57
	v_mul_f32_e32 v2, 0xbfb8aa3b, v59
	v_exp_f32_e32 v2, v2
	v_mov_b32_e32 v60, v52
	v_mov_b32_e32 v58, v68
	v_add_f32_e32 v2, 1.0, v2
	v_rcp_f32_e32 v61, v2
	s_nop 0
	v_pk_mul_f32 v[58:59], v[60:61], v[58:59]
	s_nop 0
	v_mul_f32_e32 v2, v58, v59
	v_and_b32_e32 v59, 0xffff0000, v86
	v_mul_f32_e32 v52, 0xbfb8aa3b, v59
	v_exp_f32_e32 v52, v52
	v_mov_b32_e32 v60, v53
	v_mov_b32_e32 v58, v69
	v_add_f32_e32 v52, 1.0, v52
	v_rcp_f32_e32 v61, v52
	s_nop 0
	v_pk_mul_f32 v[52:53], v[60:61], v[58:59]
	s_nop 0
	v_mul_f32_e32 v52, v52, v53
	v_lshlrev_b32_e32 v53, 16, v87
	v_cvt_pk_bf16_f32 v58, v2, v52
	v_mul_f32_e32 v2, 0xbfb8aa3b, v53
	v_exp_f32_e32 v2, v2
	v_mov_b32_e32 v60, v54
	v_mov_b32_e32 v52, v70
	v_mov_b32_e32 v54, v48
	v_add_f32_e32 v2, 1.0, v2
	v_rcp_f32_e32 v61, v2
	s_nop 0
	v_pk_mul_f32 v[52:53], v[60:61], v[52:53]
	s_nop 0
	v_mul_f32_e32 v2, v52, v53
	v_and_b32_e32 v53, 0xffff0000, v87
	v_mul_f32_e32 v52, 0xbfb8aa3b, v53
	v_exp_f32_e32 v52, v52
	v_mov_b32_e32 v60, v55
	v_add_f32_e32 v52, 1.0, v52
	v_rcp_f32_e32 v61, v52
	v_mov_b32_e32 v52, v71
	v_pk_mul_f32 v[52:53], v[60:61], v[52:53]
	s_nop 0
	v_mul_f32_e32 v52, v52, v53
	v_lshlrev_b32_e32 v53, 16, v80
	v_cvt_pk_bf16_f32 v59, v2, v52
	v_mul_f32_e32 v2, 0xbfb8aa3b, v53
	v_exp_f32_e32 v2, v2
	v_mov_b32_e32 v52, v72
	flat_store_dwordx4 v[124:125], v[56:59] offset:256
	v_add_f32_e32 v2, 1.0, v2
	v_rcp_f32_e32 v55, v2
	s_nop 0
	v_pk_mul_f32 v[52:53], v[54:55], v[52:53]
	s_nop 0
	v_mul_f32_e32 v2, v52, v53
	v_and_b32_e32 v53, 0xffff0000, v80
	v_mul_f32_e32 v48, 0xbfb8aa3b, v53
	v_exp_f32_e32 v48, v48
	v_mov_b32_e32 v54, v49
	v_mov_b32_e32 v52, v73
	v_add_f32_e32 v48, 1.0, v48
	v_rcp_f32_e32 v55, v48
	s_nop 0
	v_pk_mul_f32 v[48:49], v[54:55], v[52:53]
	s_nop 0
	v_mul_f32_e32 v48, v48, v49
	v_lshlrev_b32_e32 v53, 16, v81
	v_cvt_pk_bf16_f32 v48, v2, v48
	v_mul_f32_e32 v2, 0xbfb8aa3b, v53
	v_exp_f32_e32 v2, v2
	v_mov_b32_e32 v54, v50
	v_mov_b32_e32 v52, v74
	v_add_f32_e32 v2, 1.0, v2
	v_rcp_f32_e32 v55, v2
; __device__ __forceinline__ size_t pidx(size_t row, int col) { return ((size_t)(col >> 8) * MTOK + row) * PLD + (col & 255); }
; __device__ __forceinline__ float bflo(unsigned v) { return __uint_as_float(v << 16); }
; __device__ __forceinline__ float bfhi(unsigned v) { return __uint_as_float(v & 0xffff0000u); }
; __device__ __forceinline__ float siluf_(float x) { return x * __builtin_amdgcn_rcpf(1.0f + __expf(-x)); }
;   __device__ __forceinline__ void operator()(EPI_ARGS) const {
;     ...
;         for (int m = 0; m < 4; ++m) z[m] = *(const u32x4*)(proj + pidx(row0 + ai * HALF + m * 16, PZ + c));
;         __builtin_amdgcn_sched_barrier(0);
; #pragma unroll
;         for (int m = 0; m < 4; ++m) {
;           const size_t row = row0 + ai * HALF + m * 16;
;           const f32x4 v0 = acc[ai][bj][m][0], v1 = acc[ai][bj][m][1];
;           u32x4 o;
;           o.x = pack2(v0[0] * s0[0] * siluf_(bflo(z[m].x)), v0[1] * s0[1] * siluf_(bfhi(z[m].x)));
;           o.y = pack2(v0[2] * s0[2] * siluf_(bflo(z[m].y)), v0[3] * s0[3] * siluf_(bfhi(z[m].y)));
;           o.z = pack2(v1[0] * s1[0] * siluf_(bflo(z[m].z)), v1[1] * s1[1] * siluf_(bfhi(z[m].z)));
;           o.w = pack2(v1[2] * s1[2] * siluf_(bflo(z[m].w)), v1[3] * s1[3] * siluf_(bfhi(z[m].w)));
;           *(u32x4*)(y0 + row * DM + c) = o;
;         }
	s_nop 0
	v_pk_mul_f32 v[52:53], v[54:55], v[52:53]
	s_nop 0
	v_mul_f32_e32 v2, v52, v53
	v_and_b32_e32 v53, 0xffff0000, v81
	v_mul_f32_e32 v49, 0xbfb8aa3b, v53
	v_exp_f32_e32 v49, v49
	v_mov_b32_e32 v54, v51
	v_mov_b32_e32 v52, v75
	v_add_f32_e32 v49, 1.0, v49
	v_rcp_f32_e32 v55, v49
	s_nop 0
	v_pk_mul_f32 v[50:51], v[54:55], v[52:53]
	s_nop 0
	v_mul_f32_e32 v49, v50, v51
	v_lshlrev_b32_e32 v51, 16, v82
	v_cvt_pk_bf16_f32 v49, v2, v49
	v_mul_f32_e32 v2, 0xbfb8aa3b, v51
	v_exp_f32_e32 v2, v2
	v_mov_b32_e32 v52, v44
	v_mov_b32_e32 v50, v68
	v_add_f32_e32 v2, 1.0, v2
	v_rcp_f32_e32 v53, v2
	s_nop 0
	v_pk_mul_f32 v[50:51], v[52:53], v[50:51]
	s_nop 0
	v_mul_f32_e32 v2, v50, v51
	v_and_b32_e32 v51, 0xffff0000, v82
	v_mul_f32_e32 v44, 0xbfb8aa3b, v51
	v_exp_f32_e32 v44, v44
	v_mov_b32_e32 v52, v45
	v_mov_b32_e32 v50, v69
	v_add_f32_e32 v44, 1.0, v44
	v_rcp_f32_e32 v53, v44
	s_nop 0
	v_pk_mul_f32 v[44:45], v[52:53], v[50:51]
	s_nop 0
	v_mul_f32_e32 v44, v44, v45
	v_lshlrev_b32_e32 v45, 16, v83
	v_cvt_pk_bf16_f32 v50, v2, v44
	v_mul_f32_e32 v2, 0xbfb8aa3b, v45
	v_exp_f32_e32 v2, v2
	v_mov_b32_e32 v52, v46
	v_mov_b32_e32 v44, v70
	v_mov_b32_e32 v46, v40
	v_add_f32_e32 v2, 1.0, v2
	v_rcp_f32_e32 v53, v2
	s_nop 0
	v_pk_mul_f32 v[44:45], v[52:53], v[44:45]
	s_nop 0
	v_mul_f32_e32 v2, v44, v45
	v_and_b32_e32 v45, 0xffff0000, v83
	v_mul_f32_e32 v44, 0xbfb8aa3b, v45
	v_exp_f32_e32 v44, v44
	v_mov_b32_e32 v52, v47
	v_add_f32_e32 v44, 1.0, v44
	v_rcp_f32_e32 v53, v44
	v_mov_b32_e32 v44, v71
	v_pk_mul_f32 v[44:45], v[52:53], v[44:45]
	s_nop 0
	v_mul_f32_e32 v44, v44, v45
	v_lshlrev_b32_e32 v45, 16, v76
	v_cvt_pk_bf16_f32 v51, v2, v44
	v_mul_f32_e32 v2, 0xbfb8aa3b, v45
	v_exp_f32_e32 v2, v2
	v_mov_b32_e32 v44, v72
	flat_store_dwordx4 v[128:129], v[48:51] offset:256
	v_add_f32_e32 v2, 1.0, v2
	v_rcp_f32_e32 v47, v2
	s_nop 0
	v_pk_mul_f32 v[44:45], v[46:47], v[44:45]
	s_nop 0
	v_mul_f32_e32 v2, v44, v45
	v_and_b32_e32 v45, 0xffff0000, v76
	v_mul_f32_e32 v40, 0xbfb8aa3b, v45
	v_exp_f32_e32 v40, v40
	v_mov_b32_e32 v46, v41
	v_mov_b32_e32 v44, v73
	v_add_f32_e32 v40, 1.0, v40
	v_rcp_f32_e32 v47, v40
	s_nop 0
	v_pk_mul_f32 v[40:41], v[46:47], v[44:45]
	s_nop 0
	v_mul_f32_e32 v40, v40, v41
	v_lshlrev_b32_e32 v45, 16, v77
	v_cvt_pk_bf16_f32 v40, v2, v40
	v_mul_f32_e32 v2, 0xbfb8aa3b, v45
	v_exp_f32_e32 v2, v2
	v_mov_b32_e32 v46, v42
	v_mov_b32_e32 v44, v74
	v_add_f32_e32 v2, 1.0, v2
	v_rcp_f32_e32 v47, v2
	s_nop 0
	v_pk_mul_f32 v[44:45], v[46:47], v[44:45]
	s_nop 0
	v_mul_f32_e32 v2, v44, v45
	v_and_b32_e32 v45, 0xffff0000, v77
	v_mul_f32_e32 v41, 0xbfb8aa3b, v45
	v_exp_f32_e32 v41, v41
	v_mov_b32_e32 v46, v43
	v_mov_b32_e32 v44, v75
	v_add_f32_e32 v41, 1.0, v41
	v_rcp_f32_e32 v47, v41
	s_nop 0
	v_pk_mul_f32 v[42:43], v[46:47], v[44:45]
	s_nop 0
	v_mul_f32_e32 v41, v42, v43
	v_lshlrev_b32_e32 v43, 16, v78
	v_cvt_pk_bf16_f32 v41, v2, v41
	v_mul_f32_e32 v2, 0xbfb8aa3b, v43
	v_exp_f32_e32 v2, v2
	v_mov_b32_e32 v44, v36
	v_mov_b32_e32 v42, v68
	v_add_f32_e32 v2, 1.0, v2
	v_rcp_f32_e32 v45, v2
	s_nop 0
	v_pk_mul_f32 v[42:43], v[44:45], v[42:43]
	s_nop 0
	v_mul_f32_e32 v2, v42, v43
	v_and_b32_e32 v43, 0xffff0000, v78
	v_mul_f32_e32 v36, 0xbfb8aa3b, v43
	v_exp_f32_e32 v36, v36
	v_mov_b32_e32 v44, v37
	v_mov_b32_e32 v42, v69
	v_add_f32_e32 v36, 1.0, v36
	v_rcp_f32_e32 v45, v36
	s_nop 0
	v_pk_mul_f32 v[36:37], v[44:45], v[42:43]
	s_nop 0
	v_mul_f32_e32 v36, v36, v37
	v_lshlrev_b32_e32 v37, 16, v79
	v_cvt_pk_bf16_f32 v42, v2, v36
	v_mul_f32_e32 v2, 0xbfb8aa3b, v37
	v_exp_f32_e32 v2, v2
	v_mov_b32_e32 v44, v38
	v_mov_b32_e32 v36, v70
	v_add_f32_e32 v2, 1.0, v2
	v_rcp_f32_e32 v45, v2
	s_nop 0
	v_pk_mul_f32 v[36:37], v[44:45], v[36:37]
	s_nop 0
	v_mul_f32_e32 v2, v36, v37
	v_and_b32_e32 v37, 0xffff0000, v79
	v_mul_f32_e32 v36, 0xbfb8aa3b, v37
	v_exp_f32_e32 v36, v36
	v_mov_b32_e32 v44, v39
	v_add_f32_e32 v36, 1.0, v36
	v_rcp_f32_e32 v45, v36
	v_mov_b32_e32 v36, v71
	v_pk_mul_f32 v[36:37], v[44:45], v[36:37]
	s_nop 0
	v_mul_f32_e32 v36, v36, v37
	v_cvt_pk_bf16_f32 v43, v2, v36
	flat_store_dwordx4 v[126:127], v[40:43] offset:256
	v_lshl_add_u64 v[36:37], v[94:95], 0, v[130:131]
	flat_load_dwordx4 v[48:51], v[36:37]
	v_lshl_add_u64 v[36:37], v[94:95], 0, v[132:133]
	flat_load_dwordx4 v[44:47], v[36:37]
	v_lshl_add_u64 v[36:37], v[94:95], 0, v[134:135]
	flat_load_dwordx4 v[40:43], v[36:37]
	v_lshl_add_u64 v[36:37], v[94:95], 0, v[138:139]
	flat_load_dwordx4 v[36:39], v[36:37]
	s_waitcnt vmcnt(0) lgkmcnt(0)
; __device__ __forceinline__ float bflo(unsigned v) { return __uint_as_float(v << 16); }
; __device__ __forceinline__ float bfhi(unsigned v) { return __uint_as_float(v & 0xffff0000u); }
; __device__ __forceinline__ float siluf_(float x) { return x * __builtin_amdgcn_rcpf(1.0f + __expf(-x)); }
;   __device__ __forceinline__ void operator()(EPI_ARGS) const {
;     ...
;         for (int m = 0; m < 4; ++m) {
;           const size_t row = row0 + ai * HALF + m * 16;
;           const f32x4 v0 = acc[ai][bj][m][0], v1 = acc[ai][bj][m][1];
;           u32x4 o;
;           o.x = pack2(v0[0] * s0[0] * siluf_(bflo(z[m].x)), v0[1] * s0[1] * siluf_(bfhi(z[m].x)));
;           o.y = pack2(v0[2] * s0[2] * siluf_(bflo(z[m].y)), v0[3] * s0[3] * siluf_(bfhi(z[m].y)));
;           o.z = pack2(v1[0] * s1[0] * siluf_(bflo(z[m].z)), v1[1] * s1[1] * siluf_(bfhi(z[m].z)));
;           o.w = pack2(v1[2] * s1[2] * siluf_(bflo(z[m].w)), v1[3] * s1[3] * siluf_(bfhi(z[m].w)));
;           *(u32x4*)(y0 + row * DM + c) = o;
;         }
	v_lshlrev_b32_e32 v53, 16, v48
	v_mul_f32_e32 v2, 0xbfb8aa3b, v53
	v_exp_f32_e32 v2, v2
	v_mov_b32_e32 v54, v32
	v_mov_b32_e32 v52, v72
	s_and_b64 vcc, exec, s[18:19]
	v_add_f32_e32 v2, 1.0, v2
	v_rcp_f32_e32 v55, v2
	s_mov_b32 s33, s16
	s_mov_b32 s2, s14
	s_mov_b64 s[4:5], s[22:23]
	v_pk_mul_f32 v[52:53], v[54:55], v[52:53]
	v_mov_b32_e32 v54, v33
	v_mul_f32_e32 v2, v52, v53
	v_and_b32_e32 v53, 0xffff0000, v48
	v_mul_f32_e32 v32, 0xbfb8aa3b, v53
	v_exp_f32_e32 v32, v32
	v_mov_b32_e32 v52, v73
	v_mov_b32_e32 v48, v75
	s_mov_b64 s[6:7], s[20:21]
	v_add_f32_e32 v32, 1.0, v32
	v_rcp_f32_e32 v55, v32
	s_nop 0
	v_pk_mul_f32 v[32:33], v[54:55], v[52:53]
	s_nop 0
	v_mul_f32_e32 v32, v32, v33
	v_lshlrev_b32_e32 v53, 16, v49
	v_cvt_pk_bf16_f32 v32, v2, v32
	v_mul_f32_e32 v2, 0xbfb8aa3b, v53
	v_exp_f32_e32 v2, v2
	v_and_b32_e32 v49, 0xffff0000, v49
	v_mul_f32_e32 v33, 0xbfb8aa3b, v49
	v_exp_f32_e32 v33, v33
	v_add_f32_e32 v2, 1.0, v2
	v_rcp_f32_e32 v55, v2
	v_mov_b32_e32 v54, v34
	v_mov_b32_e32 v52, v74
	v_add_f32_e32 v33, 1.0, v33
	v_pk_mul_f32 v[52:53], v[54:55], v[52:53]
	s_nop 0
	v_mul_f32_e32 v2, v52, v53
	v_rcp_f32_e32 v53, v33
	v_mov_b32_e32 v52, v35
	v_pk_mul_f32 v[34:35], v[52:53], v[48:49]
	s_nop 0
	v_mul_f32_e32 v33, v34, v35
	v_lshlrev_b32_e32 v35, 16, v50
	v_cvt_pk_bf16_f32 v33, v2, v33
	v_mul_f32_e32 v2, 0xbfb8aa3b, v35
	v_exp_f32_e32 v2, v2
	v_mov_b32_e32 v48, v28
	v_mov_b32_e32 v34, v68
	v_add_f32_e32 v2, 1.0, v2
	v_rcp_f32_e32 v49, v2
	s_nop 0
	v_pk_mul_f32 v[34:35], v[48:49], v[34:35]
	s_nop 0
	v_mul_f32_e32 v2, v34, v35
	v_and_b32_e32 v35, 0xffff0000, v50
	v_mul_f32_e32 v28, 0xbfb8aa3b, v35
	v_exp_f32_e32 v28, v28
	v_mov_b32_e32 v48, v29
	v_mov_b32_e32 v34, v69
	v_add_f32_e32 v28, 1.0, v28
	v_rcp_f32_e32 v49, v28
	s_nop 0
	v_pk_mul_f32 v[28:29], v[48:49], v[34:35]
	s_nop 0
	v_mul_f32_e32 v28, v28, v29
	v_lshlrev_b32_e32 v29, 16, v51
	v_cvt_pk_bf16_f32 v34, v2, v28
	v_mul_f32_e32 v2, 0xbfb8aa3b, v29
	v_exp_f32_e32 v2, v2
	v_mov_b32_e32 v48, v30
	v_mov_b32_e32 v28, v70
	v_mov_b32_e32 v30, v24
	v_add_f32_e32 v2, 1.0, v2
	v_rcp_f32_e32 v49, v2
	s_nop 0
	v_pk_mul_f32 v[28:29], v[48:49], v[28:29]
	s_nop 0
	v_mul_f32_e32 v2, v28, v29
	v_and_b32_e32 v29, 0xffff0000, v51
	v_mul_f32_e32 v28, 0xbfb8aa3b, v29
	v_exp_f32_e32 v28, v28
	v_mov_b32_e32 v48, v31
	v_add_f32_e32 v28, 1.0, v28
	v_rcp_f32_e32 v49, v28
	v_mov_b32_e32 v28, v71
	v_pk_mul_f32 v[28:29], v[48:49], v[28:29]
	s_nop 0
	v_mul_f32_e32 v28, v28, v29
	v_lshlrev_b32_e32 v29, 16, v44
	v_cvt_pk_bf16_f32 v35, v2, v28
	v_mul_f32_e32 v2, 0xbfb8aa3b, v29
	v_exp_f32_e32 v2, v2
	v_mov_b32_e32 v28, v72
	flat_store_dwordx4 v[96:97], v[32:35] offset:256
	v_add_f32_e32 v2, 1.0, v2
	v_rcp_f32_e32 v31, v2
	s_nop 0
	v_pk_mul_f32 v[28:29], v[30:31], v[28:29]
	s_nop 0
	v_mul_f32_e32 v2, v28, v29
	v_and_b32_e32 v29, 0xffff0000, v44
	v_mul_f32_e32 v24, 0xbfb8aa3b, v29
	v_exp_f32_e32 v24, v24
	v_mov_b32_e32 v30, v25
	v_mov_b32_e32 v28, v73
	v_add_f32_e32 v24, 1.0, v24
	v_rcp_f32_e32 v31, v24
	s_nop 0
	v_pk_mul_f32 v[24:25], v[30:31], v[28:29]
	s_nop 0
	v_mul_f32_e32 v24, v24, v25
	v_lshlrev_b32_e32 v29, 16, v45
	v_cvt_pk_bf16_f32 v24, v2, v24
	v_mul_f32_e32 v2, 0xbfb8aa3b, v29
	v_exp_f32_e32 v2, v2
	v_mov_b32_e32 v30, v26
	v_mov_b32_e32 v28, v74
	v_add_f32_e32 v2, 1.0, v2
	v_rcp_f32_e32 v31, v2
	s_nop 0
	v_pk_mul_f32 v[28:29], v[30:31], v[28:29]
	s_nop 0
	v_mul_f32_e32 v2, v28, v29
	v_and_b32_e32 v29, 0xffff0000, v45
	v_mul_f32_e32 v25, 0xbfb8aa3b, v29
	v_exp_f32_e32 v25, v25
	v_mov_b32_e32 v30, v27
	v_mov_b32_e32 v28, v75
	v_add_f32_e32 v25, 1.0, v25
	v_rcp_f32_e32 v31, v25
	s_nop 0
	v_pk_mul_f32 v[26:27], v[30:31], v[28:29]
	s_nop 0
	v_mul_f32_e32 v25, v26, v27
	v_lshlrev_b32_e32 v27, 16, v46
	v_cvt_pk_bf16_f32 v25, v2, v25
	v_mul_f32_e32 v2, 0xbfb8aa3b, v27
	v_exp_f32_e32 v2, v2
	v_mov_b32_e32 v28, v20
	v_mov_b32_e32 v26, v68
	v_add_f32_e32 v2, 1.0, v2
	v_rcp_f32_e32 v29, v2
	s_nop 0
	v_pk_mul_f32 v[26:27], v[28:29], v[26:27]
	s_nop 0
	v_mul_f32_e32 v2, v26, v27
	v_and_b32_e32 v27, 0xffff0000, v46
	v_mul_f32_e32 v20, 0xbfb8aa3b, v27
	v_exp_f32_e32 v20, v20
	v_mov_b32_e32 v28, v21
	v_mov_b32_e32 v26, v69
	v_add_f32_e32 v20, 1.0, v20
	v_rcp_f32_e32 v29, v20
	s_nop 0
	v_pk_mul_f32 v[20:21], v[28:29], v[26:27]
	s_nop 0
	v_mul_f32_e32 v20, v20, v21
	v_lshlrev_b32_e32 v21, 16, v47
	v_cvt_pk_bf16_f32 v26, v2, v20
	v_mul_f32_e32 v2, 0xbfb8aa3b, v21
	v_exp_f32_e32 v2, v2
	v_mov_b32_e32 v28, v22
	v_mov_b32_e32 v20, v70
	v_mov_b32_e32 v22, v16
	v_add_f32_e32 v2, 1.0, v2
	v_rcp_f32_e32 v29, v2
	s_nop 0
	v_pk_mul_f32 v[20:21], v[28:29], v[20:21]
	s_nop 0
	v_mul_f32_e32 v2, v20, v21
	v_and_b32_e32 v21, 0xffff0000, v47
	v_mul_f32_e32 v20, 0xbfb8aa3b, v21
	v_exp_f32_e32 v20, v20
	v_mov_b32_e32 v28, v23
	v_add_f32_e32 v20, 1.0, v20
	v_rcp_f32_e32 v29, v20
	v_mov_b32_e32 v20, v71
	v_pk_mul_f32 v[20:21], v[28:29], v[20:21]
	s_nop 0
	v_mul_f32_e32 v20, v20, v21
	v_lshlrev_b32_e32 v21, 16, v40
	v_cvt_pk_bf16_f32 v27, v2, v20
	v_mul_f32_e32 v2, 0xbfb8aa3b, v21
	v_exp_f32_e32 v2, v2
	v_mov_b32_e32 v20, v72
	flat_store_dwordx4 v[98:99], v[24:27] offset:256
; __device__ __forceinline__ float bflo(unsigned v) { return __uint_as_float(v << 16); }
; __device__ __forceinline__ float bfhi(unsigned v) { return __uint_as_float(v & 0xffff0000u); }
; __device__ __forceinline__ float siluf_(float x) { return x * __builtin_amdgcn_rcpf(1.0f + __expf(-x)); }
; #define PG8_WAIT_V(n) asm volatile("s_waitcnt vmcnt(" #n ")" ::: "memory")
; #define PG8_BAR __builtin_amdgcn_s_barrier()
; template <class Epi, class AddrA, class AddrB>
; __device__ __forceinline__ void gemm_phase(const Sched S, const int lda, const int ldb, const int K, const AddrA addrA,
;                                            const AddrB addrB, const Epi E) {
;     ...
;     if (!has_next) break;
;     if (!(Epi::KEEP && cur.br + 1 < S.nbr)) {
; #pragma unroll
;       for (int a = 0; a < 2; ++a)
; #pragma unroll
;         for (int b = 0; b < 2; ++b)
; #pragma unroll
;           for (int m = 0; m < 4; ++m)
; #pragma unroll
;             for (int n = 0; n < 2; ++n) acc[a][b][m][n] = (f32x4){0.f, 0.f, 0.f, 0.f};
;     }
;     cur = nxt; cA = nA; cB = nB; ++ui;
;   }
;   PG8_WAIT_V(0);
;   if (wr == 0) PG8_BAR;
;   PG8_BAR;
;   __device__ __forceinline__ void operator()(EPI_ARGS) const {
;     ...
;         for (int m = 0; m < 4; ++m) {
;           const size_t row = row0 + ai * HALF + m * 16;
;           const f32x4 v0 = acc[ai][bj][m][0], v1 = acc[ai][bj][m][1];
;           u32x4 o;
;           o.x = pack2(v0[0] * s0[0] * siluf_(bflo(z[m].x)), v0[1] * s0[1] * siluf_(bfhi(z[m].x)));
;           o.y = pack2(v0[2] * s0[2] * siluf_(bflo(z[m].y)), v0[3] * s0[3] * siluf_(bfhi(z[m].y)));
;           o.z = pack2(v1[0] * s1[0] * siluf_(bflo(z[m].z)), v1[1] * s1[1] * siluf_(bfhi(z[m].z)));
;           o.w = pack2(v1[2] * s1[2] * siluf_(bflo(z[m].w)), v1[3] * s1[3] * siluf_(bfhi(z[m].w)));
;           *(u32x4*)(y0 + row * DM + c) = o;
;         }
	v_add_f32_e32 v2, 1.0, v2
	v_rcp_f32_e32 v23, v2
	s_nop 0
	v_pk_mul_f32 v[20:21], v[22:23], v[20:21]
	s_nop 0
	v_mul_f32_e32 v2, v20, v21
	v_and_b32_e32 v21, 0xffff0000, v40
	v_mul_f32_e32 v16, 0xbfb8aa3b, v21
	v_exp_f32_e32 v16, v16
	v_mov_b32_e32 v22, v17
	v_mov_b32_e32 v20, v73
	v_add_f32_e32 v16, 1.0, v16
	v_rcp_f32_e32 v23, v16
	s_nop 0
	v_pk_mul_f32 v[16:17], v[22:23], v[20:21]
	s_nop 0
	v_mul_f32_e32 v16, v16, v17
	v_lshlrev_b32_e32 v21, 16, v41
	v_cvt_pk_bf16_f32 v16, v2, v16
	v_mul_f32_e32 v2, 0xbfb8aa3b, v21
	v_exp_f32_e32 v2, v2
	v_mov_b32_e32 v22, v18
	v_mov_b32_e32 v20, v74
	v_add_f32_e32 v2, 1.0, v2
	v_rcp_f32_e32 v23, v2
	s_nop 0
	v_pk_mul_f32 v[20:21], v[22:23], v[20:21]
	s_nop 0
	v_mul_f32_e32 v2, v20, v21
	v_and_b32_e32 v21, 0xffff0000, v41
	v_mul_f32_e32 v17, 0xbfb8aa3b, v21
	v_exp_f32_e32 v17, v17
	v_mov_b32_e32 v22, v19
	v_mov_b32_e32 v20, v75
	v_add_f32_e32 v17, 1.0, v17
	v_rcp_f32_e32 v23, v17
	s_nop 0
	v_pk_mul_f32 v[18:19], v[22:23], v[20:21]
	s_nop 0
	v_mul_f32_e32 v17, v18, v19
	v_lshlrev_b32_e32 v19, 16, v42
	v_cvt_pk_bf16_f32 v17, v2, v17
	v_mul_f32_e32 v2, 0xbfb8aa3b, v19
	v_exp_f32_e32 v2, v2
	v_mov_b32_e32 v20, v12
	v_mov_b32_e32 v18, v68
	v_add_f32_e32 v2, 1.0, v2
	v_rcp_f32_e32 v21, v2
	s_nop 0
	v_pk_mul_f32 v[18:19], v[20:21], v[18:19]
	s_nop 0
	v_mul_f32_e32 v2, v18, v19
	v_and_b32_e32 v19, 0xffff0000, v42
	v_mul_f32_e32 v12, 0xbfb8aa3b, v19
	v_exp_f32_e32 v12, v12
	v_mov_b32_e32 v20, v13
	v_mov_b32_e32 v18, v69
	v_add_f32_e32 v12, 1.0, v12
	v_rcp_f32_e32 v21, v12
	s_nop 0
	v_pk_mul_f32 v[12:13], v[20:21], v[18:19]
	s_nop 0
	v_mul_f32_e32 v12, v12, v13
	v_lshlrev_b32_e32 v13, 16, v43
	v_cvt_pk_bf16_f32 v18, v2, v12
	v_mul_f32_e32 v2, 0xbfb8aa3b, v13
	v_exp_f32_e32 v2, v2
	v_mov_b32_e32 v20, v14
	v_mov_b32_e32 v12, v70
	v_mov_b32_e32 v14, v8
	v_add_f32_e32 v2, 1.0, v2
	v_rcp_f32_e32 v21, v2
	s_nop 0
	v_pk_mul_f32 v[12:13], v[20:21], v[12:13]
	s_nop 0
	v_mul_f32_e32 v2, v12, v13
	v_and_b32_e32 v13, 0xffff0000, v43
	v_mul_f32_e32 v12, 0xbfb8aa3b, v13
	v_exp_f32_e32 v12, v12
	v_mov_b32_e32 v20, v15
	v_add_f32_e32 v12, 1.0, v12
	v_rcp_f32_e32 v21, v12
	v_mov_b32_e32 v12, v71
	v_pk_mul_f32 v[12:13], v[20:21], v[12:13]
	s_nop 0
	v_mul_f32_e32 v12, v12, v13
	v_lshlrev_b32_e32 v13, 16, v36
	v_cvt_pk_bf16_f32 v19, v2, v12
	v_mul_f32_e32 v2, 0xbfb8aa3b, v13
	v_exp_f32_e32 v2, v2
	v_mov_b32_e32 v12, v72
	flat_store_dwordx4 v[104:105], v[16:19] offset:256
	v_add_f32_e32 v2, 1.0, v2
	v_rcp_f32_e32 v15, v2
	s_nop 0
	v_pk_mul_f32 v[12:13], v[14:15], v[12:13]
	s_nop 0
	v_mul_f32_e32 v2, v12, v13
	v_and_b32_e32 v13, 0xffff0000, v36
	v_mul_f32_e32 v8, 0xbfb8aa3b, v13
	v_exp_f32_e32 v8, v8
	v_mov_b32_e32 v14, v9
	v_mov_b32_e32 v12, v73
	v_add_f32_e32 v8, 1.0, v8
	v_rcp_f32_e32 v15, v8
	s_nop 0
	v_pk_mul_f32 v[8:9], v[14:15], v[12:13]
	s_nop 0
	v_mul_f32_e32 v8, v8, v9
	v_lshlrev_b32_e32 v13, 16, v37
	v_cvt_pk_bf16_f32 v8, v2, v8
	v_mul_f32_e32 v2, 0xbfb8aa3b, v13
	v_exp_f32_e32 v2, v2
	v_mov_b32_e32 v14, v10
	v_mov_b32_e32 v12, v74
	v_add_f32_e32 v2, 1.0, v2
	v_rcp_f32_e32 v15, v2
	s_nop 0
	v_pk_mul_f32 v[12:13], v[14:15], v[12:13]
	s_nop 0
	v_mul_f32_e32 v2, v12, v13
	v_and_b32_e32 v13, 0xffff0000, v37
	v_mul_f32_e32 v9, 0xbfb8aa3b, v13
	v_exp_f32_e32 v9, v9
	v_mov_b32_e32 v14, v11
	v_mov_b32_e32 v12, v75
	v_add_f32_e32 v9, 1.0, v9
	v_rcp_f32_e32 v15, v9
	s_nop 0
	v_pk_mul_f32 v[10:11], v[14:15], v[12:13]
	s_nop 0
	v_mul_f32_e32 v9, v10, v11
	v_lshlrev_b32_e32 v11, 16, v38
	v_cvt_pk_bf16_f32 v9, v2, v9
	v_mul_f32_e32 v2, 0xbfb8aa3b, v11
	v_exp_f32_e32 v2, v2
	v_mov_b32_e32 v12, v4
	v_mov_b32_e32 v10, v68
	v_add_f32_e32 v2, 1.0, v2
	v_rcp_f32_e32 v13, v2
	s_nop 0
	v_pk_mul_f32 v[10:11], v[12:13], v[10:11]
	s_nop 0
	v_mul_f32_e32 v2, v10, v11
	v_and_b32_e32 v11, 0xffff0000, v38
	v_mul_f32_e32 v4, 0xbfb8aa3b, v11
	v_exp_f32_e32 v4, v4
	v_mov_b32_e32 v12, v5
	v_mov_b32_e32 v10, v69
	v_add_f32_e32 v4, 1.0, v4
	v_rcp_f32_e32 v13, v4
	s_nop 0
	v_pk_mul_f32 v[4:5], v[12:13], v[10:11]
	s_nop 0
	v_mul_f32_e32 v4, v4, v5
	v_lshlrev_b32_e32 v5, 16, v39
	v_cvt_pk_bf16_f32 v10, v2, v4
	v_mul_f32_e32 v2, 0xbfb8aa3b, v5
	v_exp_f32_e32 v2, v2
	v_mov_b32_e32 v12, v6
	v_mov_b32_e32 v4, v70
	v_add_f32_e32 v2, 1.0, v2
	v_rcp_f32_e32 v13, v2
	s_nop 0
	v_pk_mul_f32 v[4:5], v[12:13], v[4:5]
	s_nop 0
	v_mul_f32_e32 v2, v4, v5
	v_and_b32_e32 v5, 0xffff0000, v39
	v_mul_f32_e32 v4, 0xbfb8aa3b, v5
	v_exp_f32_e32 v4, v4
	v_mov_b32_e32 v12, v7
	v_add_f32_e32 v4, 1.0, v4
	v_rcp_f32_e32 v13, v4
	v_mov_b32_e32 v4, v71
	v_pk_mul_f32 v[4:5], v[12:13], v[4:5]
	s_nop 0
	v_mul_f32_e32 v4, v4, v5
	v_cvt_pk_bf16_f32 v11, v2, v4
	flat_store_dwordx4 v[92:93], v[8:11] offset:256
	s_cbranch_vccz .LBB0_482
	s_waitcnt vmcnt(0)
	v_readlane_b32 s44, v244, 59
	v_readlane_b32 s40, v243, 18
	s_cmpk_gt_u32 s24, 0xff
	s_mov_b32 s43, 0x800000
	v_readlane_b32 s45, v244, 60
	v_readlane_b32 s46, v244, 61
	v_readlane_b32 s47, v244, 62
	v_readlane_b32 s48, v244, 63
	v_readlane_b32 s49, v243, 0
	v_readlane_b32 s50, v243, 1
	v_readlane_b32 s51, v243, 2
	v_readlane_b32 s41, v243, 19
	s_cbranch_scc1 .LBB0_489
	s_barrier

; #define PG8_WAIT_V(n) asm volatile("s_waitcnt vmcnt(" #n ")" ::: "memory")
; #define PG8_WAIT_L(n) asm volatile("s_waitcnt lgkmcnt(" #n ")" ::: "memory")
; #define PG8_BAR __builtin_amdgcn_s_barrier()
; #define PG8_SCHED __builtin_amdgcn_sched_barrier(0)
; template <class Epi, class AddrA, class AddrB>
; __device__ __forceinline__ void gemm_phase(const Sched S, const int lda, const int ldb, const int K, const AddrA addrA,
;                                            const AddrB addrB, const Epi E) {
;     ...
;       PG8_LDB(B0, 0, 0); PG8_SCHED; PG8_LDA(At, 0, 0); PG8_STAGE(PG8_SA(1, 1), a1 + hstepA, voffA);
;       PG8_WAIT_L(8); PG8_BAR; PG8_WAIT_L(0); PG8_MMA(0, 0, At, B0); PG8_BAR; PG8_SCHED;
;       PG8_LDB(B1, 0, 1); PG8_STAGE(PG8_SB(0, 0), b2, voffB);
;       PG8_BAR; PG8_WAIT_L(0); PG8_MMA(0, 1, At, B1); PG8_BAR;
;       PG8_LDA(At, 0, 1); PG8_STAGE(PG8_SA(0, 0), a2, voffA);
;       PG8_BAR; PG8_WAIT_L(0); PG8_MMA(1, 0, At, B0); PG8_BAR; PG8_SCHED;
;       PG8_STAGE(PG8_SB(0, 1), b2 + hstepB, voffB);
;       PG8_WAIT_V(6); PG8_BAR; PG8_MMA(1, 1, At, B1); PG8_BAR;
;       PG8_LDB(B0, 1, 0); PG8_SCHED; PG8_LDA(At, 1, 0); PG8_STAGE(PG8_SA(0, 1), a2 + hstepA, voffA);
;       PG8_WAIT_L(8); PG8_BAR; PG8_WAIT_L(0); PG8_MMA(0, 0, At, B0); PG8_BAR; PG8_SCHED;
.LBB0_543:
	s_add_i32 s43, 0, 0x10000
	v_add_u32_e32 v246, s43, v167
	ds_read_b128 v[132:135], v246
	ds_read_b128 v[136:139], v246 offset:1024
	ds_read_b128 v[140:143], v246 offset:2048
	ds_read_b128 v[144:147], v246 offset:3072
	s_add_i32 m0, s28, 0xc000
	ds_read_b128 v[148:151], v188
	ds_read_b128 v[152:155], v188 offset:1024
	ds_read_b128 v[156:159], v188 offset:2048
	ds_read_b128 v[160:163], v188 offset:3072
	ds_read_b128 v[182:185], v188 offset:4096
	ds_read_b128 v[190:193], v188 offset:5120
	ds_read_b128 v[194:197], v188 offset:6144
	ds_read_b128 v[212:215], v188 offset:7168
	global_load_lds_dwordx4 v180, s[2:3]
	s_add_i32 m0, s28, 0xe000
	s_nop 0
	global_load_lds_dwordx4 v178, s[2:3]
	s_waitcnt lgkmcnt(6)
	s_setprio 1
	s_barrier
	v_mfma_f32_16x16x32_bf16 v[128:131], v[132:135], v[148:151], v[128:131]
	v_mfma_f32_16x16x32_bf16 v[128:131], v[136:139], v[152:155], v[128:131]
	s_waitcnt lgkmcnt(0)
	v_mfma_f32_16x16x32_bf16 v[120:123], v[132:135], v[156:159], v[120:123]
	v_mfma_f32_16x16x32_bf16 v[120:123], v[136:139], v[160:163], v[120:123]
	v_mfma_f32_16x16x32_bf16 v[112:115], v[132:135], v[182:185], v[112:115]
	v_mfma_f32_16x16x32_bf16 v[112:115], v[136:139], v[190:193], v[112:115]
	v_mfma_f32_16x16x32_bf16 v[104:107], v[132:135], v[194:197], v[104:107]
	v_mfma_f32_16x16x32_bf16 v[104:107], v[136:139], v[212:215], v[104:107]
	v_mfma_f32_16x16x32_bf16 v[124:127], v[140:143], v[148:151], v[124:127]
	v_mfma_f32_16x16x32_bf16 v[124:127], v[144:147], v[152:155], v[124:127]
	v_mfma_f32_16x16x32_bf16 v[116:119], v[140:143], v[156:159], v[116:119]
	v_mfma_f32_16x16x32_bf16 v[116:119], v[144:147], v[160:163], v[116:119]
	v_mfma_f32_16x16x32_bf16 v[108:111], v[140:143], v[182:185], v[108:111]
	v_mfma_f32_16x16x32_bf16 v[108:111], v[144:147], v[190:193], v[108:111]
	v_mfma_f32_16x16x32_bf16 v[100:103], v[140:143], v[194:197], v[100:103]
	v_mfma_f32_16x16x32_bf16 v[100:103], v[144:147], v[212:215], v[100:103]
	s_barrier
	s_setprio 0
	s_add_u32 s4, s2, 0xfff80080
	s_addc_u32 s5, s3, -1
	s_cmp_eq_u32 s42, 28
	s_cselect_b32 s7, s1, s5
	s_cselect_b32 s6, s9, s4
	s_cselect_b32 s5, s13, s41
	s_cselect_b32 s4, s15, s33
	s_add_i32 s46, 0, 0x14000
	s_add_i32 s43, s43, s27
	ds_read_b128 v[216:219], v246 offset:16384
	ds_read_b128 v[220:223], v246 offset:17408
	ds_read_b128 v[224:227], v246 offset:18432
	ds_read_b128 v[228:231], v246 offset:19456
	s_add_u32 s98, s4, 0x80
	s_addc_u32 s99, s5, 0
	s_mov_b32 m0, s43
	s_nop 0
	global_load_lds_dwordx4 v172, s[4:5]
	s_add_i32 m0, s43, 0x2000
	s_nop 0
	global_load_lds_dwordx4 v168, s[4:5]
	s_mov_b32 m0, s28
	s_add_u32 s100, s6, 0x80
	s_addc_u32 s101, s7, 0
	s_waitcnt lgkmcnt(2)
	s_setprio 1
	s_barrier
	v_mfma_f32_16x16x32_bf16 v[96:99], v[216:219], v[148:151], v[96:99]
	v_mfma_f32_16x16x32_bf16 v[96:99], v[220:223], v[152:155], v[96:99]
	s_waitcnt lgkmcnt(0)
	v_mfma_f32_16x16x32_bf16 v[88:91], v[216:219], v[156:159], v[88:91]
	v_mfma_f32_16x16x32_bf16 v[88:91], v[220:223], v[160:163], v[88:91]
	v_mfma_f32_16x16x32_bf16 v[80:83], v[216:219], v[182:185], v[80:83]
	v_mfma_f32_16x16x32_bf16 v[80:83], v[220:223], v[190:193], v[80:83]
	v_mfma_f32_16x16x32_bf16 v[72:75], v[216:219], v[194:197], v[72:75]
	v_mfma_f32_16x16x32_bf16 v[72:75], v[220:223], v[212:215], v[72:75]
	v_mfma_f32_16x16x32_bf16 v[92:95], v[224:227], v[148:151], v[92:95]
	v_mfma_f32_16x16x32_bf16 v[92:95], v[228:231], v[152:155], v[92:95]
	v_mfma_f32_16x16x32_bf16 v[84:87], v[224:227], v[156:159], v[84:87]
	v_mfma_f32_16x16x32_bf16 v[84:87], v[228:231], v[160:163], v[84:87]
	v_mfma_f32_16x16x32_bf16 v[76:79], v[224:227], v[182:185], v[76:79]
	v_mfma_f32_16x16x32_bf16 v[76:79], v[228:231], v[190:193], v[76:79]
	v_mfma_f32_16x16x32_bf16 v[68:71], v[224:227], v[194:197], v[68:71]
	v_mfma_f32_16x16x32_bf16 v[68:71], v[228:231], v[212:215], v[68:71]
	s_barrier
	s_setprio 0
	ds_read_b128 v[148:151], v188 offset:16384
	ds_read_b128 v[152:155], v188 offset:17408
	ds_read_b128 v[156:159], v188 offset:18432
	ds_read_b128 v[160:163], v188 offset:19456
	ds_read_b128 v[182:185], v188 offset:20480
	ds_read_b128 v[190:193], v188 offset:21504
	ds_read_b128 v[194:197], v188 offset:22528
	ds_read_b128 v[212:215], v188 offset:23552
	global_load_lds_dwordx4 v174, s[6:7]
	s_mov_b32 m0, s29
	s_nop 0
	global_load_lds_dwordx4 v170, s[6:7]
	s_waitcnt lgkmcnt(6)
	s_setprio 1
	s_barrier
	v_mfma_f32_16x16x32_bf16 v[64:67], v[132:135], v[148:151], v[64:67]
	v_mfma_f32_16x16x32_bf16 v[64:67], v[136:139], v[152:155], v[64:67]
	s_waitcnt lgkmcnt(0)
	v_mfma_f32_16x16x32_bf16 v[56:59], v[132:135], v[156:159], v[56:59]
	v_mfma_f32_16x16x32_bf16 v[56:59], v[136:139], v[160:163], v[56:59]
	v_mfma_f32_16x16x32_bf16 v[48:51], v[132:135], v[182:185], v[48:51]
	v_mfma_f32_16x16x32_bf16 v[48:51], v[136:139], v[190:193], v[48:51]
	v_mfma_f32_16x16x32_bf16 v[40:43], v[132:135], v[194:197], v[40:43]
	v_mfma_f32_16x16x32_bf16 v[40:43], v[136:139], v[212:215], v[40:43]
	v_mfma_f32_16x16x32_bf16 v[60:63], v[140:143], v[148:151], v[60:63]
	v_mfma_f32_16x16x32_bf16 v[60:63], v[144:147], v[152:155], v[60:63]
	v_mfma_f32_16x16x32_bf16 v[52:55], v[140:143], v[156:159], v[52:55]
	v_mfma_f32_16x16x32_bf16 v[52:55], v[144:147], v[160:163], v[52:55]
	v_mfma_f32_16x16x32_bf16 v[44:47], v[140:143], v[182:185], v[44:47]
	v_mfma_f32_16x16x32_bf16 v[44:47], v[144:147], v[190:193], v[44:47]
	v_mfma_f32_16x16x32_bf16 v[36:39], v[140:143], v[194:197], v[36:39]
	v_mfma_f32_16x16x32_bf16 v[36:39], v[144:147], v[212:215], v[36:39]
	s_barrier
	s_setprio 0
	s_add_u32 s44, s4, 0x80000
	s_addc_u32 s45, s5, 0
	s_add_i32 s43, s46, s27
	s_mov_b32 m0, s43
	s_nop 0
	global_load_lds_dwordx4 v172, s[44:45]
	s_add_i32 m0, s43, 0x2000
	s_nop 0
	global_load_lds_dwordx4 v168, s[44:45]
	s_add_i32 s43, 0, 0x18000
	s_waitcnt vmcnt(6)
	s_setprio 1
	s_barrier
; #define PG8_WAIT_V(n) asm volatile("s_waitcnt vmcnt(" #n ")" ::: "memory")
; #define PG8_WAIT_L(n) asm volatile("s_waitcnt lgkmcnt(" #n ")" ::: "memory")
; #define PG8_BAR __builtin_amdgcn_s_barrier()
; #define PG8_SCHED __builtin_amdgcn_sched_barrier(0)
; template <class Epi, class AddrA, class AddrB>
; __device__ __forceinline__ void gemm_phase(const Sched S, const int lda, const int ldb, const int K, const AddrA addrA,
;                                            const AddrB addrB, const Epi E) {
;     ...
;       PG8_BAR; PG8_WAIT_L(0); PG8_MMA(1, 0, At, B0); PG8_BAR; PG8_SCHED;
;       PG8_STAGE(PG8_SB(0, 1), b2 + hstepB, voffB);
;       PG8_WAIT_V(6); PG8_BAR; PG8_MMA(1, 1, At, B1); PG8_BAR;
;       PG8_LDB(B0, 1, 0); PG8_SCHED; PG8_LDA(At, 1, 0); PG8_STAGE(PG8_SA(0, 1), a2 + hstepA, voffA);
;       PG8_WAIT_L(8); PG8_BAR; PG8_WAIT_L(0); PG8_MMA(0, 0, At, B0); PG8_BAR; PG8_SCHED;
;       PG8_LDB(B1, 1, 1); PG8_STAGE(PG8_SB(1, 0), b3, voffB);
;       PG8_BAR; PG8_WAIT_L(0); PG8_MMA(0, 1, At, B1); PG8_BAR;
;       PG8_LDA(At, 1, 1); PG8_STAGE(PG8_SA(1, 0), a3, voffA);
;       PG8_BAR; PG8_WAIT_L(0); PG8_MMA(1, 0, At, B0); PG8_BAR; PG8_SCHED;
	v_mfma_f32_16x16x32_bf16 v[32:35], v[216:219], v[148:151], v[32:35]
	v_mfma_f32_16x16x32_bf16 v[32:35], v[220:223], v[152:155], v[32:35]
	v_mfma_f32_16x16x32_bf16 v[24:27], v[216:219], v[156:159], v[24:27]
	v_mfma_f32_16x16x32_bf16 v[24:27], v[220:223], v[160:163], v[24:27]
	v_mfma_f32_16x16x32_bf16 v[16:19], v[216:219], v[182:185], v[16:19]
	v_mfma_f32_16x16x32_bf16 v[16:19], v[220:223], v[190:193], v[16:19]
	v_mfma_f32_16x16x32_bf16 v[8:11], v[216:219], v[194:197], v[8:11]
	v_mfma_f32_16x16x32_bf16 v[8:11], v[220:223], v[212:215], v[8:11]
	v_mfma_f32_16x16x32_bf16 v[28:31], v[224:227], v[148:151], v[28:31]
	v_mfma_f32_16x16x32_bf16 v[28:31], v[228:231], v[152:155], v[28:31]
	v_mfma_f32_16x16x32_bf16 v[20:23], v[224:227], v[156:159], v[20:23]
	v_mfma_f32_16x16x32_bf16 v[20:23], v[228:231], v[160:163], v[20:23]
	v_mfma_f32_16x16x32_bf16 v[12:15], v[224:227], v[182:185], v[12:15]
	v_mfma_f32_16x16x32_bf16 v[12:15], v[228:231], v[190:193], v[12:15]
	v_mfma_f32_16x16x32_bf16 v[4:7], v[224:227], v[194:197], v[4:7]
	v_mfma_f32_16x16x32_bf16 v[4:7], v[228:231], v[212:215], v[4:7]
	s_barrier
	s_setprio 0
	ds_read_b128 v[132:135], v246 offset:32768
	ds_read_b128 v[136:139], v246 offset:33792
	ds_read_b128 v[140:143], v246 offset:34816
	ds_read_b128 v[144:147], v246 offset:35840
	s_add_u32 s6, s6, 0x80000
	s_addc_u32 s7, s7, 0
	s_mov_b32 m0, s30
	ds_read_b128 v[148:151], v188 offset:32768
	ds_read_b128 v[152:155], v188 offset:33792
	ds_read_b128 v[156:159], v188 offset:34816
	ds_read_b128 v[160:163], v188 offset:35840
	ds_read_b128 v[182:185], v188 offset:36864
	ds_read_b128 v[190:193], v188 offset:37888
	ds_read_b128 v[194:197], v188 offset:38912
	ds_read_b128 v[212:215], v188 offset:39936
	global_load_lds_dwordx4 v174, s[6:7]
	s_mov_b32 m0, s31
	s_nop 0
	global_load_lds_dwordx4 v170, s[6:7]
	s_waitcnt lgkmcnt(6)
	s_setprio 1
	s_barrier
	v_mfma_f32_16x16x32_bf16 v[128:131], v[132:135], v[148:151], v[128:131]
	v_mfma_f32_16x16x32_bf16 v[128:131], v[136:139], v[152:155], v[128:131]
	s_waitcnt lgkmcnt(0)
	v_mfma_f32_16x16x32_bf16 v[120:123], v[132:135], v[156:159], v[120:123]
	v_mfma_f32_16x16x32_bf16 v[120:123], v[136:139], v[160:163], v[120:123]
	v_mfma_f32_16x16x32_bf16 v[112:115], v[132:135], v[182:185], v[112:115]
	v_mfma_f32_16x16x32_bf16 v[112:115], v[136:139], v[190:193], v[112:115]
	v_mfma_f32_16x16x32_bf16 v[104:107], v[132:135], v[194:197], v[104:107]
	v_mfma_f32_16x16x32_bf16 v[104:107], v[136:139], v[212:215], v[104:107]
	v_mfma_f32_16x16x32_bf16 v[124:127], v[140:143], v[148:151], v[124:127]
	v_mfma_f32_16x16x32_bf16 v[124:127], v[144:147], v[152:155], v[124:127]
	v_mfma_f32_16x16x32_bf16 v[116:119], v[140:143], v[156:159], v[116:119]
	v_mfma_f32_16x16x32_bf16 v[116:119], v[144:147], v[160:163], v[116:119]
	v_mfma_f32_16x16x32_bf16 v[108:111], v[140:143], v[182:185], v[108:111]
	v_mfma_f32_16x16x32_bf16 v[108:111], v[144:147], v[190:193], v[108:111]
	v_mfma_f32_16x16x32_bf16 v[100:103], v[140:143], v[194:197], v[100:103]
	v_mfma_f32_16x16x32_bf16 v[100:103], v[144:147], v[212:215], v[100:103]
	s_barrier
	s_setprio 0
	s_add_i32 s6, 0, 0x1c000
	s_add_i32 s7, s43, s27
	s_mov_b32 m0, s7
	ds_read_b128 v[216:219], v246 offset:49152
	ds_read_b128 v[220:223], v246 offset:50176
	ds_read_b128 v[224:227], v246 offset:51200
	ds_read_b128 v[228:231], v246 offset:52224
	global_load_lds_dwordx4 v172, s[98:99]
	s_add_i32 m0, s7, 0x2000
	s_nop 0
	global_load_lds_dwordx4 v168, s[98:99]
	s_mov_b32 m0, s38
	s_waitcnt lgkmcnt(2)
	s_setprio 1
	s_barrier
	v_mfma_f32_16x16x32_bf16 v[96:99], v[216:219], v[148:151], v[96:99]
	v_mfma_f32_16x16x32_bf16 v[96:99], v[220:223], v[152:155], v[96:99]
	s_waitcnt lgkmcnt(0)
	v_mfma_f32_16x16x32_bf16 v[88:91], v[216:219], v[156:159], v[88:91]
	v_mfma_f32_16x16x32_bf16 v[88:91], v[220:223], v[160:163], v[88:91]
	v_mfma_f32_16x16x32_bf16 v[80:83], v[216:219], v[182:185], v[80:83]
	v_mfma_f32_16x16x32_bf16 v[80:83], v[220:223], v[190:193], v[80:83]
	v_mfma_f32_16x16x32_bf16 v[72:75], v[216:219], v[194:197], v[72:75]
	v_mfma_f32_16x16x32_bf16 v[72:75], v[220:223], v[212:215], v[72:75]
	v_mfma_f32_16x16x32_bf16 v[92:95], v[224:227], v[148:151], v[92:95]
	v_mfma_f32_16x16x32_bf16 v[92:95], v[228:231], v[152:155], v[92:95]
	v_mfma_f32_16x16x32_bf16 v[84:87], v[224:227], v[156:159], v[84:87]
	v_mfma_f32_16x16x32_bf16 v[84:87], v[228:231], v[160:163], v[84:87]
	v_mfma_f32_16x16x32_bf16 v[76:79], v[224:227], v[182:185], v[76:79]
	v_mfma_f32_16x16x32_bf16 v[76:79], v[228:231], v[190:193], v[76:79]
	v_mfma_f32_16x16x32_bf16 v[68:71], v[224:227], v[194:197], v[68:71]
	v_mfma_f32_16x16x32_bf16 v[68:71], v[228:231], v[212:215], v[68:71]
	s_barrier
	s_setprio 0
	ds_read_b128 v[148:151], v188 offset:49152
	ds_read_b128 v[152:155], v188 offset:50176
	ds_read_b128 v[156:159], v188 offset:51200
	ds_read_b128 v[160:163], v188 offset:52224
	ds_read_b128 v[182:185], v188 offset:53248
	ds_read_b128 v[190:193], v188 offset:54272
	ds_read_b128 v[194:197], v188 offset:55296
	ds_read_b128 v[212:215], v188 offset:56320
	global_load_lds_dwordx4 v174, s[100:101]
	s_mov_b32 m0, s39
	s_nop 0
	global_load_lds_dwordx4 v170, s[100:101]
	s_waitcnt lgkmcnt(6)
	s_setprio 1
	s_barrier
; #define PG8_WAIT_V(n) asm volatile("s_waitcnt vmcnt(" #n ")" ::: "memory")
; template <class Epi, class AddrA, class AddrB>
; __device__ __forceinline__ void gemm_phase(const Sched S, const int lda, const int ldb, const int K, const AddrA addrA,
;                                            const AddrB addrB, const Epi E) {
;     ...
;       PG8_BAR; PG8_WAIT_L(0); PG8_MMA(0, 1, At, B1); PG8_BAR;
;       PG8_LDA(At, 1, 1); PG8_STAGE(PG8_SA(1, 0), a3, voffA);
;       PG8_BAR; PG8_WAIT_L(0); PG8_MMA(1, 0, At, B0); PG8_BAR; PG8_SCHED;
;       PG8_STAGE(PG8_SB(1, 1), b3 + hstepB, voffB);
;       PG8_WAIT_V(6); PG8_BAR; PG8_MMA(1, 1, At, B1); PG8_BAR;
;   __device__ __forceinline__ void operator()(EPI_ARGS) const {
;     const int col0 = u.pn * 256 + wc * 32 + 8 * fq;
;     const int br = u.br, brn = br < 2 ? br + 1 : 2;
;     const unsigned loff0 = (unsigned)((wr * 64 + fr) * PLD + wc * 32 + 8 * fq);
;     const bf16_t* pc = proj + ((size_t)((GT + br * DM) / 256 + u.pn) * MTOK + (size_t)u.pm * 256) * PLD;
;     const bf16_t* pn_ = proj + ((size_t)((GT + brn * DM) / 256 + u.pn) * MTOK + (size_t)u.pm * 256) * PLD;
;     bf16_t* mrow = merged + ((size_t)u.pm * 256 + wr * 64 + fr) * DM + col0;
; #pragma unroll
;     for (int bj = 0; bj < 2; ++bj) {
;       const int c = col0 + bj * HALF;
;       float gc[8], gn[8];
;       {
;         const f32x4 a0 = *(const f32x4*)(bg + br * DM + c), a1 = *(const f32x4*)(bg + br * DM + c + 4);
;         const f32x4 b0 = *(const f32x4*)(bg + brn * DM + c), b1 = *(const f32x4*)(bg + brn * DM + c + 4);
; #pragma unroll
;         for (int k = 0; k < 4; ++k) { gc[k] = a0[k]; gc[4 + k] = a1[k]; gn[k] = b0[k]; gn[4 + k] = b1[k]; }
;       }
; #pragma unroll
;       for (int ai = 0; ai < 2; ++ai) {
;         unsigned loff = loff0;
;         asm volatile("" : "+v"(loff));
;         u32x4 zc[4], zn[4];
; #pragma unroll
;         for (int m = 0; m < 4; ++m) {
;           const unsigned o = loff + (unsigned)((ai * HALF + m * 16) * PLD + bj * HALF);
;           zc[m] = *(const u32x4*)(pc + o);
;           zn[m] = *(const u32x4*)(pn_ + o);
;         }
;         __builtin_amdgcn_sched_barrier(0);
;         if (br < 2) {
; #pragma unroll
;           for (int m = 0; m < 4; ++m) {
;             float xc[8], xn[8];
;             unpack8(zc[m], xc);
;             unpack8(zn[m], xn);
; #pragma unroll
;             for (int k = 0; k < 8; ++k) {
	v_mfma_f32_16x16x32_bf16 v[64:67], v[132:135], v[148:151], v[64:67]
	v_mfma_f32_16x16x32_bf16 v[64:67], v[136:139], v[152:155], v[64:67]
	s_waitcnt lgkmcnt(0)
	v_mfma_f32_16x16x32_bf16 v[56:59], v[132:135], v[156:159], v[56:59]
	v_mfma_f32_16x16x32_bf16 v[56:59], v[136:139], v[160:163], v[56:59]
	v_mfma_f32_16x16x32_bf16 v[48:51], v[132:135], v[182:185], v[48:51]
	v_mfma_f32_16x16x32_bf16 v[48:51], v[136:139], v[190:193], v[48:51]
	v_mfma_f32_16x16x32_bf16 v[40:43], v[132:135], v[194:197], v[40:43]
	v_mfma_f32_16x16x32_bf16 v[40:43], v[136:139], v[212:215], v[40:43]
	v_mfma_f32_16x16x32_bf16 v[60:63], v[140:143], v[148:151], v[60:63]
	v_mfma_f32_16x16x32_bf16 v[60:63], v[144:147], v[152:155], v[60:63]
	v_mfma_f32_16x16x32_bf16 v[52:55], v[140:143], v[156:159], v[52:55]
	v_mfma_f32_16x16x32_bf16 v[52:55], v[144:147], v[160:163], v[52:55]
	v_mfma_f32_16x16x32_bf16 v[44:47], v[140:143], v[182:185], v[44:47]
	v_mfma_f32_16x16x32_bf16 v[44:47], v[144:147], v[190:193], v[44:47]
	v_mfma_f32_16x16x32_bf16 v[36:39], v[140:143], v[194:197], v[36:39]
	v_mfma_f32_16x16x32_bf16 v[36:39], v[144:147], v[212:215], v[36:39]
	s_barrier
	s_setprio 0
	s_add_u32 s4, s4, 0x80080
	s_addc_u32 s5, s5, 0
	s_add_i32 s6, s6, s27
	s_mov_b32 m0, s6
	s_nop 0
	global_load_lds_dwordx4 v172, s[4:5]
	s_add_i32 m0, s6, 0x2000
	s_nop 0
	global_load_lds_dwordx4 v168, s[4:5]
	s_add_i32 s42, s42, 2
	s_add_u32 s33, s33, 0x100
	s_addc_u32 s41, s41, 0
	s_add_u32 s2, s2, 0x100
	s_addc_u32 s3, s3, 0
	s_waitcnt vmcnt(6)
	s_setprio 1
	s_barrier
	v_mfma_f32_16x16x32_bf16 v[32:35], v[216:219], v[148:151], v[32:35]
	v_mfma_f32_16x16x32_bf16 v[32:35], v[220:223], v[152:155], v[32:35]
	v_mfma_f32_16x16x32_bf16 v[24:27], v[216:219], v[156:159], v[24:27]
	v_mfma_f32_16x16x32_bf16 v[24:27], v[220:223], v[160:163], v[24:27]
	v_mfma_f32_16x16x32_bf16 v[16:19], v[216:219], v[182:185], v[16:19]
	v_mfma_f32_16x16x32_bf16 v[16:19], v[220:223], v[190:193], v[16:19]
	v_mfma_f32_16x16x32_bf16 v[8:11], v[216:219], v[194:197], v[8:11]
	v_mfma_f32_16x16x32_bf16 v[8:11], v[220:223], v[212:215], v[8:11]
	v_mfma_f32_16x16x32_bf16 v[28:31], v[224:227], v[148:151], v[28:31]
	v_mfma_f32_16x16x32_bf16 v[28:31], v[228:231], v[152:155], v[28:31]
	v_mfma_f32_16x16x32_bf16 v[20:23], v[224:227], v[156:159], v[20:23]
	v_mfma_f32_16x16x32_bf16 v[20:23], v[228:231], v[160:163], v[20:23]
	v_mfma_f32_16x16x32_bf16 v[12:15], v[224:227], v[182:185], v[12:15]
	v_mfma_f32_16x16x32_bf16 v[12:15], v[228:231], v[190:193], v[12:15]
	v_mfma_f32_16x16x32_bf16 v[4:7], v[224:227], v[194:197], v[4:7]
	v_mfma_f32_16x16x32_bf16 v[4:7], v[228:231], v[212:215], v[4:7]
	s_barrier
	s_setprio 0
	s_cmp_gt_u32 s42, 29
	s_cbranch_scc0 .LBB0_543
	s_cmp_gt_i32 s10, 1
	s_cselect_b64 s[6:7], -1, 0
	s_lshl_b32 s42, s10, 11
	s_add_i32 s2, s42, 0x4c00
	s_ashr_i32 s2, s2, 8
	s_add_i32 s2, s2, s11
	s_ashr_i32 s3, s2, 31
	s_min_i32 s1, s10, 1
	s_ashr_i32 s9, s8, 31
	s_lshl_b64 s[2:3], s[2:3], 23
	s_add_u32 s2, s34, s2
	s_addc_u32 s3, s35, s3
	s_lshl_b64 s[4:5], s[8:9], 17
	s_add_u32 s2, s2, s4
	s_addc_u32 s3, s3, s5
	s_lshl_b32 s1, s1, 11
	s_add_i32 s44, s1, 0x800
	s_addk_i32 s1, 0x5400
	s_ashr_i32 s1, s1, 8
	s_add_i32 s46, s1, s11
	s_ashr_i32 s47, s46, 31
	s_lshl_b64 s[46:47], s[46:47], 23
	s_add_u32 s1, s34, s46
	v_lshl_or_b32 v132, s11, 8, v187
	s_addc_u32 s11, s35, s47
	s_add_u32 s4, s1, s4
	s_addc_u32 s5, s11, s5
	s_ashr_i32 s43, s42, 31
	s_lshl_b64 s[8:9], s[8:9], 20
	s_ashr_i32 s45, s44, 31
	s_lshl_b64 s[42:43], s[42:43], 2
	s_add_u32 s42, s36, s42
	s_addc_u32 s43, s37, s43
	s_lshl_b64 s[44:45], s[44:45], 2
	s_add_u32 s44, s36, s44
	v_lshl_add_u64 v[0:1], v[176:177], 0, s[8:9]
	v_ashrrev_i32_e32 v133, 31, v132
	s_addc_u32 s45, s37, s45
	v_lshl_add_u64 v[0:1], v[132:133], 1, v[0:1]
	v_lshlrev_b64 v[132:133], 2, v[132:133]
	v_lshl_add_u64 v[182:183], s[42:43], 0, v[132:133]
	v_lshl_add_u64 v[184:185], s[44:45], 0, v[132:133]
	v_mov_b32_e32 v2, v186
	global_load_dwordx4 v[144:147], v[182:183], off
	global_load_dwordx4 v[136:139], v[182:183], off offset:16
	global_load_dwordx4 v[140:143], v[184:185], off
	global_load_dwordx4 v[132:135], v[184:185], off offset:16
	s_cmp_lt_i32 s10, 2
	v_lshlrev_b64 v[148:149], 1, v[2:3]
	v_lshl_add_u64 v[150:151], s[2:3], 0, v[148:149]
	v_lshl_add_u64 v[148:149], s[4:5], 0, v[148:149]
	flat_load_dwordx4 v[190:193], v[150:151]
	flat_load_dwordx4 v[160:163], v[148:149]
	v_add_u32_e32 v148, 0x1000, v2
	v_mov_b32_e32 v149, v3
	v_lshlrev_b64 v[148:149], 1, v[148:149]
	v_lshl_add_u64 v[150:151], s[2:3], 0, v[148:149]
	v_lshl_add_u64 v[148:149], s[4:5], 0, v[148:149]
	flat_load_dwordx4 v[194:197], v[150:151]
	flat_load_dwordx4 v[156:159], v[148:149]
	v_add_u32_e32 v148, 0x2000, v2
	v_mov_b32_e32 v149, v3
	v_lshlrev_b64 v[148:149], 1, v[148:149]
	v_lshl_add_u64 v[150:151], s[2:3], 0, v[148:149]
	v_lshl_add_u64 v[148:149], s[4:5], 0, v[148:149]
	v_add_u32_e32 v2, 0x3000, v2
	flat_load_dwordx4 v[234:237], v[150:151]
	flat_load_dwordx4 v[152:155], v[148:149]
	v_lshlrev_b64 v[148:149], 1, v[2:3]
	v_lshl_add_u64 v[150:151], s[2:3], 0, v[148:149]
	v_lshl_add_u64 v[148:149], s[4:5], 0, v[148:149]
	flat_load_dwordx4 v[238:241], v[150:151]
	s_nop 0
	flat_load_dwordx4 v[148:151], v[148:149]
	s_waitcnt vmcnt(0) lgkmcnt(0)
	v_lshlrev_b32_e32 v2, 16, v190
	v_and_b32_e32 v189, 0xffff0000, v190
	v_lshlrev_b32_e32 v190, 16, v191
	v_and_b32_e32 v191, 0xffff0000, v191
	v_lshlrev_b32_e32 v212, 16, v192
	v_and_b32_e32 v192, 0xffff0000, v192
	v_lshlrev_b32_e32 v213, 16, v193
	v_and_b32_e32 v193, 0xffff0000, v193
	v_add_f32_e32 v2, v144, v2
	v_add_f32_e32 v189, v145, v189
	v_add_f32_e32 v190, v146, v190
	v_add_f32_e32 v191, v147, v191
	v_add_f32_e32 v212, v136, v212
	v_add_f32_e32 v192, v137, v192
	v_add_f32_e32 v213, v138, v213
	v_add_f32_e32 v193, v139, v193
	s_mov_b64 s[8:9], -1
	v_max_f32_e32 v233, 0xc2200000, v2
	v_max_f32_e32 v232, 0xc2200000, v189
	v_max_f32_e32 v231, 0xc2200000, v190
	v_max_f32_e32 v230, 0xc2200000, v191
	v_max_f32_e32 v229, 0xc2200000, v212
	v_max_f32_e32 v228, 0xc2200000, v192
	v_max_f32_e32 v227, 0xc2200000, v213
	v_max_f32_e32 v226, 0xc2200000, v193
	v_lshlrev_b32_e32 v225, 16, v194
	v_and_b32_e32 v224, 0xffff0000, v194
	v_lshlrev_b32_e32 v223, 16, v195
	v_and_b32_e32 v222, 0xffff0000, v195
	v_lshlrev_b32_e32 v221, 16, v196
	v_and_b32_e32 v220, 0xffff0000, v196
	v_lshlrev_b32_e32 v219, 16, v197
	v_and_b32_e32 v218, 0xffff0000, v197
	v_lshlrev_b32_e32 v217, 16, v234
	v_and_b32_e32 v216, 0xffff0000, v234
	v_lshlrev_b32_e32 v215, 16, v235
	v_and_b32_e32 v214, 0xffff0000, v235
	v_lshlrev_b32_e32 v213, 16, v236
	v_and_b32_e32 v212, 0xffff0000, v236
	v_lshlrev_b32_e32 v197, 16, v237
	v_and_b32_e32 v196, 0xffff0000, v237
	v_lshlrev_b32_e32 v195, 16, v238
	v_and_b32_e32 v194, 0xffff0000, v238
	v_lshlrev_b32_e32 v193, 16, v239
	v_and_b32_e32 v192, 0xffff0000, v239
	v_lshlrev_b32_e32 v191, 16, v240
	v_and_b32_e32 v190, 0xffff0000, v240
	v_lshlrev_b32_e32 v189, 16, v241
	v_and_b32_e32 v2, 0xffff0000, v241
	s_cbranch_scc1 .LBB0_546
; __device__ __forceinline__ float sigmoidf_(float x) { return __builtin_amdgcn_rcpf(1.0f + __expf(-x)); }
;   __device__ __forceinline__ void operator()(EPI_ARGS) const {
;     ...
; #pragma unroll
;           for (int m = 0; m < 4; ++m) {
;             float xc[8], y[8];
;             unpack8(zc[m], xc);
; #pragma unroll
;             for (int k = 0; k < 8; ++k) y[k] = acc[ai][bj][m][k >> 2][k & 3] * sigmoidf_(fmaxf(xc[k] + gc[k], -40.f));
;             u32x4 o;
;             o.x = pack2(y[0], y[1]); o.y = pack2(y[2], y[3]); o.z = pack2(y[4], y[5]); o.w = pack2(y[6], y[7]);
;             *(u32x4*)(mrow + (size_t)(ai * HALF + m * 16) * DM + bj * HALF) = o;
;           }
	v_mul_f32_e32 v234, 0xbfb8aa3b, v233
	v_mul_f32_e32 v235, 0xbfb8aa3b, v232
	v_mul_f32_e32 v236, 0xbfb8aa3b, v231
	v_exp_f32_e32 v234, v234
	v_exp_f32_e32 v235, v235
	v_exp_f32_e32 v236, v236
	v_mul_f32_e32 v237, 0xbfb8aa3b, v230
	v_exp_f32_e32 v237, v237
	v_mul_f32_e32 v238, 0xbfb8aa3b, v229
	v_mul_f32_e32 v239, 0xbfb8aa3b, v228
	v_add_f32_e32 v234, 1.0, v234
	v_add_f32_e32 v235, 1.0, v235
	v_add_f32_e32 v236, 1.0, v236
	v_exp_f32_e32 v238, v238
	v_exp_f32_e32 v239, v239
	v_mul_f32_e32 v240, 0xbfb8aa3b, v227
	v_mul_f32_e32 v241, 0xbfb8aa3b, v226
	v_rcp_f32_e32 v234, v234
	v_rcp_f32_e32 v235, v235
	v_rcp_f32_e32 v236, v236
	v_add_f32_e32 v237, 1.0, v237
	v_exp_f32_e32 v240, v240
	v_exp_f32_e32 v241, v241
	v_rcp_f32_e32 v237, v237
	v_add_f32_e32 v238, 1.0, v238
	v_add_f32_e32 v239, 1.0, v239
	v_mul_f32_e32 v234, v128, v234
	v_mul_f32_e32 v235, v129, v235
	v_mul_f32_e32 v236, v130, v236
	v_rcp_f32_e32 v238, v238
	v_rcp_f32_e32 v239, v239
	v_add_f32_e32 v240, 1.0, v240
	v_add_f32_e32 v241, 1.0, v241
	v_mul_f32_e32 v237, v131, v237
	v_rcp_f32_e32 v240, v240
	v_rcp_f32_e32 v241, v241
	v_cvt_pk_bf16_f32 v234, v234, v235
	v_cvt_pk_bf16_f32 v235, v236, v237
	v_add_f32_e32 v236, v144, v225
	v_max_f32_e32 v236, 0xc2200000, v236
	v_mul_f32_e32 v236, 0xbfb8aa3b, v236
	v_mul_f32_e32 v238, v124, v238
	v_mul_f32_e32 v239, v125, v239
	v_exp_f32_e32 v242, v236
	v_cvt_pk_bf16_f32 v236, v238, v239
	v_mul_f32_e32 v240, v126, v240
	v_mul_f32_e32 v241, v127, v241
	v_cvt_pk_bf16_f32 v237, v240, v241
	flat_store_dwordx4 v[0:1], v[234:237]
	v_add_f32_e32 v238, v136, v221
	v_max_f32_e32 v238, 0xc2200000, v238
	v_add_f32_e32 v235, v145, v224
	v_add_f32_e32 v236, v146, v223
	v_max_f32_e32 v235, 0xc2200000, v235
	v_max_f32_e32 v236, 0xc2200000, v236
	v_add_f32_e32 v237, v147, v222
	v_add_f32_e32 v239, v137, v220
	v_mul_f32_e32 v235, 0xbfb8aa3b, v235
	v_mul_f32_e32 v236, 0xbfb8aa3b, v236
	v_max_f32_e32 v237, 0xc2200000, v237
	v_mul_f32_e32 v238, 0xbfb8aa3b, v238
	v_max_f32_e32 v239, 0xc2200000, v239
	v_exp_f32_e32 v235, v235
	v_exp_f32_e32 v236, v236
	v_mul_f32_e32 v237, 0xbfb8aa3b, v237
	v_exp_f32_e32 v238, v238
	v_mul_f32_e32 v239, 0xbfb8aa3b, v239
	v_add_f32_e32 v240, v138, v219
	v_exp_f32_e32 v237, v237
	v_exp_f32_e32 v239, v239
	v_max_f32_e32 v240, 0xc2200000, v240
	v_add_f32_e32 v241, v139, v218
	v_mul_f32_e32 v240, 0xbfb8aa3b, v240
	v_max_f32_e32 v241, 0xc2200000, v241
	v_exp_f32_e32 v240, v240
	v_mul_f32_e32 v241, 0xbfb8aa3b, v241
	v_add_f32_e32 v234, 1.0, v242
	v_add_f32_e32 v235, 1.0, v235
	v_add_f32_e32 v236, 1.0, v236
	v_add_f32_e32 v238, 1.0, v238
	v_exp_f32_e32 v241, v241
	v_rcp_f32_e32 v234, v234
	v_rcp_f32_e32 v235, v235
	v_rcp_f32_e32 v236, v236
	v_add_f32_e32 v237, 1.0, v237
	v_rcp_f32_e32 v238, v238
	v_add_f32_e32 v239, 1.0, v239
	v_rcp_f32_e32 v237, v237
	v_rcp_f32_e32 v239, v239
	v_add_f32_e32 v240, 1.0, v240
	v_rcp_f32_e32 v240, v240
	v_add_f32_e32 v241, 1.0, v241
	v_mul_f32_e32 v234, v120, v234
	v_mul_f32_e32 v235, v121, v235
	v_mul_f32_e32 v236, v122, v236
	v_rcp_f32_e32 v241, v241
	v_mul_f32_e32 v238, v116, v238
	v_mul_f32_e32 v237, v123, v237
	v_mul_f32_e32 v239, v117, v239
	v_cvt_pk_bf16_f32 v234, v234, v235
	v_cvt_pk_bf16_f32 v235, v236, v237
	v_cvt_pk_bf16_f32 v236, v238, v239
	v_add_f32_e32 v238, v144, v217
	v_max_f32_e32 v238, 0xc2200000, v238
	v_mul_f32_e32 v240, v118, v240
	v_mul_f32_e32 v238, 0xbfb8aa3b, v238
	v_mul_f32_e32 v241, v119, v241
	v_cvt_pk_bf16_f32 v237, v240, v241
	v_exp_f32_e32 v240, v238
	v_add_co_u32_e32 v238, vcc, s67, v0
	v_add_f32_e32 v241, v139, v196
	s_nop 0
	v_addc_co_u32_e32 v239, vcc, 0, v1, vcc
	flat_store_dwordx4 v[238:239], v[234:237]
	v_add_f32_e32 v238, v136, v213
	v_max_f32_e32 v238, 0xc2200000, v238
	v_add_f32_e32 v235, v145, v216
	v_add_f32_e32 v236, v146, v215
	v_max_f32_e32 v235, 0xc2200000, v235
; __device__ __forceinline__ float sigmoidf_(float x) { return __builtin_amdgcn_rcpf(1.0f + __expf(-x)); }
;   __device__ __forceinline__ void operator()(EPI_ARGS) const {
;     ...
; #pragma unroll
;           for (int m = 0; m < 4; ++m) {
;             float xc[8], y[8];
;             unpack8(zc[m], xc);
; #pragma unroll
;             for (int k = 0; k < 8; ++k) y[k] = acc[ai][bj][m][k >> 2][k & 3] * sigmoidf_(fmaxf(xc[k] + gc[k], -40.f));
;             u32x4 o;
;             o.x = pack2(y[0], y[1]); o.y = pack2(y[2], y[3]); o.z = pack2(y[4], y[5]); o.w = pack2(y[6], y[7]);
;             *(u32x4*)(mrow + (size_t)(ai * HALF + m * 16) * DM + bj * HALF) = o;
;           }
	v_max_f32_e32 v236, 0xc2200000, v236
	v_add_f32_e32 v237, v147, v214
	v_add_f32_e32 v239, v137, v212
	v_mul_f32_e32 v235, 0xbfb8aa3b, v235
	v_mul_f32_e32 v236, 0xbfb8aa3b, v236
	v_max_f32_e32 v237, 0xc2200000, v237
	v_mul_f32_e32 v238, 0xbfb8aa3b, v238
	v_max_f32_e32 v239, 0xc2200000, v239
	v_add_f32_e32 v234, 1.0, v240
	v_exp_f32_e32 v235, v235
	v_exp_f32_e32 v236, v236
	v_mul_f32_e32 v237, 0xbfb8aa3b, v237
	v_exp_f32_e32 v238, v238
	v_mul_f32_e32 v239, 0xbfb8aa3b, v239
	v_add_f32_e32 v240, v138, v197
	v_exp_f32_e32 v237, v237
	v_exp_f32_e32 v239, v239
	v_max_f32_e32 v240, 0xc2200000, v240
	v_mul_f32_e32 v240, 0xbfb8aa3b, v240
	v_max_f32_e32 v241, 0xc2200000, v241
	v_exp_f32_e32 v240, v240
	v_mul_f32_e32 v241, 0xbfb8aa3b, v241
	v_add_f32_e32 v235, 1.0, v235
	v_add_f32_e32 v236, 1.0, v236
	v_add_f32_e32 v238, 1.0, v238
	v_exp_f32_e32 v241, v241
	v_rcp_f32_e32 v234, v234
	v_rcp_f32_e32 v235, v235
	v_rcp_f32_e32 v236, v236
	v_add_f32_e32 v237, 1.0, v237
	v_rcp_f32_e32 v238, v238
	v_add_f32_e32 v239, 1.0, v239
	v_rcp_f32_e32 v237, v237
	v_rcp_f32_e32 v239, v239
	v_add_f32_e32 v240, 1.0, v240
	v_rcp_f32_e32 v240, v240
	v_add_f32_e32 v241, 1.0, v241
	v_mul_f32_e32 v234, v112, v234
	v_mul_f32_e32 v235, v113, v235
	v_mul_f32_e32 v236, v114, v236
	v_rcp_f32_e32 v241, v241
	v_mul_f32_e32 v238, v108, v238
	v_mul_f32_e32 v237, v115, v237
	v_mul_f32_e32 v239, v109, v239
	v_cvt_pk_bf16_f32 v234, v234, v235
	v_cvt_pk_bf16_f32 v235, v236, v237
	v_cvt_pk_bf16_f32 v236, v238, v239
	v_add_f32_e32 v238, v144, v195
	v_max_f32_e32 v238, 0xc2200000, v238
	v_mul_f32_e32 v240, v110, v240
	v_mul_f32_e32 v238, 0xbfb8aa3b, v238
	s_mov_b32 s1, 0x20000
	v_mul_f32_e32 v241, v111, v241
	v_cvt_pk_bf16_f32 v237, v240, v241
	v_exp_f32_e32 v240, v238
	v_add_co_u32_e32 v238, vcc, s1, v0
	v_add_f32_e32 v241, v139, v2
	s_nop 0
	v_addc_co_u32_e32 v239, vcc, 0, v1, vcc
	flat_store_dwordx4 v[238:239], v[234:237]
	v_add_f32_e32 v238, v136, v191
	v_max_f32_e32 v238, 0xc2200000, v238
	v_add_f32_e32 v235, v145, v194
	v_add_f32_e32 v236, v146, v193
	v_max_f32_e32 v235, 0xc2200000, v235
	v_max_f32_e32 v236, 0xc2200000, v236
	v_add_f32_e32 v237, v147, v192
	v_add_f32_e32 v239, v137, v190
	v_mul_f32_e32 v235, 0xbfb8aa3b, v235
	v_mul_f32_e32 v236, 0xbfb8aa3b, v236
	v_max_f32_e32 v237, 0xc2200000, v237
	v_mul_f32_e32 v238, 0xbfb8aa3b, v238
	v_max_f32_e32 v239, 0xc2200000, v239
	v_add_f32_e32 v234, 1.0, v240
	v_exp_f32_e32 v235, v235
	v_exp_f32_e32 v236, v236
	v_mul_f32_e32 v237, 0xbfb8aa3b, v237
	v_exp_f32_e32 v238, v238
	v_mul_f32_e32 v239, 0xbfb8aa3b, v239
	v_add_f32_e32 v240, v138, v189
	v_exp_f32_e32 v237, v237
	v_exp_f32_e32 v239, v239
	v_max_f32_e32 v240, 0xc2200000, v240
	v_max_f32_e32 v241, 0xc2200000, v241
	v_mul_f32_e32 v240, 0xbfb8aa3b, v240
	v_mul_f32_e32 v241, 0xbfb8aa3b, v241
	v_exp_f32_e32 v240, v240
	v_exp_f32_e32 v241, v241
	v_add_f32_e32 v235, 1.0, v235
	v_add_f32_e32 v236, 1.0, v236
	v_add_f32_e32 v238, 1.0, v238
	v_rcp_f32_e32 v234, v234
	v_rcp_f32_e32 v235, v235
	v_rcp_f32_e32 v236, v236
	v_add_f32_e32 v237, 1.0, v237
	v_rcp_f32_e32 v238, v238
	v_add_f32_e32 v239, 1.0, v239
	v_rcp_f32_e32 v237, v237
	v_rcp_f32_e32 v239, v239
	v_add_f32_e32 v240, 1.0, v240
	v_add_f32_e32 v241, 1.0, v241
	v_rcp_f32_e32 v240, v240
	v_rcp_f32_e32 v241, v241
	v_mul_f32_e32 v234, v104, v234
	v_mul_f32_e32 v235, v105, v235
	v_mul_f32_e32 v236, v106, v236
	v_mul_f32_e32 v238, v100, v238
	v_mul_f32_e32 v237, v107, v237
	v_mul_f32_e32 v239, v101, v239
	v_cvt_pk_bf16_f32 v234, v234, v235
	v_cvt_pk_bf16_f32 v235, v236, v237
	v_cvt_pk_bf16_f32 v236, v238, v239
	v_add_co_u32_e32 v238, vcc, 0x30000, v0
	s_mov_b64 s[8:9], 0
	s_nop 0
	v_addc_co_u32_e32 v239, vcc, 0, v1, vcc
	v_mul_f32_e32 v240, v102, v240
	v_mul_f32_e32 v241, v103, v241
	v_cvt_pk_bf16_f32 v237, v240, v241
	flat_store_dwordx4 v[238:239], v[234:237]

; #define PG8_WAIT_L(n) asm volatile("s_waitcnt lgkmcnt(" #n ")" ::: "memory")
; #define PG8_BAR __builtin_amdgcn_s_barrier()
; #define PG8_SCHED __builtin_amdgcn_sched_barrier(0)
; template <class Epi, class AddrA, class AddrB>
; __device__ __forceinline__ void gemm_phase(const Sched S, const int lda, const int ldb, const int K, const AddrA addrA,
;                                            const AddrB addrB, const Epi E) {
;     ...
;     const bool has_next = S.next(ui + 1, nxt);
;     const char* nA = has_next ? addrA(nxt) : cA;
;     const char* nB = has_next ? addrB(nxt) : cB;
;     for (int t = 0; t < nt; t += 2) {
;       const bool last = (t == nt - 2);
;       const char* a1 = cA + (size_t)(t + 1) * kstep;
;       const char* a2 = last ? nA : cA + (size_t)(t + 2) * kstep;
;       const char* b2 = last ? nB : cB + (size_t)(t + 2) * kstep;
;       const char* a3 = a2 + kstep;
;       const char* b3 = b2 + kstep;
;       PG8_LDB(B0, 0, 0); PG8_SCHED; PG8_LDA(At, 0, 0); PG8_STAGE(PG8_SA(1, 1), a1 + hstepA, voffA);
;       PG8_WAIT_L(8); PG8_BAR; PG8_WAIT_L(0); PG8_MMA(0, 0, At, B0); PG8_BAR; PG8_SCHED;
;       PG8_LDB(B1, 0, 1); PG8_STAGE(PG8_SB(0, 0), b2, voffB);
;       PG8_BAR; PG8_WAIT_L(0); PG8_MMA(0, 1, At, B1); PG8_BAR;
;       PG8_LDA(At, 0, 1); PG8_STAGE(PG8_SA(0, 0), a2, voffA);
;       PG8_BAR; PG8_WAIT_L(0); PG8_MMA(1, 0, At, B0); PG8_BAR; PG8_SCHED;
.LBB0_618:
	s_ashr_i32 s3, s2, 31
	s_lshl_b64 s[8:9], s[2:3], 20
	s_add_u32 s8, s23, s8
	s_addc_u32 s9, s24, s9
	s_and_b64 s[10:11], s[18:19], exec
	s_cselect_b32 s3, s9, s17
	s_cselect_b32 s13, s8, s16
	s_ashr_i32 s5, s4, 31
	s_lshl_b64 s[10:11], s[4:5], 20
	s_add_u32 s10, s21, s10
	s_addc_u32 s11, s22, s11
	s_and_b64 s[18:19], s[18:19], exec
	s_cselect_b32 s5, s11, s15
	s_cselect_b32 s35, s10, s14
	s_add_u32 s36, s14, 0x100
	s_addc_u32 s37, s15, 0
	s_add_u32 s14, s16, 0x80080
	s_addc_u32 s15, s17, 0
	s_mov_b32 s38, -2
	s_add_i32 s39, 0, 0x10000
	v_add_u32_e32 v246, s39, v144
	ds_read_b128 v[148:151], v246
	ds_read_b128 v[152:155], v246 offset:1024
	ds_read_b128 v[156:159], v246 offset:2048
	ds_read_b128 v[160:163], v246 offset:3072
	s_add_i32 m0, s26, 0xc000
	ds_read_b128 v[168:171], v146
	ds_read_b128 v[172:175], v146 offset:1024
	ds_read_b128 v[176:179], v146 offset:2048
	ds_read_b128 v[180:183], v146 offset:3072
	ds_read_b128 v[184:187], v146 offset:4096
	ds_read_b128 v[188:191], v146 offset:5120
	ds_read_b128 v[192:195], v146 offset:6144
	ds_read_b128 v[212:215], v146 offset:7168
	global_load_lds_dwordx4 v140, s[14:15]
	s_add_i32 m0, s26, 0xe000
	s_nop 0
	global_load_lds_dwordx4 v138, s[14:15]
	s_waitcnt lgkmcnt(6)
	s_setprio 1
	s_barrier
	v_mfma_f32_16x16x32_bf16 v[128:131], v[148:151], v[168:171], 0
	v_mfma_f32_16x16x32_bf16 v[128:131], v[152:155], v[172:175], v[128:131]
	s_waitcnt lgkmcnt(0)
	v_mfma_f32_16x16x32_bf16 v[120:123], v[148:151], v[176:179], 0
	v_mfma_f32_16x16x32_bf16 v[120:123], v[152:155], v[180:183], v[120:123]
	v_mfma_f32_16x16x32_bf16 v[112:115], v[148:151], v[184:187], 0
	v_mfma_f32_16x16x32_bf16 v[112:115], v[152:155], v[188:191], v[112:115]
	v_mfma_f32_16x16x32_bf16 v[104:107], v[148:151], v[192:195], 0
	v_mfma_f32_16x16x32_bf16 v[104:107], v[152:155], v[212:215], v[104:107]
	v_mfma_f32_16x16x32_bf16 v[124:127], v[156:159], v[168:171], 0
	v_mfma_f32_16x16x32_bf16 v[124:127], v[160:163], v[172:175], v[124:127]
	v_mfma_f32_16x16x32_bf16 v[116:119], v[156:159], v[176:179], 0
	v_mfma_f32_16x16x32_bf16 v[116:119], v[160:163], v[180:183], v[116:119]
	v_mfma_f32_16x16x32_bf16 v[108:111], v[156:159], v[184:187], 0
	v_mfma_f32_16x16x32_bf16 v[108:111], v[160:163], v[188:191], v[108:111]
	v_mfma_f32_16x16x32_bf16 v[100:103], v[156:159], v[192:195], 0
	v_mfma_f32_16x16x32_bf16 v[100:103], v[160:163], v[212:215], v[100:103]
	s_barrier
	s_setprio 0
	s_add_u32 s16, s14, 0xfff80080
	s_addc_u32 s17, s15, -1
	s_cmp_eq_u32 s38, 28
	s_cselect_b32 s19, s3, s17
	s_cselect_b32 s18, s13, s16
	s_cselect_b32 s17, s5, s37
	s_cselect_b32 s16, s35, s36
	s_add_i32 s42, 0, 0x14000
	s_add_i32 s39, s39, s25
	ds_read_b128 v[216:219], v246 offset:16384
	ds_read_b128 v[220:223], v246 offset:17408
	ds_read_b128 v[224:227], v246 offset:18432
	ds_read_b128 v[228:231], v246 offset:19456
	s_add_u32 s98, s16, 0x80
	s_addc_u32 s99, s17, 0
	s_mov_b32 m0, s39
	s_nop 0
	global_load_lds_dwordx4 v2, s[16:17]
	s_add_i32 m0, s39, 0x2000
	s_nop 0
	global_load_lds_dwordx4 v0, s[16:17]
	s_mov_b32 m0, s26
	s_add_u32 s100, s18, 0x80
	s_addc_u32 s101, s19, 0
	s_waitcnt lgkmcnt(2)
	s_setprio 1
	s_barrier
	v_mfma_f32_16x16x32_bf16 v[96:99], v[216:219], v[168:171], 0
	v_mfma_f32_16x16x32_bf16 v[96:99], v[220:223], v[172:175], v[96:99]
	s_waitcnt lgkmcnt(0)
	v_mfma_f32_16x16x32_bf16 v[88:91], v[216:219], v[176:179], 0
	v_mfma_f32_16x16x32_bf16 v[88:91], v[220:223], v[180:183], v[88:91]
	v_mfma_f32_16x16x32_bf16 v[80:83], v[216:219], v[184:187], 0
	v_mfma_f32_16x16x32_bf16 v[80:83], v[220:223], v[188:191], v[80:83]
	v_mfma_f32_16x16x32_bf16 v[72:75], v[216:219], v[192:195], 0
	v_mfma_f32_16x16x32_bf16 v[72:75], v[220:223], v[212:215], v[72:75]
	v_mfma_f32_16x16x32_bf16 v[92:95], v[224:227], v[168:171], 0
	v_mfma_f32_16x16x32_bf16 v[92:95], v[228:231], v[172:175], v[92:95]
	v_mfma_f32_16x16x32_bf16 v[84:87], v[224:227], v[176:179], 0
	v_mfma_f32_16x16x32_bf16 v[84:87], v[228:231], v[180:183], v[84:87]
	v_mfma_f32_16x16x32_bf16 v[76:79], v[224:227], v[184:187], 0
	v_mfma_f32_16x16x32_bf16 v[76:79], v[228:231], v[188:191], v[76:79]
	v_mfma_f32_16x16x32_bf16 v[68:71], v[224:227], v[192:195], 0
	v_mfma_f32_16x16x32_bf16 v[68:71], v[228:231], v[212:215], v[68:71]
	s_barrier
	s_setprio 0
	ds_read_b128 v[168:171], v146 offset:16384
	ds_read_b128 v[172:175], v146 offset:17408
	ds_read_b128 v[176:179], v146 offset:18432
	ds_read_b128 v[180:183], v146 offset:19456
	ds_read_b128 v[184:187], v146 offset:20480
	ds_read_b128 v[188:191], v146 offset:21504
	ds_read_b128 v[192:195], v146 offset:22528
	ds_read_b128 v[212:215], v146 offset:23552
	global_load_lds_dwordx4 v134, s[18:19]
	s_mov_b32 m0, s27
	s_nop 0
	global_load_lds_dwordx4 v132, s[18:19]
	s_waitcnt lgkmcnt(6)
	s_setprio 1
	s_barrier
	v_mfma_f32_16x16x32_bf16 v[64:67], v[148:151], v[168:171], 0
	v_mfma_f32_16x16x32_bf16 v[64:67], v[152:155], v[172:175], v[64:67]
	s_waitcnt lgkmcnt(0)
	v_mfma_f32_16x16x32_bf16 v[56:59], v[148:151], v[176:179], 0
	v_mfma_f32_16x16x32_bf16 v[56:59], v[152:155], v[180:183], v[56:59]
	v_mfma_f32_16x16x32_bf16 v[48:51], v[148:151], v[184:187], 0
	v_mfma_f32_16x16x32_bf16 v[48:51], v[152:155], v[188:191], v[48:51]
	v_mfma_f32_16x16x32_bf16 v[40:43], v[148:151], v[192:195], 0
	v_mfma_f32_16x16x32_bf16 v[40:43], v[152:155], v[212:215], v[40:43]
	v_mfma_f32_16x16x32_bf16 v[60:63], v[156:159], v[168:171], 0
	v_mfma_f32_16x16x32_bf16 v[60:63], v[160:163], v[172:175], v[60:63]
	v_mfma_f32_16x16x32_bf16 v[52:55], v[156:159], v[176:179], 0
	v_mfma_f32_16x16x32_bf16 v[52:55], v[160:163], v[180:183], v[52:55]
	v_mfma_f32_16x16x32_bf16 v[44:47], v[156:159], v[184:187], 0
	v_mfma_f32_16x16x32_bf16 v[44:47], v[160:163], v[188:191], v[44:47]
	v_mfma_f32_16x16x32_bf16 v[36:39], v[156:159], v[192:195], 0
	v_mfma_f32_16x16x32_bf16 v[36:39], v[160:163], v[212:215], v[36:39]
	s_barrier
; #define PG8_WAIT_V(n) asm volatile("s_waitcnt vmcnt(" #n ")" ::: "memory")
; #define PG8_WAIT_L(n) asm volatile("s_waitcnt lgkmcnt(" #n ")" ::: "memory")
; #define PG8_BAR __builtin_amdgcn_s_barrier()
; #define PG8_SCHED __builtin_amdgcn_sched_barrier(0)
; template <class Epi, class AddrA, class AddrB>
; __device__ __forceinline__ void gemm_phase(const Sched S, const int lda, const int ldb, const int K, const AddrA addrA,
;                                            const AddrB addrB, const Epi E) {
;     ...
;       PG8_LDB(B0, 0, 0); PG8_SCHED; PG8_LDA(At, 0, 0); PG8_STAGE(PG8_SA(1, 1), a1 + hstepA, voffA);
;       PG8_WAIT_L(8); PG8_BAR; PG8_WAIT_L(0); PG8_MMA(0, 0, At, B0); PG8_BAR; PG8_SCHED;
;       PG8_LDB(B1, 0, 1); PG8_STAGE(PG8_SB(0, 0), b2, voffB);
;       PG8_BAR; PG8_WAIT_L(0); PG8_MMA(0, 1, At, B1); PG8_BAR;
;       PG8_LDA(At, 0, 1); PG8_STAGE(PG8_SA(0, 0), a2, voffA);
;       PG8_BAR; PG8_WAIT_L(0); PG8_MMA(1, 0, At, B0); PG8_BAR; PG8_SCHED;
;       PG8_STAGE(PG8_SB(0, 1), b2 + hstepB, voffB);
;       PG8_WAIT_V(6); PG8_BAR; PG8_MMA(1, 1, At, B1); PG8_BAR;
;       PG8_LDB(B0, 1, 0); PG8_SCHED; PG8_LDA(At, 1, 0); PG8_STAGE(PG8_SA(0, 1), a2 + hstepA, voffA);
;       PG8_WAIT_L(8); PG8_BAR; PG8_WAIT_L(0); PG8_MMA(0, 0, At, B0); PG8_BAR; PG8_SCHED;
;       PG8_LDB(B1, 1, 1); PG8_STAGE(PG8_SB(1, 0), b3, voffB);
;       PG8_BAR; PG8_WAIT_L(0); PG8_MMA(0, 1, At, B1); PG8_BAR;
;       PG8_LDA(At, 1, 1); PG8_STAGE(PG8_SA(1, 0), a3, voffA);
;       PG8_BAR; PG8_WAIT_L(0); PG8_MMA(1, 0, At, B0); PG8_BAR; PG8_SCHED;
;       PG8_STAGE(PG8_SB(1, 1), b3 + hstepB, voffB);
;       PG8_WAIT_V(6); PG8_BAR; PG8_MMA(1, 1, At, B1); PG8_BAR;
	s_setprio 0
	s_add_u32 s40, s16, 0x80000
	s_addc_u32 s41, s17, 0
	s_add_i32 s39, s42, s25
	s_mov_b32 m0, s39
	s_nop 0
	global_load_lds_dwordx4 v2, s[40:41]
	s_add_i32 m0, s39, 0x2000
	s_nop 0
	global_load_lds_dwordx4 v0, s[40:41]
	s_add_i32 s39, 0, 0x18000
	s_waitcnt vmcnt(6)
	s_setprio 1
	s_barrier
	v_mfma_f32_16x16x32_bf16 v[32:35], v[216:219], v[168:171], 0
	v_mfma_f32_16x16x32_bf16 v[32:35], v[220:223], v[172:175], v[32:35]
	v_mfma_f32_16x16x32_bf16 v[24:27], v[216:219], v[176:179], 0
	v_mfma_f32_16x16x32_bf16 v[24:27], v[220:223], v[180:183], v[24:27]
	v_mfma_f32_16x16x32_bf16 v[16:19], v[216:219], v[184:187], 0
	v_mfma_f32_16x16x32_bf16 v[16:19], v[220:223], v[188:191], v[16:19]
	v_mfma_f32_16x16x32_bf16 v[8:11], v[216:219], v[192:195], 0
	v_mfma_f32_16x16x32_bf16 v[8:11], v[220:223], v[212:215], v[8:11]
	v_mfma_f32_16x16x32_bf16 v[28:31], v[224:227], v[168:171], 0
	v_mfma_f32_16x16x32_bf16 v[28:31], v[228:231], v[172:175], v[28:31]
	v_mfma_f32_16x16x32_bf16 v[20:23], v[224:227], v[176:179], 0
	v_mfma_f32_16x16x32_bf16 v[20:23], v[228:231], v[180:183], v[20:23]
	v_mfma_f32_16x16x32_bf16 v[12:15], v[224:227], v[184:187], 0
	v_mfma_f32_16x16x32_bf16 v[12:15], v[228:231], v[188:191], v[12:15]
	v_mfma_f32_16x16x32_bf16 v[4:7], v[224:227], v[192:195], 0
	v_mfma_f32_16x16x32_bf16 v[4:7], v[228:231], v[212:215], v[4:7]
	s_barrier
	s_setprio 0
	ds_read_b128 v[148:151], v246 offset:32768
	ds_read_b128 v[152:155], v246 offset:33792
	ds_read_b128 v[156:159], v246 offset:34816
	ds_read_b128 v[160:163], v246 offset:35840
	s_add_u32 s18, s18, 0x80000
	s_addc_u32 s19, s19, 0
	s_mov_b32 m0, s28
	ds_read_b128 v[168:171], v146 offset:32768
	ds_read_b128 v[172:175], v146 offset:33792
	ds_read_b128 v[176:179], v146 offset:34816
	ds_read_b128 v[180:183], v146 offset:35840
	ds_read_b128 v[184:187], v146 offset:36864
	ds_read_b128 v[188:191], v146 offset:37888
	ds_read_b128 v[192:195], v146 offset:38912
	ds_read_b128 v[212:215], v146 offset:39936
	global_load_lds_dwordx4 v134, s[18:19]
	s_mov_b32 m0, s29
	s_nop 0
	global_load_lds_dwordx4 v132, s[18:19]
	s_waitcnt lgkmcnt(6)
	s_setprio 1
	s_barrier
	v_mfma_f32_16x16x32_bf16 v[128:131], v[148:151], v[168:171], v[128:131]
	v_mfma_f32_16x16x32_bf16 v[128:131], v[152:155], v[172:175], v[128:131]
	s_waitcnt lgkmcnt(0)
	v_mfma_f32_16x16x32_bf16 v[120:123], v[148:151], v[176:179], v[120:123]
	v_mfma_f32_16x16x32_bf16 v[120:123], v[152:155], v[180:183], v[120:123]
	v_mfma_f32_16x16x32_bf16 v[112:115], v[148:151], v[184:187], v[112:115]
	v_mfma_f32_16x16x32_bf16 v[112:115], v[152:155], v[188:191], v[112:115]
	v_mfma_f32_16x16x32_bf16 v[104:107], v[148:151], v[192:195], v[104:107]
	v_mfma_f32_16x16x32_bf16 v[104:107], v[152:155], v[212:215], v[104:107]
	v_mfma_f32_16x16x32_bf16 v[124:127], v[156:159], v[168:171], v[124:127]
	v_mfma_f32_16x16x32_bf16 v[124:127], v[160:163], v[172:175], v[124:127]
	v_mfma_f32_16x16x32_bf16 v[116:119], v[156:159], v[176:179], v[116:119]
	v_mfma_f32_16x16x32_bf16 v[116:119], v[160:163], v[180:183], v[116:119]
	v_mfma_f32_16x16x32_bf16 v[108:111], v[156:159], v[184:187], v[108:111]
	v_mfma_f32_16x16x32_bf16 v[108:111], v[160:163], v[188:191], v[108:111]
	v_mfma_f32_16x16x32_bf16 v[100:103], v[156:159], v[192:195], v[100:103]
	v_mfma_f32_16x16x32_bf16 v[100:103], v[160:163], v[212:215], v[100:103]
	s_barrier
	s_setprio 0
	s_add_i32 s18, 0, 0x1c000
	s_add_i32 s19, s39, s25
	s_mov_b32 m0, s19
	ds_read_b128 v[216:219], v246 offset:49152
	ds_read_b128 v[220:223], v246 offset:50176
	ds_read_b128 v[224:227], v246 offset:51200
	ds_read_b128 v[228:231], v246 offset:52224
	global_load_lds_dwordx4 v2, s[98:99]
	s_add_i32 m0, s19, 0x2000
	s_nop 0
	global_load_lds_dwordx4 v0, s[98:99]
	s_mov_b32 m0, s30
	s_waitcnt lgkmcnt(2)
	s_setprio 1
	s_barrier
	v_mfma_f32_16x16x32_bf16 v[96:99], v[216:219], v[168:171], v[96:99]
	v_mfma_f32_16x16x32_bf16 v[96:99], v[220:223], v[172:175], v[96:99]
	s_waitcnt lgkmcnt(0)
	v_mfma_f32_16x16x32_bf16 v[88:91], v[216:219], v[176:179], v[88:91]
	v_mfma_f32_16x16x32_bf16 v[88:91], v[220:223], v[180:183], v[88:91]
	v_mfma_f32_16x16x32_bf16 v[80:83], v[216:219], v[184:187], v[80:83]
	v_mfma_f32_16x16x32_bf16 v[80:83], v[220:223], v[188:191], v[80:83]
	v_mfma_f32_16x16x32_bf16 v[72:75], v[216:219], v[192:195], v[72:75]
	v_mfma_f32_16x16x32_bf16 v[72:75], v[220:223], v[212:215], v[72:75]
	v_mfma_f32_16x16x32_bf16 v[92:95], v[224:227], v[168:171], v[92:95]
	v_mfma_f32_16x16x32_bf16 v[92:95], v[228:231], v[172:175], v[92:95]
	v_mfma_f32_16x16x32_bf16 v[84:87], v[224:227], v[176:179], v[84:87]
	v_mfma_f32_16x16x32_bf16 v[84:87], v[228:231], v[180:183], v[84:87]
	v_mfma_f32_16x16x32_bf16 v[76:79], v[224:227], v[184:187], v[76:79]
	v_mfma_f32_16x16x32_bf16 v[76:79], v[228:231], v[188:191], v[76:79]
	v_mfma_f32_16x16x32_bf16 v[68:71], v[224:227], v[192:195], v[68:71]
	v_mfma_f32_16x16x32_bf16 v[68:71], v[228:231], v[212:215], v[68:71]
	s_barrier
	s_setprio 0
	ds_read_b128 v[168:171], v146 offset:49152
	ds_read_b128 v[172:175], v146 offset:50176
	ds_read_b128 v[176:179], v146 offset:51200
	ds_read_b128 v[180:183], v146 offset:52224
	ds_read_b128 v[184:187], v146 offset:53248
	ds_read_b128 v[188:191], v146 offset:54272
	ds_read_b128 v[192:195], v146 offset:55296
	ds_read_b128 v[212:215], v146 offset:56320
	global_load_lds_dwordx4 v134, s[100:101]
	s_mov_b32 m0, s31
	s_nop 0
	global_load_lds_dwordx4 v132, s[100:101]
	s_waitcnt lgkmcnt(6)
	s_setprio 1
	s_barrier
; #define PG8_WAIT_V(n) asm volatile("s_waitcnt vmcnt(" #n ")" ::: "memory")
; #define PG8_WAIT_L(n) asm volatile("s_waitcnt lgkmcnt(" #n ")" ::: "memory")
; #define PG8_BAR __builtin_amdgcn_s_barrier()
; #define PG8_SCHED __builtin_amdgcn_sched_barrier(0)
; template <class Epi, class AddrA, class AddrB>
; __device__ __forceinline__ void gemm_phase(const Sched S, const int lda, const int ldb, const int K, const AddrA addrA,
;                                            const AddrB addrB, const Epi E) {
;     ...
;     for (int t = 0; t < nt; t += 2) {
;       const bool last = (t == nt - 2);
;       const char* a1 = cA + (size_t)(t + 1) * kstep;
;       const char* a2 = last ? nA : cA + (size_t)(t + 2) * kstep;
;       const char* b2 = last ? nB : cB + (size_t)(t + 2) * kstep;
;       const char* a3 = a2 + kstep;
;       const char* b3 = b2 + kstep;
;       PG8_LDB(B0, 0, 0); PG8_SCHED; PG8_LDA(At, 0, 0); PG8_STAGE(PG8_SA(1, 1), a1 + hstepA, voffA);
;       PG8_WAIT_L(8); PG8_BAR; PG8_WAIT_L(0); PG8_MMA(0, 0, At, B0); PG8_BAR; PG8_SCHED;
;       PG8_LDB(B1, 0, 1); PG8_STAGE(PG8_SB(0, 0), b2, voffB);
;       PG8_BAR; PG8_WAIT_L(0); PG8_MMA(0, 1, At, B1); PG8_BAR;
;       PG8_LDA(At, 0, 1); PG8_STAGE(PG8_SA(0, 0), a2, voffA);
;       PG8_BAR; PG8_WAIT_L(0); PG8_MMA(1, 0, At, B0); PG8_BAR; PG8_SCHED;
;       PG8_STAGE(PG8_SB(0, 1), b2 + hstepB, voffB);
;       PG8_WAIT_V(6); PG8_BAR; PG8_MMA(1, 1, At, B1); PG8_BAR;
;       PG8_LDB(B0, 1, 0); PG8_SCHED; PG8_LDA(At, 1, 0); PG8_STAGE(PG8_SA(0, 1), a2 + hstepA, voffA);
;       PG8_WAIT_L(8); PG8_BAR; PG8_WAIT_L(0); PG8_MMA(0, 0, At, B0); PG8_BAR; PG8_SCHED;
;       PG8_LDB(B1, 1, 1); PG8_STAGE(PG8_SB(1, 0), b3, voffB);
;       PG8_BAR; PG8_WAIT_L(0); PG8_MMA(0, 1, At, B1); PG8_BAR;
;       PG8_LDA(At, 1, 1); PG8_STAGE(PG8_SA(1, 0), a3, voffA);
;       PG8_BAR; PG8_WAIT_L(0); PG8_MMA(1, 0, At, B0); PG8_BAR; PG8_SCHED;
;       PG8_STAGE(PG8_SB(1, 1), b3 + hstepB, voffB);
;       PG8_WAIT_V(6); PG8_BAR; PG8_MMA(1, 1, At, B1); PG8_BAR;
	v_mfma_f32_16x16x32_bf16 v[64:67], v[148:151], v[168:171], v[64:67]
	v_mfma_f32_16x16x32_bf16 v[64:67], v[152:155], v[172:175], v[64:67]
	s_waitcnt lgkmcnt(0)
	v_mfma_f32_16x16x32_bf16 v[56:59], v[148:151], v[176:179], v[56:59]
	v_mfma_f32_16x16x32_bf16 v[56:59], v[152:155], v[180:183], v[56:59]
	v_mfma_f32_16x16x32_bf16 v[48:51], v[148:151], v[184:187], v[48:51]
	v_mfma_f32_16x16x32_bf16 v[48:51], v[152:155], v[188:191], v[48:51]
	v_mfma_f32_16x16x32_bf16 v[40:43], v[148:151], v[192:195], v[40:43]
	v_mfma_f32_16x16x32_bf16 v[40:43], v[152:155], v[212:215], v[40:43]
	v_mfma_f32_16x16x32_bf16 v[60:63], v[156:159], v[168:171], v[60:63]
	v_mfma_f32_16x16x32_bf16 v[60:63], v[160:163], v[172:175], v[60:63]
	v_mfma_f32_16x16x32_bf16 v[52:55], v[156:159], v[176:179], v[52:55]
	v_mfma_f32_16x16x32_bf16 v[52:55], v[160:163], v[180:183], v[52:55]
	v_mfma_f32_16x16x32_bf16 v[44:47], v[156:159], v[184:187], v[44:47]
	v_mfma_f32_16x16x32_bf16 v[44:47], v[160:163], v[188:191], v[44:47]
	v_mfma_f32_16x16x32_bf16 v[36:39], v[156:159], v[192:195], v[36:39]
	v_mfma_f32_16x16x32_bf16 v[36:39], v[160:163], v[212:215], v[36:39]
	s_barrier
	s_setprio 0
	s_add_u32 s16, s16, 0x80080
	s_addc_u32 s17, s17, 0
	s_add_i32 s18, s18, s25
	s_mov_b32 m0, s18
	s_nop 0
	global_load_lds_dwordx4 v2, s[16:17]
	s_add_i32 m0, s18, 0x2000
	s_nop 0
	global_load_lds_dwordx4 v0, s[16:17]
	s_add_i32 s38, s38, 2
	s_add_u32 s36, s36, 0x100
	s_addc_u32 s37, s37, 0
	s_add_u32 s14, s14, 0x100
	s_addc_u32 s15, s15, 0
	s_waitcnt vmcnt(6)
	s_setprio 1
	s_barrier
	v_mfma_f32_16x16x32_bf16 v[32:35], v[216:219], v[168:171], v[32:35]
	v_mfma_f32_16x16x32_bf16 v[32:35], v[220:223], v[172:175], v[32:35]
	v_mfma_f32_16x16x32_bf16 v[24:27], v[216:219], v[176:179], v[24:27]
	v_mfma_f32_16x16x32_bf16 v[24:27], v[220:223], v[180:183], v[24:27]
	v_mfma_f32_16x16x32_bf16 v[16:19], v[216:219], v[184:187], v[16:19]
	v_mfma_f32_16x16x32_bf16 v[16:19], v[220:223], v[188:191], v[16:19]
	v_mfma_f32_16x16x32_bf16 v[8:11], v[216:219], v[192:195], v[8:11]
	v_mfma_f32_16x16x32_bf16 v[8:11], v[220:223], v[212:215], v[8:11]
	v_mfma_f32_16x16x32_bf16 v[28:31], v[224:227], v[168:171], v[28:31]
	v_mfma_f32_16x16x32_bf16 v[28:31], v[228:231], v[172:175], v[28:31]
	v_mfma_f32_16x16x32_bf16 v[20:23], v[224:227], v[176:179], v[20:23]
	v_mfma_f32_16x16x32_bf16 v[20:23], v[228:231], v[180:183], v[20:23]
	v_mfma_f32_16x16x32_bf16 v[12:15], v[224:227], v[184:187], v[12:15]
	v_mfma_f32_16x16x32_bf16 v[12:15], v[228:231], v[188:191], v[12:15]
	v_mfma_f32_16x16x32_bf16 v[4:7], v[224:227], v[192:195], v[4:7]
	v_mfma_f32_16x16x32_bf16 v[4:7], v[228:231], v[212:215], v[4:7]
	s_barrier
	s_setprio 0
	s_cmp_gt_u32 s38, 29
.LBB0_619:
	s_add_i32 s39, 0, 0x10000
	v_add_u32_e32 v246, s39, v144
	ds_read_b128 v[148:151], v246
	ds_read_b128 v[152:155], v246 offset:1024
	ds_read_b128 v[156:159], v246 offset:2048
	ds_read_b128 v[160:163], v246 offset:3072
	s_add_i32 m0, s26, 0xc000
	ds_read_b128 v[168:171], v146
	ds_read_b128 v[172:175], v146 offset:1024
	ds_read_b128 v[176:179], v146 offset:2048
	ds_read_b128 v[180:183], v146 offset:3072
	ds_read_b128 v[184:187], v146 offset:4096
	ds_read_b128 v[188:191], v146 offset:5120
	ds_read_b128 v[192:195], v146 offset:6144
	ds_read_b128 v[212:215], v146 offset:7168
	global_load_lds_dwordx4 v140, s[14:15]
	s_add_i32 m0, s26, 0xe000
	s_nop 0
	global_load_lds_dwordx4 v138, s[14:15]
	s_waitcnt lgkmcnt(6)
	s_setprio 1
	s_barrier
	v_mfma_f32_16x16x32_bf16 v[128:131], v[148:151], v[168:171], v[128:131]
	v_mfma_f32_16x16x32_bf16 v[128:131], v[152:155], v[172:175], v[128:131]
	s_waitcnt lgkmcnt(0)
	v_mfma_f32_16x16x32_bf16 v[120:123], v[148:151], v[176:179], v[120:123]
	v_mfma_f32_16x16x32_bf16 v[120:123], v[152:155], v[180:183], v[120:123]
	v_mfma_f32_16x16x32_bf16 v[112:115], v[148:151], v[184:187], v[112:115]
	v_mfma_f32_16x16x32_bf16 v[112:115], v[152:155], v[188:191], v[112:115]
	v_mfma_f32_16x16x32_bf16 v[104:107], v[148:151], v[192:195], v[104:107]
	v_mfma_f32_16x16x32_bf16 v[104:107], v[152:155], v[212:215], v[104:107]
	v_mfma_f32_16x16x32_bf16 v[124:127], v[156:159], v[168:171], v[124:127]
	v_mfma_f32_16x16x32_bf16 v[124:127], v[160:163], v[172:175], v[124:127]
	v_mfma_f32_16x16x32_bf16 v[116:119], v[156:159], v[176:179], v[116:119]
	v_mfma_f32_16x16x32_bf16 v[116:119], v[160:163], v[180:183], v[116:119]
	v_mfma_f32_16x16x32_bf16 v[108:111], v[156:159], v[184:187], v[108:111]
	v_mfma_f32_16x16x32_bf16 v[108:111], v[160:163], v[188:191], v[108:111]
	v_mfma_f32_16x16x32_bf16 v[100:103], v[156:159], v[192:195], v[100:103]
	v_mfma_f32_16x16x32_bf16 v[100:103], v[160:163], v[212:215], v[100:103]
	s_barrier
	s_setprio 0
	s_add_u32 s16, s14, 0xfff80080
	s_addc_u32 s17, s15, -1
	s_cmp_eq_u32 s38, 28
	s_cselect_b32 s19, s3, s17
	s_cselect_b32 s18, s13, s16
	s_cselect_b32 s17, s5, s37
	s_cselect_b32 s16, s35, s36
	s_add_i32 s42, 0, 0x14000
	s_add_i32 s39, s39, s25
	ds_read_b128 v[216:219], v246 offset:16384
	ds_read_b128 v[220:223], v246 offset:17408
	ds_read_b128 v[224:227], v246 offset:18432
	ds_read_b128 v[228:231], v246 offset:19456
	s_add_u32 s98, s16, 0x80
	s_addc_u32 s99, s17, 0
	s_mov_b32 m0, s39
	s_nop 0
	global_load_lds_dwordx4 v2, s[16:17]
	s_add_i32 m0, s39, 0x2000
	s_nop 0
	global_load_lds_dwordx4 v0, s[16:17]
	s_mov_b32 m0, s26
	s_add_u32 s100, s18, 0x80
	s_addc_u32 s101, s19, 0
	s_waitcnt lgkmcnt(2)
	s_setprio 1
	s_barrier
; #define PG8_WAIT_V(n) asm volatile("s_waitcnt vmcnt(" #n ")" ::: "memory")
; #define PG8_WAIT_L(n) asm volatile("s_waitcnt lgkmcnt(" #n ")" ::: "memory")
; #define PG8_BAR __builtin_amdgcn_s_barrier()
; #define PG8_SCHED __builtin_amdgcn_sched_barrier(0)
; template <class Epi, class AddrA, class AddrB>
; __device__ __forceinline__ void gemm_phase(const Sched S, const int lda, const int ldb, const int K, const AddrA addrA,
;                                            const AddrB addrB, const Epi E) {
;     ...
;       PG8_LDB(B0, 0, 0); PG8_SCHED; PG8_LDA(At, 0, 0); PG8_STAGE(PG8_SA(1, 1), a1 + hstepA, voffA);
;       PG8_WAIT_L(8); PG8_BAR; PG8_WAIT_L(0); PG8_MMA(0, 0, At, B0); PG8_BAR; PG8_SCHED;
;       PG8_LDB(B1, 0, 1); PG8_STAGE(PG8_SB(0, 0), b2, voffB);
;       PG8_BAR; PG8_WAIT_L(0); PG8_MMA(0, 1, At, B1); PG8_BAR;
;       PG8_LDA(At, 0, 1); PG8_STAGE(PG8_SA(0, 0), a2, voffA);
;       PG8_BAR; PG8_WAIT_L(0); PG8_MMA(1, 0, At, B0); PG8_BAR; PG8_SCHED;
;       PG8_STAGE(PG8_SB(0, 1), b2 + hstepB, voffB);
;       PG8_WAIT_V(6); PG8_BAR; PG8_MMA(1, 1, At, B1); PG8_BAR;
;       PG8_LDB(B0, 1, 0); PG8_SCHED; PG8_LDA(At, 1, 0); PG8_STAGE(PG8_SA(0, 1), a2 + hstepA, voffA);
;       PG8_WAIT_L(8); PG8_BAR; PG8_WAIT_L(0); PG8_MMA(0, 0, At, B0); PG8_BAR; PG8_SCHED;
;       PG8_LDB(B1, 1, 1); PG8_STAGE(PG8_SB(1, 0), b3, voffB);
;       PG8_BAR; PG8_WAIT_L(0); PG8_MMA(0, 1, At, B1); PG8_BAR;
;       PG8_LDA(At, 1, 1); PG8_STAGE(PG8_SA(1, 0), a3, voffA);
;       PG8_BAR; PG8_WAIT_L(0); PG8_MMA(1, 0, At, B0); PG8_BAR; PG8_SCHED;
;       PG8_STAGE(PG8_SB(1, 1), b3 + hstepB, voffB);
;       PG8_WAIT_V(6); PG8_BAR; PG8_MMA(1, 1, At, B1); PG8_BAR;
	v_mfma_f32_16x16x32_bf16 v[96:99], v[216:219], v[168:171], v[96:99]
	v_mfma_f32_16x16x32_bf16 v[96:99], v[220:223], v[172:175], v[96:99]
	s_waitcnt lgkmcnt(0)
	v_mfma_f32_16x16x32_bf16 v[88:91], v[216:219], v[176:179], v[88:91]
	v_mfma_f32_16x16x32_bf16 v[88:91], v[220:223], v[180:183], v[88:91]
	v_mfma_f32_16x16x32_bf16 v[80:83], v[216:219], v[184:187], v[80:83]
	v_mfma_f32_16x16x32_bf16 v[80:83], v[220:223], v[188:191], v[80:83]
	v_mfma_f32_16x16x32_bf16 v[72:75], v[216:219], v[192:195], v[72:75]
	v_mfma_f32_16x16x32_bf16 v[72:75], v[220:223], v[212:215], v[72:75]
	v_mfma_f32_16x16x32_bf16 v[92:95], v[224:227], v[168:171], v[92:95]
	v_mfma_f32_16x16x32_bf16 v[92:95], v[228:231], v[172:175], v[92:95]
	v_mfma_f32_16x16x32_bf16 v[84:87], v[224:227], v[176:179], v[84:87]
	v_mfma_f32_16x16x32_bf16 v[84:87], v[228:231], v[180:183], v[84:87]
	v_mfma_f32_16x16x32_bf16 v[76:79], v[224:227], v[184:187], v[76:79]
	v_mfma_f32_16x16x32_bf16 v[76:79], v[228:231], v[188:191], v[76:79]
	v_mfma_f32_16x16x32_bf16 v[68:71], v[224:227], v[192:195], v[68:71]
	v_mfma_f32_16x16x32_bf16 v[68:71], v[228:231], v[212:215], v[68:71]
	s_barrier
	s_setprio 0
	ds_read_b128 v[168:171], v146 offset:16384
	ds_read_b128 v[172:175], v146 offset:17408
	ds_read_b128 v[176:179], v146 offset:18432
	ds_read_b128 v[180:183], v146 offset:19456
	ds_read_b128 v[184:187], v146 offset:20480
	ds_read_b128 v[188:191], v146 offset:21504
	ds_read_b128 v[192:195], v146 offset:22528
	ds_read_b128 v[212:215], v146 offset:23552
	global_load_lds_dwordx4 v134, s[18:19]
	s_mov_b32 m0, s27
	s_nop 0
	global_load_lds_dwordx4 v132, s[18:19]
	s_waitcnt lgkmcnt(6)
	s_setprio 1
	s_barrier
	v_mfma_f32_16x16x32_bf16 v[64:67], v[148:151], v[168:171], v[64:67]
	v_mfma_f32_16x16x32_bf16 v[64:67], v[152:155], v[172:175], v[64:67]
	s_waitcnt lgkmcnt(0)
	v_mfma_f32_16x16x32_bf16 v[56:59], v[148:151], v[176:179], v[56:59]
	v_mfma_f32_16x16x32_bf16 v[56:59], v[152:155], v[180:183], v[56:59]
	v_mfma_f32_16x16x32_bf16 v[48:51], v[148:151], v[184:187], v[48:51]
	v_mfma_f32_16x16x32_bf16 v[48:51], v[152:155], v[188:191], v[48:51]
	v_mfma_f32_16x16x32_bf16 v[40:43], v[148:151], v[192:195], v[40:43]
	v_mfma_f32_16x16x32_bf16 v[40:43], v[152:155], v[212:215], v[40:43]
	v_mfma_f32_16x16x32_bf16 v[60:63], v[156:159], v[168:171], v[60:63]
	v_mfma_f32_16x16x32_bf16 v[60:63], v[160:163], v[172:175], v[60:63]
	v_mfma_f32_16x16x32_bf16 v[52:55], v[156:159], v[176:179], v[52:55]
	v_mfma_f32_16x16x32_bf16 v[52:55], v[160:163], v[180:183], v[52:55]
	v_mfma_f32_16x16x32_bf16 v[44:47], v[156:159], v[184:187], v[44:47]
	v_mfma_f32_16x16x32_bf16 v[44:47], v[160:163], v[188:191], v[44:47]
	v_mfma_f32_16x16x32_bf16 v[36:39], v[156:159], v[192:195], v[36:39]
	v_mfma_f32_16x16x32_bf16 v[36:39], v[160:163], v[212:215], v[36:39]
	s_barrier
	s_setprio 0
	s_add_u32 s40, s16, 0x80000
	s_addc_u32 s41, s17, 0
	s_add_i32 s39, s42, s25
	s_mov_b32 m0, s39
	s_nop 0
	global_load_lds_dwordx4 v2, s[40:41]
	s_add_i32 m0, s39, 0x2000
	s_nop 0
	global_load_lds_dwordx4 v0, s[40:41]
	s_add_i32 s39, 0, 0x18000
	s_waitcnt vmcnt(6)
	s_setprio 1
	s_barrier
	v_mfma_f32_16x16x32_bf16 v[32:35], v[216:219], v[168:171], v[32:35]
	v_mfma_f32_16x16x32_bf16 v[32:35], v[220:223], v[172:175], v[32:35]
	v_mfma_f32_16x16x32_bf16 v[24:27], v[216:219], v[176:179], v[24:27]
	v_mfma_f32_16x16x32_bf16 v[24:27], v[220:223], v[180:183], v[24:27]
	v_mfma_f32_16x16x32_bf16 v[16:19], v[216:219], v[184:187], v[16:19]
	v_mfma_f32_16x16x32_bf16 v[16:19], v[220:223], v[188:191], v[16:19]
	v_mfma_f32_16x16x32_bf16 v[8:11], v[216:219], v[192:195], v[8:11]
	v_mfma_f32_16x16x32_bf16 v[8:11], v[220:223], v[212:215], v[8:11]
	v_mfma_f32_16x16x32_bf16 v[28:31], v[224:227], v[168:171], v[28:31]
	v_mfma_f32_16x16x32_bf16 v[28:31], v[228:231], v[172:175], v[28:31]
	v_mfma_f32_16x16x32_bf16 v[20:23], v[224:227], v[176:179], v[20:23]
	v_mfma_f32_16x16x32_bf16 v[20:23], v[228:231], v[180:183], v[20:23]
	v_mfma_f32_16x16x32_bf16 v[12:15], v[224:227], v[184:187], v[12:15]
	v_mfma_f32_16x16x32_bf16 v[12:15], v[228:231], v[188:191], v[12:15]
	v_mfma_f32_16x16x32_bf16 v[4:7], v[224:227], v[192:195], v[4:7]
	v_mfma_f32_16x16x32_bf16 v[4:7], v[228:231], v[212:215], v[4:7]
	s_barrier
	s_setprio 0
	ds_read_b128 v[148:151], v246 offset:32768
	ds_read_b128 v[152:155], v246 offset:33792
	ds_read_b128 v[156:159], v246 offset:34816
	ds_read_b128 v[160:163], v246 offset:35840
	s_add_u32 s18, s18, 0x80000
	s_addc_u32 s19, s19, 0
	s_mov_b32 m0, s28
	ds_read_b128 v[168:171], v146 offset:32768
	ds_read_b128 v[172:175], v146 offset:33792
	ds_read_b128 v[176:179], v146 offset:34816
	ds_read_b128 v[180:183], v146 offset:35840
	ds_read_b128 v[184:187], v146 offset:36864
	ds_read_b128 v[188:191], v146 offset:37888
	ds_read_b128 v[192:195], v146 offset:38912
	ds_read_b128 v[212:215], v146 offset:39936
	global_load_lds_dwordx4 v134, s[18:19]
	s_mov_b32 m0, s29
	s_nop 0
	global_load_lds_dwordx4 v132, s[18:19]
	s_waitcnt lgkmcnt(6)
	s_setprio 1
	s_barrier
	v_mfma_f32_16x16x32_bf16 v[128:131], v[148:151], v[168:171], v[128:131]
	v_mfma_f32_16x16x32_bf16 v[128:131], v[152:155], v[172:175], v[128:131]
	s_waitcnt lgkmcnt(0)
	v_mfma_f32_16x16x32_bf16 v[120:123], v[148:151], v[176:179], v[120:123]
	v_mfma_f32_16x16x32_bf16 v[120:123], v[152:155], v[180:183], v[120:123]
	v_mfma_f32_16x16x32_bf16 v[112:115], v[148:151], v[184:187], v[112:115]
	v_mfma_f32_16x16x32_bf16 v[112:115], v[152:155], v[188:191], v[112:115]
	v_mfma_f32_16x16x32_bf16 v[104:107], v[148:151], v[192:195], v[104:107]
	v_mfma_f32_16x16x32_bf16 v[104:107], v[152:155], v[212:215], v[104:107]
	v_mfma_f32_16x16x32_bf16 v[124:127], v[156:159], v[168:171], v[124:127]
	v_mfma_f32_16x16x32_bf16 v[124:127], v[160:163], v[172:175], v[124:127]
	v_mfma_f32_16x16x32_bf16 v[116:119], v[156:159], v[176:179], v[116:119]
	v_mfma_f32_16x16x32_bf16 v[116:119], v[160:163], v[180:183], v[116:119]
	v_mfma_f32_16x16x32_bf16 v[108:111], v[156:159], v[184:187], v[108:111]
	v_mfma_f32_16x16x32_bf16 v[108:111], v[160:163], v[188:191], v[108:111]
	v_mfma_f32_16x16x32_bf16 v[100:103], v[156:159], v[192:195], v[100:103]
	v_mfma_f32_16x16x32_bf16 v[100:103], v[160:163], v[212:215], v[100:103]
	s_barrier
; #define PG8_WAIT_V(n) asm volatile("s_waitcnt vmcnt(" #n ")" ::: "memory")
; #define PG8_WAIT_L(n) asm volatile("s_waitcnt lgkmcnt(" #n ")" ::: "memory")
; #define PG8_BAR __builtin_amdgcn_s_barrier()
; #define PG8_SCHED __builtin_amdgcn_sched_barrier(0)
; template <class Epi, class AddrA, class AddrB>
; __device__ __forceinline__ void gemm_phase(const Sched S, const int lda, const int ldb, const int K, const AddrA addrA,
;                                            const AddrB addrB, const Epi E) {
;     ...
;       PG8_LDB(B0, 0, 0); PG8_SCHED; PG8_LDA(At, 0, 0); PG8_STAGE(PG8_SA(1, 1), a1 + hstepA, voffA);
;       PG8_WAIT_L(8); PG8_BAR; PG8_WAIT_L(0); PG8_MMA(0, 0, At, B0); PG8_BAR; PG8_SCHED;
;       PG8_LDB(B1, 0, 1); PG8_STAGE(PG8_SB(0, 0), b2, voffB);
;       PG8_BAR; PG8_WAIT_L(0); PG8_MMA(0, 1, At, B1); PG8_BAR;
;       PG8_LDA(At, 0, 1); PG8_STAGE(PG8_SA(0, 0), a2, voffA);
;       PG8_BAR; PG8_WAIT_L(0); PG8_MMA(1, 0, At, B0); PG8_BAR; PG8_SCHED;
;       PG8_STAGE(PG8_SB(0, 1), b2 + hstepB, voffB);
;       PG8_WAIT_V(6); PG8_BAR; PG8_MMA(1, 1, At, B1); PG8_BAR;
;       PG8_LDB(B0, 1, 0); PG8_SCHED; PG8_LDA(At, 1, 0); PG8_STAGE(PG8_SA(0, 1), a2 + hstepA, voffA);
;       PG8_WAIT_L(8); PG8_BAR; PG8_WAIT_L(0); PG8_MMA(0, 0, At, B0); PG8_BAR; PG8_SCHED;
;       PG8_LDB(B1, 1, 1); PG8_STAGE(PG8_SB(1, 0), b3, voffB);
;       PG8_BAR; PG8_WAIT_L(0); PG8_MMA(0, 1, At, B1); PG8_BAR;
;       PG8_LDA(At, 1, 1); PG8_STAGE(PG8_SA(1, 0), a3, voffA);
;       PG8_BAR; PG8_WAIT_L(0); PG8_MMA(1, 0, At, B0); PG8_BAR; PG8_SCHED;
;       PG8_STAGE(PG8_SB(1, 1), b3 + hstepB, voffB);
;       PG8_WAIT_V(6); PG8_BAR; PG8_MMA(1, 1, At, B1); PG8_BAR;
	s_setprio 0
	s_add_i32 s18, 0, 0x1c000
	s_add_i32 s19, s39, s25
	s_mov_b32 m0, s19
	ds_read_b128 v[216:219], v246 offset:49152
	ds_read_b128 v[220:223], v246 offset:50176
	ds_read_b128 v[224:227], v246 offset:51200
	ds_read_b128 v[228:231], v246 offset:52224
	global_load_lds_dwordx4 v2, s[98:99]
	s_add_i32 m0, s19, 0x2000
	s_nop 0
	global_load_lds_dwordx4 v0, s[98:99]
	s_mov_b32 m0, s30
	s_waitcnt lgkmcnt(2)
	s_setprio 1
	s_barrier
	v_mfma_f32_16x16x32_bf16 v[96:99], v[216:219], v[168:171], v[96:99]
	v_mfma_f32_16x16x32_bf16 v[96:99], v[220:223], v[172:175], v[96:99]
	s_waitcnt lgkmcnt(0)
	v_mfma_f32_16x16x32_bf16 v[88:91], v[216:219], v[176:179], v[88:91]
	v_mfma_f32_16x16x32_bf16 v[88:91], v[220:223], v[180:183], v[88:91]
	v_mfma_f32_16x16x32_bf16 v[80:83], v[216:219], v[184:187], v[80:83]
	v_mfma_f32_16x16x32_bf16 v[80:83], v[220:223], v[188:191], v[80:83]
	v_mfma_f32_16x16x32_bf16 v[72:75], v[216:219], v[192:195], v[72:75]
	v_mfma_f32_16x16x32_bf16 v[72:75], v[220:223], v[212:215], v[72:75]
	v_mfma_f32_16x16x32_bf16 v[92:95], v[224:227], v[168:171], v[92:95]
	v_mfma_f32_16x16x32_bf16 v[92:95], v[228:231], v[172:175], v[92:95]
	v_mfma_f32_16x16x32_bf16 v[84:87], v[224:227], v[176:179], v[84:87]
	v_mfma_f32_16x16x32_bf16 v[84:87], v[228:231], v[180:183], v[84:87]
	v_mfma_f32_16x16x32_bf16 v[76:79], v[224:227], v[184:187], v[76:79]
	v_mfma_f32_16x16x32_bf16 v[76:79], v[228:231], v[188:191], v[76:79]
	v_mfma_f32_16x16x32_bf16 v[68:71], v[224:227], v[192:195], v[68:71]
	v_mfma_f32_16x16x32_bf16 v[68:71], v[228:231], v[212:215], v[68:71]
	s_barrier
	s_setprio 0
	ds_read_b128 v[168:171], v146 offset:49152
	ds_read_b128 v[172:175], v146 offset:50176
	ds_read_b128 v[176:179], v146 offset:51200
	ds_read_b128 v[180:183], v146 offset:52224
	ds_read_b128 v[184:187], v146 offset:53248
	ds_read_b128 v[188:191], v146 offset:54272
	ds_read_b128 v[192:195], v146 offset:55296
	ds_read_b128 v[212:215], v146 offset:56320
	global_load_lds_dwordx4 v134, s[100:101]
	s_mov_b32 m0, s31
	s_nop 0
	global_load_lds_dwordx4 v132, s[100:101]
	s_waitcnt lgkmcnt(6)
	s_setprio 1
	s_barrier
	v_mfma_f32_16x16x32_bf16 v[64:67], v[148:151], v[168:171], v[64:67]
	v_mfma_f32_16x16x32_bf16 v[64:67], v[152:155], v[172:175], v[64:67]
	s_waitcnt lgkmcnt(0)
	v_mfma_f32_16x16x32_bf16 v[56:59], v[148:151], v[176:179], v[56:59]
	v_mfma_f32_16x16x32_bf16 v[56:59], v[152:155], v[180:183], v[56:59]
	v_mfma_f32_16x16x32_bf16 v[48:51], v[148:151], v[184:187], v[48:51]
	v_mfma_f32_16x16x32_bf16 v[48:51], v[152:155], v[188:191], v[48:51]
	v_mfma_f32_16x16x32_bf16 v[40:43], v[148:151], v[192:195], v[40:43]
	v_mfma_f32_16x16x32_bf16 v[40:43], v[152:155], v[212:215], v[40:43]
	v_mfma_f32_16x16x32_bf16 v[60:63], v[156:159], v[168:171], v[60:63]
	v_mfma_f32_16x16x32_bf16 v[60:63], v[160:163], v[172:175], v[60:63]
	v_mfma_f32_16x16x32_bf16 v[52:55], v[156:159], v[176:179], v[52:55]
	v_mfma_f32_16x16x32_bf16 v[52:55], v[160:163], v[180:183], v[52:55]
	v_mfma_f32_16x16x32_bf16 v[44:47], v[156:159], v[184:187], v[44:47]
	v_mfma_f32_16x16x32_bf16 v[44:47], v[160:163], v[188:191], v[44:47]
	v_mfma_f32_16x16x32_bf16 v[36:39], v[156:159], v[192:195], v[36:39]
	v_mfma_f32_16x16x32_bf16 v[36:39], v[160:163], v[212:215], v[36:39]
	s_barrier
	s_setprio 0
	s_add_u32 s16, s16, 0x80080
	s_addc_u32 s17, s17, 0
	s_add_i32 s18, s18, s25
	s_mov_b32 m0, s18
	s_nop 0
	global_load_lds_dwordx4 v2, s[16:17]
	s_add_i32 m0, s18, 0x2000
	s_nop 0
	global_load_lds_dwordx4 v0, s[16:17]
	s_add_i32 s38, s38, 2
	s_add_u32 s36, s36, 0x100
	s_addc_u32 s37, s37, 0
	s_add_u32 s14, s14, 0x100
	s_addc_u32 s15, s15, 0
	s_waitcnt vmcnt(6)
	s_setprio 1
	s_barrier
	v_mfma_f32_16x16x32_bf16 v[32:35], v[216:219], v[168:171], v[32:35]
	v_mfma_f32_16x16x32_bf16 v[32:35], v[220:223], v[172:175], v[32:35]
	v_mfma_f32_16x16x32_bf16 v[24:27], v[216:219], v[176:179], v[24:27]
	v_mfma_f32_16x16x32_bf16 v[24:27], v[220:223], v[180:183], v[24:27]
	v_mfma_f32_16x16x32_bf16 v[16:19], v[216:219], v[184:187], v[16:19]
	v_mfma_f32_16x16x32_bf16 v[16:19], v[220:223], v[188:191], v[16:19]
	v_mfma_f32_16x16x32_bf16 v[8:11], v[216:219], v[192:195], v[8:11]
	v_mfma_f32_16x16x32_bf16 v[8:11], v[220:223], v[212:215], v[8:11]
	v_mfma_f32_16x16x32_bf16 v[28:31], v[224:227], v[168:171], v[28:31]
	v_mfma_f32_16x16x32_bf16 v[28:31], v[228:231], v[172:175], v[28:31]
	v_mfma_f32_16x16x32_bf16 v[20:23], v[224:227], v[176:179], v[20:23]
	v_mfma_f32_16x16x32_bf16 v[20:23], v[228:231], v[180:183], v[20:23]
	v_mfma_f32_16x16x32_bf16 v[12:15], v[224:227], v[184:187], v[12:15]
	v_mfma_f32_16x16x32_bf16 v[12:15], v[228:231], v[188:191], v[12:15]
	v_mfma_f32_16x16x32_bf16 v[4:7], v[224:227], v[192:195], v[4:7]
	v_mfma_f32_16x16x32_bf16 v[4:7], v[228:231], v[212:215], v[4:7]
	s_barrier
	s_setprio 0
	s_cmp_gt_u32 s38, 29
	s_cbranch_scc0 .LBB0_619
;   __device__ __forceinline__ void operator()(EPI_ARGS) const {
;     const size_t row0 = (size_t)u.pm * 256 + wr * 64 + fr;
;     const int col0 = u.pn * 256 + wc * 32 + 8 * fq;
; #pragma unroll
;     for (int ai = 0; ai < 2; ++ai)
; #pragma unroll
;       for (int bj = 0; bj < 2; ++bj) {
;         f32x4 x0[4], x1[4];
; #pragma unroll
;         for (int m = 0; m < 4; ++m) {
;           const size_t o = (row0 + ai * HALF + m * 16) * DM + col0 + bj * HALF;
;           x0[m] = *(const f32x4*)(xres + o);
;           x1[m] = *(const f32x4*)(xres + o + 4);
;         }
;         __builtin_amdgcn_sched_barrier(0);
; #pragma unroll
;         for (int m = 0; m < 4; ++m) {
;           const size_t o = (row0 + ai * HALF + m * 16) * DM + col0 + bj * HALF;
;           *(f32x4*)(hbuf + o) = acc[ai][bj][m][0] + x0[m] * ALPHA;
;           *(f32x4*)(hbuf + o + 4) = acc[ai][bj][m][1] + x1[m] * ALPHA;
;         }
	s_ashr_i32 s13, s12, 31
	v_lshl_or_b32 v142, s34, 8, v145
	v_ashrrev_i32_e32 v143, 31, v142
	s_lshl_b64 s[12:13], s[12:13], 21
	v_lshlrev_b64 v[184:185], 2, v[142:143]
	v_lshl_add_u64 v[188:189], s[12:13], 0, v[136:137]
	v_lshl_add_u64 v[186:187], s[0:1], 0, v[184:185]
	v_or_b32_e32 v190, 0x20000, v188
	v_mov_b32_e32 v191, v189
	v_or_b32_e32 v192, 0x40000, v188
	v_mov_b32_e32 v193, v189
	v_or_b32_e32 v194, 0x60000, v188
	v_mov_b32_e32 v195, v189
	v_lshl_add_u64 v[142:143], v[186:187], 0, v[188:189]
	v_lshl_add_u64 v[160:161], v[186:187], 0, v[190:191]
	v_lshl_add_u64 v[172:173], v[186:187], 0, v[192:193]
	v_lshl_add_u64 v[180:181], v[186:187], 0, v[194:195]
	flat_load_dwordx4 v[148:151], v[142:143]
	flat_load_dwordx4 v[152:155], v[142:143] offset:16
	flat_load_dwordx4 v[156:159], v[160:161]
	s_nop 0
	flat_load_dwordx4 v[160:163], v[160:161] offset:16
	s_nop 0
	flat_load_dwordx4 v[168:171], v[172:173]
	s_nop 0
	flat_load_dwordx4 v[172:175], v[172:173] offset:16
	s_nop 0
	flat_load_dwordx4 v[176:179], v[180:181]
	s_nop 0
	flat_load_dwordx4 v[180:183], v[180:181] offset:16
	v_lshl_add_u64 v[184:185], s[48:49], 0, v[184:185]
	s_mov_b32 s14, 0x3fb504f3
	s_waitcnt vmcnt(0) lgkmcnt(0)
	v_pk_fma_f32 v[148:149], v[148:149], s[14:15], v[128:129] op_sel_hi:[1,0,1]
	v_lshl_add_u64 v[128:129], v[184:185], 0, v[188:189]
	v_pk_fma_f32 v[126:127], v[154:155], s[14:15], v[126:127] op_sel_hi:[1,0,1]
	v_pk_fma_f32 v[124:125], v[152:153], s[14:15], v[124:125] op_sel_hi:[1,0,1]
	global_store_dwordx4 v[128:129], v[124:127], off offset:16
	v_pk_fma_f32 v[118:119], v[162:163], s[14:15], v[118:119] op_sel_hi:[1,0,1]
	v_pk_fma_f32 v[116:117], v[160:161], s[14:15], v[116:117] op_sel_hi:[1,0,1]
	v_lshl_add_u64 v[124:125], v[184:185], 0, v[190:191]
	v_pk_fma_f32 v[122:123], v[158:159], s[14:15], v[122:123] op_sel_hi:[1,0,1]
	v_pk_fma_f32 v[120:121], v[156:157], s[14:15], v[120:121] op_sel_hi:[1,0,1]
	global_store_dwordx4 v[124:125], v[116:119], off offset:16
	v_pk_fma_f32 v[110:111], v[174:175], s[14:15], v[110:111] op_sel_hi:[1,0,1]
	v_pk_fma_f32 v[108:109], v[172:173], s[14:15], v[108:109] op_sel_hi:[1,0,1]
	v_lshl_add_u64 v[116:117], v[184:185], 0, v[192:193]
	s_mov_b64 s[12:13], 0x200
	v_pk_fma_f32 v[150:151], v[150:151], s[14:15], v[130:131] op_sel_hi:[1,0,1]
	global_store_dwordx4 v[124:125], v[120:123], off
	v_pk_fma_f32 v[114:115], v[170:171], s[14:15], v[114:115] op_sel_hi:[1,0,1]
	v_pk_fma_f32 v[112:113], v[168:169], s[14:15], v[112:113] op_sel_hi:[1,0,1]
	global_store_dwordx4 v[116:117], v[108:111], off offset:16
	v_pk_fma_f32 v[106:107], v[178:179], s[14:15], v[106:107] op_sel_hi:[1,0,1]
	v_pk_fma_f32 v[104:105], v[176:177], s[14:15], v[104:105] op_sel_hi:[1,0,1]
	v_lshl_add_u64 v[108:109], v[184:185], 0, v[194:195]
	v_pk_fma_f32 v[102:103], v[182:183], s[14:15], v[102:103] op_sel_hi:[1,0,1]
	v_pk_fma_f32 v[100:101], v[180:181], s[14:15], v[100:101] op_sel_hi:[1,0,1]
	v_lshl_add_u64 v[124:125], v[186:187], 0, s[12:13]
	global_store_dwordx4 v[128:129], v[148:151], off
	global_store_dwordx4 v[116:117], v[112:115], off
	global_store_dwordx4 v[108:109], v[104:107], off
	global_store_dwordx4 v[108:109], v[100:103], off offset:16
	v_lshl_add_u64 v[112:113], v[124:125], 0, v[190:191]
	v_lshl_add_u64 v[120:121], v[124:125], 0, v[192:193]
	v_lshl_add_u64 v[130:131], v[124:125], 0, v[194:195]
	flat_load_dwordx4 v[100:103], v[142:143] offset:512
	flat_load_dwordx4 v[104:107], v[142:143] offset:528
	flat_load_dwordx4 v[108:111], v[112:113]
	s_nop 0
	flat_load_dwordx4 v[112:115], v[112:113] offset:16
	s_nop 0
	flat_load_dwordx4 v[116:119], v[120:121]
	s_nop 0
	flat_load_dwordx4 v[120:123], v[120:121] offset:16
	s_nop 0
	flat_load_dwordx4 v[124:127], v[130:131]
	flat_load_dwordx4 v[148:151], v[130:131] offset:16
	s_mov_b32 s3, 0x100000
	s_waitcnt vmcnt(0) lgkmcnt(0)
	v_pk_fma_f32 v[96:97], v[100:101], s[14:15], v[96:97] op_sel_hi:[1,0,1]
	v_add_co_u32_e32 v100, vcc, s3, v142
	s_mov_b32 s5, 0x120000
	s_nop 0
	v_addc_co_u32_e32 v101, vcc, 0, v143, vcc
	v_pk_fma_f32 v[98:99], v[102:103], s[14:15], v[98:99] op_sel_hi:[1,0,1]
	v_add_co_u32_e32 v102, vcc, s5, v142
	v_lshl_add_u64 v[130:131], v[184:185], 0, s[12:13]
	v_pk_fma_f32 v[94:95], v[106:107], s[14:15], v[94:95] op_sel_hi:[1,0,1]
	v_pk_fma_f32 v[92:93], v[104:105], s[14:15], v[92:93] op_sel_hi:[1,0,1]
	v_addc_co_u32_e32 v103, vcc, 0, v143, vcc
	s_mov_b32 s12, 0x140000
	global_store_dwordx4 v[128:129], v[92:95], off offset:528
	v_pk_fma_f32 v[86:87], v[114:115], s[14:15], v[86:87] op_sel_hi:[1,0,1]
	v_pk_fma_f32 v[84:85], v[112:113], s[14:15], v[84:85] op_sel_hi:[1,0,1]
	v_lshl_add_u64 v[92:93], v[130:131], 0, v[190:191]
	v_add_co_u32_e32 v104, vcc, s12, v142
	global_store_dwordx4 v[92:93], v[84:87], off offset:16
	v_pk_fma_f32 v[78:79], v[122:123], s[14:15], v[78:79] op_sel_hi:[1,0,1]
	v_pk_fma_f32 v[76:77], v[120:121], s[14:15], v[76:77] op_sel_hi:[1,0,1]
	v_lshl_add_u64 v[84:85], v[130:131], 0, v[192:193]
	v_addc_co_u32_e32 v105, vcc, 0, v143, vcc
	s_mov_b32 s13, 0x160000
	v_pk_fma_f32 v[90:91], v[110:111], s[14:15], v[90:91] op_sel_hi:[1,0,1]
	v_pk_fma_f32 v[88:89], v[108:109], s[14:15], v[88:89] op_sel_hi:[1,0,1]
	v_pk_fma_f32 v[82:83], v[118:119], s[14:15], v[82:83] op_sel_hi:[1,0,1]
	v_pk_fma_f32 v[80:81], v[116:117], s[14:15], v[80:81] op_sel_hi:[1,0,1]
	global_store_dwordx4 v[84:85], v[76:79], off offset:16
	v_pk_fma_f32 v[74:75], v[126:127], s[14:15], v[74:75] op_sel_hi:[1,0,1]
	v_pk_fma_f32 v[72:73], v[124:125], s[14:15], v[72:73] op_sel_hi:[1,0,1]
	v_lshl_add_u64 v[76:77], v[130:131], 0, v[194:195]
	v_pk_fma_f32 v[70:71], v[150:151], s[14:15], v[70:71] op_sel_hi:[1,0,1]
	v_pk_fma_f32 v[68:69], v[148:149], s[14:15], v[68:69] op_sel_hi:[1,0,1]
	s_mov_b64 s[16:17], 0x100000
	s_mov_b64 s[18:19], 0x120000
	s_mov_b64 s[34:35], 0x140000
	s_mov_b64 s[36:37], 0x160000
	v_add_co_u32_e32 v106, vcc, s13, v142
	global_store_dwordx4 v[128:129], v[96:99], off offset:512
	global_store_dwordx4 v[92:93], v[88:91], off
	global_store_dwordx4 v[84:85], v[80:83], off
	global_store_dwordx4 v[76:77], v[72:75], off
	global_store_dwordx4 v[76:77], v[68:71], off offset:16
	v_lshl_add_u64 v[80:81], v[142:143], 0, s[18:19]
	v_lshl_add_u64 v[72:73], v[142:143], 0, s[16:17]
	v_lshl_add_u64 v[88:89], v[142:143], 0, s[34:35]
	v_lshl_add_u64 v[96:97], v[142:143], 0, s[36:37]
	v_addc_co_u32_e32 v107, vcc, 0, v143, vcc
	flat_load_dwordx4 v[68:71], v[100:101]
	s_nop 0
	flat_load_dwordx4 v[72:75], v[72:73] offset:16
	s_nop 0
	flat_load_dwordx4 v[76:79], v[102:103]
	s_nop 0
	flat_load_dwordx4 v[80:83], v[80:81] offset:16
	s_nop 0
	flat_load_dwordx4 v[84:87], v[104:105]
	s_nop 0
	flat_load_dwordx4 v[88:91], v[88:89] offset:16
	s_nop 0
	flat_load_dwordx4 v[92:95], v[106:107]
	s_nop 0
	flat_load_dwordx4 v[96:99], v[96:97] offset:16
	s_waitcnt vmcnt(0) lgkmcnt(0)
; template <class Epi, class AddrA, class AddrB>
; __device__ __forceinline__ void gemm_phase(const Sched S, const int lda, const int ldb, const int K, const AddrA addrA,
;                                            const AddrB addrB, const Epi E) {
;     ...
;     E(acc, cur, wr, wc, fr, fq);
;     if (!has_next) break;
;     if (!(Epi::KEEP && cur.br + 1 < S.nbr)) {
; #pragma unroll
;       for (int a = 0; a < 2; ++a)
; #pragma unroll
;         for (int b = 0; b < 2; ++b)
; #pragma unroll
;           for (int m = 0; m < 4; ++m)
; #pragma unroll
;             for (int n = 0; n < 2; ++n) acc[a][b][m][n] = (f32x4){0.f, 0.f, 0.f, 0.f};
;     }
;     cur = nxt; cA = nA; cB = nB; ++ui;
;   __device__ __forceinline__ void operator()(EPI_ARGS) const {
;     ...
; #pragma unroll
;         for (int m = 0; m < 4; ++m) {
;           const size_t o = (row0 + ai * HALF + m * 16) * DM + col0 + bj * HALF;
;           x0[m] = *(const f32x4*)(xres + o);
;           x1[m] = *(const f32x4*)(xres + o + 4);
;         }
;         __builtin_amdgcn_sched_barrier(0);
; #pragma unroll
;         for (int m = 0; m < 4; ++m) {
;           const size_t o = (row0 + ai * HALF + m * 16) * DM + col0 + bj * HALF;
;           *(f32x4*)(hbuf + o) = acc[ai][bj][m][0] + x0[m] * ALPHA;
;           *(f32x4*)(hbuf + o + 4) = acc[ai][bj][m][1] + x1[m] * ALPHA;
;         }
;       }
;   }
	v_pk_fma_f32 v[66:67], v[70:71], s[14:15], v[66:67] op_sel_hi:[1,0,1]
	v_add_co_u32_e32 v70, vcc, s3, v128
	v_pk_fma_f32 v[64:65], v[68:69], s[14:15], v[64:65] op_sel_hi:[1,0,1]
	v_lshl_add_u64 v[68:69], v[128:129], 0, s[16:17]
	v_addc_co_u32_e32 v71, vcc, 0, v129, vcc
	v_pk_fma_f32 v[62:63], v[74:75], s[14:15], v[62:63] op_sel_hi:[1,0,1]
	v_pk_fma_f32 v[60:61], v[72:73], s[14:15], v[60:61] op_sel_hi:[1,0,1]
	global_store_dwordx4 v[68:69], v[60:63], off offset:16
	v_add_co_u32_e32 v68, vcc, s5, v128
	s_nop 0
	v_lshl_add_u64 v[60:61], v[128:129], 0, s[18:19]
	v_addc_co_u32_e32 v69, vcc, 0, v129, vcc
	v_add_co_u32_e32 v72, vcc, s12, v128
	v_pk_fma_f32 v[54:55], v[82:83], s[14:15], v[54:55] op_sel_hi:[1,0,1]
	v_pk_fma_f32 v[52:53], v[80:81], s[14:15], v[52:53] op_sel_hi:[1,0,1]
	v_addc_co_u32_e32 v73, vcc, 0, v129, vcc
	global_store_dwordx4 v[60:61], v[52:55], off offset:16
	v_pk_fma_f32 v[46:47], v[90:91], s[14:15], v[46:47] op_sel_hi:[1,0,1]
	v_pk_fma_f32 v[44:45], v[88:89], s[14:15], v[44:45] op_sel_hi:[1,0,1]
	v_lshl_add_u64 v[52:53], v[128:129], 0, s[34:35]
	v_add_co_u32_e32 v74, vcc, s13, v128
	v_pk_fma_f32 v[58:59], v[78:79], s[14:15], v[58:59] op_sel_hi:[1,0,1]
	v_pk_fma_f32 v[56:57], v[76:77], s[14:15], v[56:57] op_sel_hi:[1,0,1]
	v_pk_fma_f32 v[50:51], v[86:87], s[14:15], v[50:51] op_sel_hi:[1,0,1]
	v_pk_fma_f32 v[48:49], v[84:85], s[14:15], v[48:49] op_sel_hi:[1,0,1]
	global_store_dwordx4 v[52:53], v[44:47], off offset:16
	v_pk_fma_f32 v[42:43], v[94:95], s[14:15], v[42:43] op_sel_hi:[1,0,1]
	v_pk_fma_f32 v[40:41], v[92:93], s[14:15], v[40:41] op_sel_hi:[1,0,1]
	v_lshl_add_u64 v[44:45], v[128:129], 0, s[36:37]
	v_addc_co_u32_e32 v75, vcc, 0, v129, vcc
	v_pk_fma_f32 v[38:39], v[98:99], s[14:15], v[38:39] op_sel_hi:[1,0,1]
	v_pk_fma_f32 v[36:37], v[96:97], s[14:15], v[36:37] op_sel_hi:[1,0,1]
	s_mov_b64 s[12:13], 0x100200
	s_mov_b64 s[16:17], 0x120200
	s_mov_b64 s[18:19], 0x140200
	s_mov_b64 s[34:35], 0x160200
	global_store_dwordx4 v[70:71], v[64:67], off
	global_store_dwordx4 v[68:69], v[56:59], off
	global_store_dwordx4 v[72:73], v[48:51], off
	global_store_dwordx4 v[74:75], v[40:43], off
	global_store_dwordx4 v[44:45], v[36:39], off offset:16
	v_lshl_add_u64 v[44:45], v[142:143], 0, s[12:13]
	v_lshl_add_u64 v[48:49], v[142:143], 0, s[16:17]
	v_lshl_add_u64 v[60:61], v[142:143], 0, s[18:19]
	v_lshl_add_u64 v[64:65], v[142:143], 0, s[34:35]
	flat_load_dwordx4 v[36:39], v[100:101] offset:512
	flat_load_dwordx4 v[40:43], v[102:103] offset:512
	s_nop 0
	flat_load_dwordx4 v[44:47], v[44:45] offset:16
	s_nop 0
	flat_load_dwordx4 v[48:51], v[48:49] offset:16
	s_nop 0
	flat_load_dwordx4 v[52:55], v[104:105] offset:512
	flat_load_dwordx4 v[56:59], v[106:107] offset:512
	s_nop 0
	flat_load_dwordx4 v[60:63], v[60:61] offset:16
	s_nop 0
	flat_load_dwordx4 v[64:67], v[64:65] offset:16
	s_waitcnt vmcnt(0) lgkmcnt(0)
	v_pk_fma_f32 v[32:33], v[36:37], s[14:15], v[32:33] op_sel_hi:[1,0,1]
	v_lshl_add_u64 v[36:37], v[128:129], 0, s[12:13]
	v_pk_fma_f32 v[30:31], v[46:47], s[14:15], v[30:31] op_sel_hi:[1,0,1]
	v_pk_fma_f32 v[28:29], v[44:45], s[14:15], v[28:29] op_sel_hi:[1,0,1]
	global_store_dwordx4 v[36:37], v[28:31], off offset:16
	v_pk_fma_f32 v[22:23], v[50:51], s[14:15], v[22:23] op_sel_hi:[1,0,1]
	v_pk_fma_f32 v[20:21], v[48:49], s[14:15], v[20:21] op_sel_hi:[1,0,1]
	v_lshl_add_u64 v[28:29], v[128:129], 0, s[16:17]
	global_store_dwordx4 v[28:29], v[20:23], off offset:16
	v_pk_fma_f32 v[14:15], v[62:63], s[14:15], v[14:15] op_sel_hi:[1,0,1]
	v_pk_fma_f32 v[12:13], v[60:61], s[14:15], v[12:13] op_sel_hi:[1,0,1]
	v_lshl_add_u64 v[20:21], v[128:129], 0, s[18:19]
	v_pk_fma_f32 v[34:35], v[38:39], s[14:15], v[34:35] op_sel_hi:[1,0,1]
	v_pk_fma_f32 v[26:27], v[42:43], s[14:15], v[26:27] op_sel_hi:[1,0,1]
	v_pk_fma_f32 v[24:25], v[40:41], s[14:15], v[24:25] op_sel_hi:[1,0,1]
	v_pk_fma_f32 v[18:19], v[54:55], s[14:15], v[18:19] op_sel_hi:[1,0,1]
	v_pk_fma_f32 v[16:17], v[52:53], s[14:15], v[16:17] op_sel_hi:[1,0,1]
	global_store_dwordx4 v[20:21], v[12:15], off offset:16
	v_pk_fma_f32 v[10:11], v[58:59], s[14:15], v[10:11] op_sel_hi:[1,0,1]
	v_pk_fma_f32 v[8:9], v[56:57], s[14:15], v[8:9] op_sel_hi:[1,0,1]
	v_lshl_add_u64 v[12:13], v[128:129], 0, s[34:35]
	v_pk_fma_f32 v[6:7], v[66:67], s[14:15], v[6:7] op_sel_hi:[1,0,1]
	v_pk_fma_f32 v[4:5], v[64:65], s[14:15], v[4:5] op_sel_hi:[1,0,1]
	s_and_b64 vcc, exec, s[6:7]
	s_mov_b32 s34, s4
	s_mov_b32 s12, s2
	s_mov_b64 s[14:15], s[10:11]
	s_mov_b64 s[16:17], s[8:9]
	global_store_dwordx4 v[70:71], v[32:35], off offset:512
	global_store_dwordx4 v[68:69], v[24:27], off offset:512
	global_store_dwordx4 v[72:73], v[16:19], off offset:512
	global_store_dwordx4 v[74:75], v[8:11], off offset:512
	global_store_dwordx4 v[12:13], v[4:7], off offset:16
	s_cbranch_vccz .LBB0_616
	s_waitcnt vmcnt(0)
	s_cmpk_gt_u32 s20, 0xff
	s_cbranch_scc1 .LBB0_623
	s_barrier

; __global__ void __launch_bounds__(512) fwd_megakernel(Params p) {
	.amdhsa_kernel _Z14fwd_megakernel6Params
		.amdhsa_group_segment_fixed_size 0
		.amdhsa_private_segment_fixed_size 0
		.amdhsa_kernarg_size 416
		.amdhsa_user_sgpr_count 2
		.amdhsa_user_sgpr_dispatch_ptr 0
		.amdhsa_user_sgpr_queue_ptr 0
		.amdhsa_user_sgpr_kernarg_segment_ptr 1
		.amdhsa_user_sgpr_dispatch_id 0
		.amdhsa_user_sgpr_kernarg_preload_length 0
		.amdhsa_user_sgpr_kernarg_preload_offset 0
		.amdhsa_user_sgpr_private_segment_size 0
		.amdhsa_uses_dynamic_stack 0
		.amdhsa_enable_private_segment 0
		.amdhsa_system_sgpr_workgroup_id_x 1
		.amdhsa_system_sgpr_workgroup_id_y 0
		.amdhsa_system_sgpr_workgroup_id_z 0
		.amdhsa_system_sgpr_workgroup_info 0
		.amdhsa_system_vgpr_workitem_id 2
		.amdhsa_next_free_vgpr 248
		.amdhsa_next_free_sgpr 102
		.amdhsa_accum_offset 248
		.amdhsa_reserve_vcc 1
		.amdhsa_float_round_mode_32 0
		.amdhsa_float_round_mode_16_64 0
		.amdhsa_float_denorm_mode_32 3
		.amdhsa_float_denorm_mode_16_64 3
		.amdhsa_dx10_clamp 1
		.amdhsa_ieee_mode 1
		.amdhsa_fp16_overflow 0
		.amdhsa_tg_split 0
		.amdhsa_exception_fp_ieee_invalid_op 0
		.amdhsa_exception_fp_denorm_src 0
		.amdhsa_exception_fp_ieee_div_zero 0
		.amdhsa_exception_fp_ieee_overflow 0
		.amdhsa_exception_fp_ieee_underflow 0
		.amdhsa_exception_fp_ieee_inexact 0
		.amdhsa_exception_int_div_zero 0
	.end_amdhsa_kernel

; __global__ void __launch_bounds__(512) fwd_megakernel(Params p) {
amdhsa.kernels:
  - .agpr_count:     0
    .args:
      - .offset:         0
        .size:           160
        .value_kind:     by_value
      - .offset:         160
        .size:           4
        .value_kind:     hidden_block_count_x
      - .offset:         164
        .size:           4
        .value_kind:     hidden_block_count_y
      - .offset:         168
        .size:           4
        .value_kind:     hidden_block_count_z
      - .offset:         172
        .size:           2
        .value_kind:     hidden_group_size_x
      - .offset:         174
        .size:           2
        .value_kind:     hidden_group_size_y
      - .offset:         176
        .size:           2
        .value_kind:     hidden_group_size_z
      - .offset:         178
        .size:           2
        .value_kind:     hidden_remainder_x
      - .offset:         180
        .size:           2
        .value_kind:     hidden_remainder_y
      - .offset:         182
        .size:           2
        .value_kind:     hidden_remainder_z
      - .offset:         200
        .size:           8
        .value_kind:     hidden_global_offset_x
      - .offset:         208
        .size:           8
        .value_kind:     hidden_global_offset_y
      - .offset:         216
        .size:           8
        .value_kind:     hidden_global_offset_z
      - .offset:         224
        .size:           2
        .value_kind:     hidden_grid_dims
      - .offset:         248
        .size:           8
        .value_kind:     hidden_multigrid_sync_arg
      - .offset:         280
        .size:           4
        .value_kind:     hidden_dynamic_lds_size
    .group_segment_fixed_size: 0
    .kernarg_segment_align: 8
    .kernarg_segment_size: 416
    .language:       OpenCL C
    .language_version:
      - 2
      - 0
    .max_flat_workgroup_size: 512
    .name:           _Z14fwd_megakernel6Params
    .private_segment_fixed_size: 0
    .sgpr_count:     108
    .sgpr_spill_count: 156
    .symbol:         _Z14fwd_megakernel6Params.kd
    .uniform_work_group_size: 1
    .uses_dynamic_stack: false
    .vgpr_count:     248
    .vgpr_spill_count: 0
    .wavefront_size: 64
